# v19 plus weight-conversion loops: next-tile load wait/select block moved after the LDS transpose+store block so loads overlap the stores (26 sites)
# speedup vs baseline: 1.0095x; 1.0002x over previous
; DEVI unsigned pk_bf16(float lo, float hi) { unsigned r; asm("v_cvt_pk_bf16_f32 %0, %1, %2" : "=v"(r) : "v"(lo), "v"(hi)); return r; }
; DEVI void cvt_job(LAS float* tile, const float* src, int srcK, int srcN, bf16_t* dst, int dstLd, int dstRows, int dstCol0, int mode, const float* gk = nullptr) {
;     ...
;         for (int i = 0; i < 16; ++i) { const int k = kap0 + ty + 8 * i - dstCol0; regs[i] = (nok && k >= 0 && k < srcK) ? raw[i] * gs[i] : 0.f; }
;     };
;     auto emit = [&](int t, float (&regs)[16]) {
; #pragma unroll
;         for (int i = 0; i < 16; ++i) tile[(ty + 8 * i) * 65 + tx] = regs[i];
;         __syncthreads();
;         int rho0, kap0, n0; coords(t, rho0, kap0, n0);
;         const int tn = t + 2 * gridDim.x;
;         if (tn < ntot) gl(tn, regs);
; #pragma unroll
;         for (int i = 0; i < 8; ++i) { const int row = ty + 8 * i;
;             const float lo = tile[(2 * tx) * 65 + row], hi = tile[(2 * tx + 1) * 65 + row];
;             *(unsigned*)(dst + (size_t)(rho0 + row) * dstLd + kap0 + 2 * tx) = pk_bf16(lo, hi); }
.LBB0_31:
.LBB0_32:
	s_mul_hi_i32 s4, s73, 0x78787879
	s_lshr_b32 s5, s4, 31
	s_ashr_i32 s4, s4, 5
	s_add_i32 s6, s4, s5
	s_lshl_b32 s4, s6, 7
	s_mulk_i32 s6, 0xef00
	s_add_i32 s6, s6, s28
	ds_read2_b32 v[136:137], v55 offset0:65 offset1:73
	ds_read2_b32 v[138:139], v55 offset1:8
	v_add_u32_e32 v140, s6, v56
	v_ashrrev_i32_e32 v141, 31, v140
	s_ashr_i32 s5, s4, 31
	v_lshlrev_b64 v[142:143], 12, v[140:141]
	v_lshl_add_u64 v[142:143], s[2:3], 0, v[142:143]
	s_lshl_b64 s[4:5], s[4:5], 1
	v_lshl_add_u64 v[142:143], v[142:143], 0, s[4:5]
	s_waitcnt lgkmcnt(0)
	v_cvt_pk_bf16_f32 v133, v138, v136
	v_lshl_add_u64 v[142:143], v[142:143], 0, v[34:35]
	v_add_u32_e32 v136, 8, v140
	global_store_dword v[142:143], v133, off
	v_cvt_pk_bf16_f32 v133, v139, v137
	v_ashrrev_i32_e32 v137, 31, v136
	v_lshlrev_b64 v[136:137], 12, v[136:137]
	v_lshl_add_u64 v[136:137], s[2:3], 0, v[136:137]
	v_lshl_add_u64 v[136:137], v[136:137], 0, s[4:5]
	v_lshl_add_u64 v[136:137], v[136:137], 0, v[34:35]
	ds_read2_b32 v[138:139], v55 offset0:16 offset1:24
	ds_read2_b32 v[142:143], v55 offset0:81 offset1:89
	global_store_dword v[136:137], v133, off
	v_add_u32_e32 v136, 16, v140
	v_ashrrev_i32_e32 v137, 31, v136
	v_lshlrev_b64 v[136:137], 12, v[136:137]
	v_lshl_add_u64 v[136:137], s[2:3], 0, v[136:137]
	v_lshl_add_u64 v[136:137], v[136:137], 0, s[4:5]
	v_lshl_add_u64 v[136:137], v[136:137], 0, v[34:35]
	s_waitcnt lgkmcnt(0)
	v_cvt_pk_bf16_f32 v133, v138, v142
	global_store_dword v[136:137], v133, off
	v_add_u32_e32 v136, 24, v140
	v_ashrrev_i32_e32 v137, 31, v136
	v_lshlrev_b64 v[136:137], 12, v[136:137]
	v_lshl_add_u64 v[136:137], s[2:3], 0, v[136:137]
	v_lshl_add_u64 v[136:137], v[136:137], 0, s[4:5]
	v_lshl_add_u64 v[136:137], v[136:137], 0, v[34:35]
	v_cvt_pk_bf16_f32 v133, v139, v143
	ds_read2_b32 v[138:139], v55 offset0:32 offset1:40
	ds_read2_b32 v[142:143], v55 offset0:97 offset1:105
	global_store_dword v[136:137], v133, off
	v_add_u32_e32 v136, 32, v140
	v_ashrrev_i32_e32 v137, 31, v136
	v_lshlrev_b64 v[136:137], 12, v[136:137]
	v_lshl_add_u64 v[136:137], s[2:3], 0, v[136:137]
	v_lshl_add_u64 v[136:137], v[136:137], 0, s[4:5]
	v_lshl_add_u64 v[136:137], v[136:137], 0, v[34:35]
	s_waitcnt lgkmcnt(0)
	v_cvt_pk_bf16_f32 v133, v138, v142
	global_store_dword v[136:137], v133, off
	v_add_u32_e32 v136, 40, v140
	v_ashrrev_i32_e32 v137, 31, v136
	v_lshlrev_b64 v[136:137], 12, v[136:137]
	v_lshl_add_u64 v[136:137], s[2:3], 0, v[136:137]
	v_lshl_add_u64 v[136:137], v[136:137], 0, s[4:5]
	v_lshl_add_u64 v[136:137], v[136:137], 0, v[34:35]
	v_cvt_pk_bf16_f32 v133, v139, v143
	ds_read2_b32 v[138:139], v55 offset0:48 offset1:56
	ds_read2_b32 v[142:143], v55 offset0:113 offset1:121
	global_store_dword v[136:137], v133, off
	v_add_u32_e32 v136, 48, v140
	v_ashrrev_i32_e32 v137, 31, v136
	v_lshlrev_b64 v[136:137], 12, v[136:137]
	v_lshl_add_u64 v[136:137], s[2:3], 0, v[136:137]
	v_lshl_add_u64 v[136:137], v[136:137], 0, s[4:5]
	v_lshl_add_u64 v[136:137], v[136:137], 0, v[34:35]
	s_waitcnt lgkmcnt(0)
	v_cvt_pk_bf16_f32 v133, v138, v142
	global_store_dword v[136:137], v133, off
	v_add_u32_e32 v136, 56, v140
	v_ashrrev_i32_e32 v137, 31, v136
	v_lshlrev_b64 v[136:137], 12, v[136:137]
	v_lshl_add_u64 v[136:137], s[2:3], 0, v[136:137]
	v_lshl_add_u64 v[136:137], v[136:137], 0, s[4:5]
	v_lshl_add_u64 v[136:137], v[136:137], 0, v[34:35]
	v_cvt_pk_bf16_f32 v133, v139, v143
	global_store_dword v[136:137], v133, off
	v_cmp_gt_i32_e32 vcc, s35, v53
	v_cmp_gt_u32_e64 s[4:5], s51, v17
	s_waitcnt vmcnt(23)
	v_mul_f32_e32 v18, v89, v18
	s_and_b64 s[4:5], s[4:5], vcc
	v_cndmask_b32_e64 v18, 0, v18, s[4:5]
	v_cmp_gt_u32_e64 s[4:5], s51, v62
	s_waitcnt vmcnt(22)
	v_mul_f32_e32 v17, v87, v33
	s_and_b64 s[4:5], s[4:5], vcc
	v_cndmask_b32_e64 v17, 0, v17, s[4:5]
	v_cmp_gt_u32_e64 s[4:5], s51, v63
	s_waitcnt vmcnt(21)
	v_mul_f32_e32 v20, v85, v20
	s_and_b64 s[4:5], s[4:5], vcc
	v_cndmask_b32_e64 v20, 0, v20, s[4:5]
	v_cmp_gt_u32_e64 s[4:5], s51, v64
	s_waitcnt vmcnt(20)
	v_mul_f32_e32 v32, v83, v32
	s_and_b64 s[4:5], s[4:5], vcc
	s_waitcnt vmcnt(16)
	v_mul_f32_e32 v33, v76, v19
	v_cndmask_b32_e64 v19, 0, v32, s[4:5]
	v_cmp_gt_u32_e64 s[4:5], s51, v69
	s_waitcnt vmcnt(15)
	v_mul_f32_e32 v30, v91, v30
	v_cmp_gt_u32_e64 s[14:15], s51, v70
	s_and_b64 s[4:5], s[4:5], vcc
	v_cmp_gt_u32_e64 s[8:9], s51, v66
	s_waitcnt vmcnt(14)
	v_mul_f32_e32 v28, v90, v28
	s_waitcnt vmcnt(13)
	v_mul_f32_e32 v32, v88, v26
	v_cmp_gt_u32_e64 s[16:17], s51, v71
	v_cndmask_b32_e64 v26, 0, v30, s[4:5]
	s_and_b64 s[4:5], s[14:15], vcc
	v_mul_f32_e32 v29, v79, v29
	v_cmp_gt_u32_e64 s[10:11], s51, v67
	s_waitcnt vmcnt(12)
	v_mul_f32_e32 v36, v86, v25
	v_cmp_gt_u32_e64 s[18:19], s51, v72
	s_and_b64 s[8:9], s[8:9], vcc
	v_cndmask_b32_e64 v25, 0, v28, s[4:5]
	s_and_b64 s[4:5], s[16:17], vcc
	v_cmp_gt_u32_e64 s[6:7], s51, v65
	v_mul_f32_e32 v27, v77, v27
	v_cmp_gt_u32_e64 s[20:21], s51, v73
	s_waitcnt vmcnt(8)
	v_mul_f32_e32 v40, v78, v21
	v_cndmask_b32_e64 v21, 0, v29, s[8:9]
	s_and_b64 s[8:9], s[10:11], vcc
	v_cndmask_b32_e64 v28, 0, v32, s[4:5]
	s_and_b64 s[4:5], s[18:19], vcc
	v_mul_f32_e32 v31, v81, v31
	v_mul_f32_e32 v37, v84, v24
	v_cmp_gt_u32_e64 s[22:23], s51, v74
	s_and_b64 s[6:7], s[6:7], vcc
	v_cndmask_b32_e64 v24, 0, v27, s[8:9]
	v_cndmask_b32_e64 v27, 0, v36, s[4:5]
	s_and_b64 s[4:5], s[20:21], vcc
	v_cmp_gt_u32_e64 s[12:13], s51, v68
	v_mul_f32_e32 v38, v82, v23
	v_mul_f32_e32 v39, v80, v22
	v_cmp_gt_u32_e64 s[24:25], s51, v75
	v_cndmask_b32_e64 v22, 0, v31, s[6:7]
	v_cmp_gt_u32_e64 s[6:7], s51, v52
	v_cndmask_b32_e64 v30, 0, v37, s[4:5]
	s_and_b64 s[4:5], s[22:23], vcc
	s_and_b64 s[8:9], s[12:13], vcc
	v_cndmask_b32_e64 v29, 0, v38, s[4:5]
	s_and_b64 s[4:5], s[24:25], vcc
	s_and_b64 vcc, s[6:7], vcc
	v_cndmask_b32_e64 v23, 0, v33, s[8:9]
	v_cndmask_b32_e64 v32, 0, v39, s[4:5]
	v_cndmask_b32_e32 v31, 0, v40, vcc
	s_barrier

; DEVI unsigned pk_bf16(float lo, float hi) { unsigned r; asm("v_cvt_pk_bf16_f32 %0, %1, %2" : "=v"(r) : "v"(lo), "v"(hi)); return r; }
; DEVI void cvt_job(LAS float* tile, const float* src, int srcK, int srcN, bf16_t* dst, int dstLd, int dstRows, int dstCol0, int mode, const float* gk = nullptr) {
;     ...
;         for (int i = 0; i < 16; ++i) { const int k = kap0 + ty + 8 * i - dstCol0; regs[i] = (nok && k >= 0 && k < srcK) ? raw[i] * gs[i] : 0.f; }
;     };
;     auto emit = [&](int t, float (&regs)[16]) {
; #pragma unroll
;         for (int i = 0; i < 16; ++i) tile[(ty + 8 * i) * 65 + tx] = regs[i];
;         __syncthreads();
;         int rho0, kap0, n0; coords(t, rho0, kap0, n0);
;         const int tn = t + 2 * gridDim.x;
;         if (tn < ntot) gl(tn, regs);
; #pragma unroll
;         for (int i = 0; i < 8; ++i) { const int row = ty + 8 * i;
;             const float lo = tile[(2 * tx) * 65 + row], hi = tile[(2 * tx + 1) * 65 + row];
;             *(unsigned*)(dst + (size_t)(rho0 + row) * dstLd + kap0 + 2 * tx) = pk_bf16(lo, hi); }
.LBB0_38:
.LBB0_39:
	s_mul_hi_i32 s4, s31, 0x78787879
	s_lshr_b32 s5, s4, 31
	s_ashr_i32 s4, s4, 5
	s_add_i32 s6, s4, s5
	s_lshl_b32 s4, s6, 7
	s_mulk_i32 s6, 0xef00
	s_add_i32 s6, s6, s28
	ds_read2_b32 v[136:137], v55 offset0:65 offset1:73
	ds_read2_b32 v[138:139], v55 offset1:8
	v_add_u32_e32 v140, s6, v59
	v_ashrrev_i32_e32 v141, 31, v140
	s_ashr_i32 s5, s4, 31
	v_lshlrev_b64 v[142:143], 12, v[140:141]
	v_lshl_add_u64 v[142:143], s[2:3], 0, v[142:143]
	s_lshl_b64 s[4:5], s[4:5], 1
	v_lshl_add_u64 v[142:143], v[142:143], 0, s[4:5]
	s_waitcnt lgkmcnt(0)
	v_cvt_pk_bf16_f32 v133, v138, v136
	v_lshl_add_u64 v[142:143], v[142:143], 0, v[34:35]
	v_add_u32_e32 v136, 8, v140
	global_store_dword v[142:143], v133, off
	v_cvt_pk_bf16_f32 v133, v139, v137
	v_ashrrev_i32_e32 v137, 31, v136
	v_lshlrev_b64 v[136:137], 12, v[136:137]
	v_lshl_add_u64 v[136:137], s[2:3], 0, v[136:137]
	v_lshl_add_u64 v[136:137], v[136:137], 0, s[4:5]
	v_lshl_add_u64 v[136:137], v[136:137], 0, v[34:35]
	ds_read2_b32 v[138:139], v55 offset0:16 offset1:24
	ds_read2_b32 v[142:143], v55 offset0:81 offset1:89
	global_store_dword v[136:137], v133, off
	v_add_u32_e32 v136, 16, v140
	v_ashrrev_i32_e32 v137, 31, v136
	v_lshlrev_b64 v[136:137], 12, v[136:137]
	v_lshl_add_u64 v[136:137], s[2:3], 0, v[136:137]
	v_lshl_add_u64 v[136:137], v[136:137], 0, s[4:5]
	v_lshl_add_u64 v[136:137], v[136:137], 0, v[34:35]
	s_waitcnt lgkmcnt(0)
	v_cvt_pk_bf16_f32 v133, v138, v142
	global_store_dword v[136:137], v133, off
	v_add_u32_e32 v136, 24, v140
	v_ashrrev_i32_e32 v137, 31, v136
	v_lshlrev_b64 v[136:137], 12, v[136:137]
	v_lshl_add_u64 v[136:137], s[2:3], 0, v[136:137]
	v_lshl_add_u64 v[136:137], v[136:137], 0, s[4:5]
	v_lshl_add_u64 v[136:137], v[136:137], 0, v[34:35]
	v_cvt_pk_bf16_f32 v133, v139, v143
	ds_read2_b32 v[138:139], v55 offset0:32 offset1:40
	ds_read2_b32 v[142:143], v55 offset0:97 offset1:105
	global_store_dword v[136:137], v133, off
	v_add_u32_e32 v136, 32, v140
	v_ashrrev_i32_e32 v137, 31, v136
	v_lshlrev_b64 v[136:137], 12, v[136:137]
	v_lshl_add_u64 v[136:137], s[2:3], 0, v[136:137]
	v_lshl_add_u64 v[136:137], v[136:137], 0, s[4:5]
	v_lshl_add_u64 v[136:137], v[136:137], 0, v[34:35]
	s_waitcnt lgkmcnt(0)
	v_cvt_pk_bf16_f32 v133, v138, v142
	global_store_dword v[136:137], v133, off
	v_add_u32_e32 v136, 40, v140
	v_ashrrev_i32_e32 v137, 31, v136
	v_lshlrev_b64 v[136:137], 12, v[136:137]
	v_lshl_add_u64 v[136:137], s[2:3], 0, v[136:137]
	v_lshl_add_u64 v[136:137], v[136:137], 0, s[4:5]
	v_lshl_add_u64 v[136:137], v[136:137], 0, v[34:35]
	v_cvt_pk_bf16_f32 v133, v139, v143
	ds_read2_b32 v[138:139], v55 offset0:48 offset1:56
	ds_read2_b32 v[142:143], v55 offset0:113 offset1:121
	global_store_dword v[136:137], v133, off
	v_add_u32_e32 v136, 48, v140
	v_ashrrev_i32_e32 v137, 31, v136
	v_lshlrev_b64 v[136:137], 12, v[136:137]
	v_lshl_add_u64 v[136:137], s[2:3], 0, v[136:137]
	v_lshl_add_u64 v[136:137], v[136:137], 0, s[4:5]
	v_lshl_add_u64 v[136:137], v[136:137], 0, v[34:35]
	s_waitcnt lgkmcnt(0)
	v_cvt_pk_bf16_f32 v133, v138, v142
	global_store_dword v[136:137], v133, off
	v_add_u32_e32 v136, 56, v140
	v_ashrrev_i32_e32 v137, 31, v136
	v_lshlrev_b64 v[136:137], 12, v[136:137]
	v_lshl_add_u64 v[136:137], s[2:3], 0, v[136:137]
	v_lshl_add_u64 v[136:137], v[136:137], 0, s[4:5]
	s_add_i32 s73, s33, s31
	v_lshl_add_u64 v[136:137], v[136:137], 0, v[34:35]
	s_cmpk_gt_i32 s73, 0x43f
	v_cvt_pk_bf16_f32 v133, v139, v143
	global_store_dword v[136:137], v133, off
	s_cselect_b32 s98, 1, 0
	v_cmp_gt_i32_e32 vcc, s35, v33
	v_cmp_gt_u32_e64 s[4:5], s51, v1
	s_waitcnt vmcnt(23)
	v_mul_f32_e32 v2, v89, v2
	s_and_b64 s[4:5], s[4:5], vcc
	v_cndmask_b32_e64 v2, 0, v2, s[4:5]
	v_cmp_gt_u32_e64 s[4:5], s51, v62
	s_waitcnt vmcnt(22)
	v_mul_f32_e32 v1, v87, v37
	s_and_b64 s[4:5], s[4:5], vcc
	v_cndmask_b32_e64 v1, 0, v1, s[4:5]
	v_cmp_gt_u32_e64 s[4:5], s51, v63
	s_waitcnt vmcnt(21)
	v_mul_f32_e32 v4, v85, v4
	s_and_b64 s[4:5], s[4:5], vcc
	v_cndmask_b32_e64 v4, 0, v4, s[4:5]
	v_cmp_gt_u32_e64 s[4:5], s51, v64
	s_waitcnt vmcnt(20)
	v_mul_f32_e32 v33, v83, v36
	s_and_b64 s[4:5], s[4:5], vcc
	s_waitcnt vmcnt(16)
	v_mul_f32_e32 v36, v76, v3
	v_cndmask_b32_e64 v3, 0, v33, s[4:5]
	v_cmp_gt_u32_e64 s[4:5], s51, v69
	s_waitcnt vmcnt(15)
	v_mul_f32_e32 v14, v91, v14
	v_cmp_gt_u32_e64 s[14:15], s51, v70
	s_and_b64 s[4:5], s[4:5], vcc
	v_cmp_gt_u32_e64 s[8:9], s51, v66
	s_waitcnt vmcnt(14)
	v_mul_f32_e32 v12, v90, v12
	s_waitcnt vmcnt(13)
	v_mul_f32_e32 v33, v88, v10
	v_cmp_gt_u32_e64 s[16:17], s51, v71
	v_cndmask_b32_e64 v10, 0, v14, s[4:5]
	s_and_b64 s[4:5], s[14:15], vcc
	v_mul_f32_e32 v13, v79, v13
	v_cmp_gt_u32_e64 s[10:11], s51, v67
	s_waitcnt vmcnt(12)
	v_mul_f32_e32 v37, v86, v9
	v_cmp_gt_u32_e64 s[18:19], s51, v72
	s_and_b64 s[8:9], s[8:9], vcc
	v_cndmask_b32_e64 v9, 0, v12, s[4:5]
	s_and_b64 s[4:5], s[16:17], vcc
	v_cmp_gt_u32_e64 s[6:7], s51, v65
	v_mul_f32_e32 v11, v77, v11
	v_cmp_gt_u32_e64 s[20:21], s51, v73
	s_waitcnt vmcnt(8)
	v_mul_f32_e32 v41, v78, v5
	v_cndmask_b32_e64 v5, 0, v13, s[8:9]
	s_and_b64 s[8:9], s[10:11], vcc
	v_cndmask_b32_e64 v12, 0, v33, s[4:5]
	s_and_b64 s[4:5], s[18:19], vcc
	v_mul_f32_e32 v15, v81, v15
	v_mul_f32_e32 v38, v84, v8
	v_cmp_gt_u32_e64 s[22:23], s51, v74
	s_and_b64 s[6:7], s[6:7], vcc
	v_cndmask_b32_e64 v8, 0, v11, s[8:9]
	v_cndmask_b32_e64 v11, 0, v37, s[4:5]
	s_and_b64 s[4:5], s[20:21], vcc
	v_cmp_gt_u32_e64 s[12:13], s51, v68
	v_mul_f32_e32 v39, v82, v7
	v_mul_f32_e32 v40, v80, v6
	v_cmp_gt_u32_e64 s[24:25], s51, v75
	v_cndmask_b32_e64 v6, 0, v15, s[6:7]
	v_cmp_gt_u32_e64 s[6:7], s51, v16
	v_cndmask_b32_e64 v14, 0, v38, s[4:5]
	s_and_b64 s[4:5], s[22:23], vcc
	s_and_b64 s[8:9], s[12:13], vcc
	v_cndmask_b32_e64 v13, 0, v39, s[4:5]
	s_and_b64 s[4:5], s[24:25], vcc
	s_and_b64 vcc, s[6:7], vcc
	v_cndmask_b32_e64 v7, 0, v36, s[8:9]
	v_cndmask_b32_e64 v16, 0, v40, s[4:5]
	v_cndmask_b32_e32 v15, 0, v41, vcc
	s_cmp_lg_u32 s98, 0
	s_barrier
; DEVI void cvt_job(LAS float* tile, const float* src, int srcK, int srcN, bf16_t* dst, int dstLd, int dstRows, int dstCol0, int mode, const float* gk = nullptr) {
;     ...
;         const int n = n0 + tx, nc = n < srcN ? n : srcN - 1;
;         const bool nok = n < srcN;
;         float raw[16], gs[16];
; #pragma unroll
;         for (int i = 0; i < 16; ++i) { const int k = kap0 + ty + 8 * i - dstCol0; const int kc = k < 0 ? 0 : (k < srcK ? k : srcK - 1);
;             raw[i] = __builtin_nontemporal_load(src + (size_t)kc * srcN + nc); }
;         if (gk) {
; #pragma unroll
;             for (int i = 0; i < 16; ++i) { const int k = kap0 + ty + 8 * i - dstCol0; const int kc = k < 0 ? 0 : (k < srcK ? k : srcK - 1); gs[i] = gk[kc]; }
;         } else {
; #pragma unroll
;             for (int i = 0; i < 16; ++i) gs[i] = 1.0f;
;         }
; #pragma unroll
;         for (int i = 0; i < 16; ++i) { const int k = kap0 + ty + 8 * i - dstCol0; regs[i] = (nok && k >= 0 && k < srcK) ? raw[i] * gs[i] : 0.f; }
;     };
;     auto emit = [&](int t, float (&regs)[16]) {
; #pragma unroll
;         for (int i = 0; i < 16; ++i) tile[(ty + 8 * i) * 65 + tx] = regs[i];
;         __syncthreads();
;         int rho0, kap0, n0; coords(t, rho0, kap0, n0);
;         const int tn = t + 2 * gridDim.x;
;         if (tn < ntot) gl(tn, regs);
	s_cbranch_scc1 .LBB0_33
	s_mul_i32 s4, s33, 3
	s_add_i32 s4, s4, s31
	s_cmpk_gt_i32 s4, 0x43f
	ds_write_b32 v60, v18
	ds_write_b32 v60, v17 offset:2080
	ds_write_b32 v60, v20 offset:4160
	ds_write_b32 v60, v19 offset:6240
	ds_write_b32 v60, v22 offset:8320
	ds_write_b32 v60, v21 offset:10400
	ds_write_b32 v60, v24 offset:12480
	ds_write_b32 v60, v23 offset:14560
	ds_write_b32 v60, v26 offset:16640
	ds_write_b32 v60, v25 offset:18720
	ds_write_b32 v60, v28 offset:20800
	ds_write_b32 v60, v27 offset:22880
	ds_write_b32 v60, v30 offset:24960
	ds_write_b32 v60, v29 offset:27040
	ds_write_b32 v60, v32 offset:29120
	ds_write_b32 v60, v31 offset:31200
	s_waitcnt lgkmcnt(0)
	s_barrier
	s_cbranch_scc1 .LBB0_32
	s_mul_hi_i32 s4, s4, 0x78787879
	s_lshr_b32 s5, s4, 31
	s_ashr_i32 s4, s4, 5
	s_add_i32 s4, s4, s5
	s_mul_i32 s5, s4, 0xffffef00
	s_add_i32 s5, s5, s28
	v_add_u32_e32 v53, s5, v57
	v_min_i32_e32 v18, 0x105f, v53
	v_lshl_add_u32 v17, s4, 7, v54
	v_ashrrev_i32_e32 v19, 31, v18
	v_lshl_add_u64 v[90:91], v[18:19], 2, s[62:63]
	v_med3_i32 v18, v17, 0, v61
	v_add_u32_e32 v62, 8, v17
	v_add_u32_e32 v63, 16, v17
	v_add_u32_e32 v64, 24, v17
	v_add_u32_e32 v65, 32, v17
	v_add_u32_e32 v66, 40, v17
	v_add_u32_e32 v67, 48, v17
	v_add_u32_e32 v68, 56, v17
	v_mad_u64_u32 v[36:37], s[4:5], v18, s34, v[90:91]
	v_med3_i32 v20, v62, 0, v61
	v_med3_i32 v22, v63, 0, v61
	v_med3_i32 v24, v64, 0, v61
	v_med3_i32 v26, v65, 0, v61
	v_med3_i32 v28, v66, 0, v61
	v_med3_i32 v30, v67, 0, v61
	v_med3_i32 v32, v68, 0, v61
	v_add_u32_e32 v69, 64, v17
	v_mad_u64_u32 v[38:39], s[4:5], v20, s34, v[90:91]
	v_mad_u64_u32 v[40:41], s[4:5], v22, s34, v[90:91]
	v_mad_u64_u32 v[42:43], s[4:5], v24, s34, v[90:91]
	v_mad_u64_u32 v[44:45], s[4:5], v26, s34, v[90:91]
	v_mad_u64_u32 v[46:47], s[4:5], v28, s34, v[90:91]
	v_mad_u64_u32 v[48:49], s[4:5], v30, s34, v[90:91]
	v_mad_u64_u32 v[50:51], s[4:5], v32, s34, v[90:91]
	global_load_dword v89, v[36:37], off nt
	global_load_dword v87, v[38:39], off nt
	global_load_dword v85, v[40:41], off nt
	global_load_dword v83, v[42:43], off nt
	global_load_dword v81, v[44:45], off nt
	global_load_dword v79, v[46:47], off nt
	global_load_dword v77, v[48:49], off nt
	global_load_dword v76, v[50:51], off nt
	v_med3_i32 v36, v69, 0, v61
	v_add_u32_e32 v70, 0x48, v17
	v_add_u32_e32 v71, 0x50, v17
	v_add_u32_e32 v72, 0x58, v17
	v_add_u32_e32 v73, 0x60, v17
	v_add_u32_e32 v74, 0x68, v17
	v_add_u32_e32 v75, 0x70, v17
	v_add_u32_e32 v52, 0x78, v17
	v_mad_u64_u32 v[92:93], s[4:5], v36, s34, v[90:91]
	v_med3_i32 v38, v70, 0, v61
	v_med3_i32 v40, v71, 0, v61
	v_med3_i32 v42, v72, 0, v61
	v_med3_i32 v44, v73, 0, v61
	v_med3_i32 v46, v74, 0, v61
	v_med3_i32 v48, v75, 0, v61
	v_med3_i32 v50, v52, 0, v61
	v_mad_u64_u32 v[94:95], s[4:5], v38, s34, v[90:91]
	v_mad_u64_u32 v[96:97], s[4:5], v40, s34, v[90:91]
	v_mad_u64_u32 v[98:99], s[4:5], v42, s34, v[90:91]
	v_mad_u64_u32 v[100:101], s[4:5], v44, s34, v[90:91]
	v_mad_u64_u32 v[102:103], s[4:5], v46, s34, v[90:91]
	v_mad_u64_u32 v[104:105], s[4:5], v48, s34, v[90:91]
	v_mad_u64_u32 v[106:107], s[4:5], v50, s34, v[90:91]
	global_load_dword v91, v[92:93], off nt
	global_load_dword v90, v[94:95], off nt
	global_load_dword v88, v[96:97], off nt
	global_load_dword v86, v[98:99], off nt
	global_load_dword v84, v[100:101], off nt
	global_load_dword v82, v[102:103], off nt
	global_load_dword v80, v[104:105], off nt
	global_load_dword v78, v[106:107], off nt
	s_and_b64 vcc, exec, s[0:1]
	s_cbranch_vccz .LBB0_30
	v_mov_b32_e32 v21, 1.0
	v_mov_b32_e32 v22, 1.0
	v_mov_b32_e32 v23, 1.0
	v_mov_b32_e32 v24, 1.0
	v_mov_b32_e32 v25, 1.0
	v_mov_b32_e32 v26, 1.0
	v_mov_b32_e32 v28, 1.0
	v_mov_b32_e32 v30, 1.0
	v_mov_b32_e32 v19, 1.0
	v_mov_b32_e32 v27, 1.0
	v_mov_b32_e32 v29, 1.0
	v_mov_b32_e32 v31, 1.0
	v_mov_b32_e32 v32, 1.0
	v_mov_b32_e32 v20, 1.0
	v_mov_b32_e32 v33, 1.0
	v_mov_b32_e32 v18, 1.0
	s_branch .LBB0_31

; DEVI unsigned pk_bf16(float lo, float hi) { unsigned r; asm("v_cvt_pk_bf16_f32 %0, %1, %2" : "=v"(r) : "v"(lo), "v"(hi)); return r; }
; DEVI void cvt_job(LAS float* tile, const float* src, int srcK, int srcN, bf16_t* dst, int dstLd, int dstRows, int dstCol0, int mode, const float* gk = nullptr) {
;     ...
;         for (int i = 0; i < 16; ++i) { const int k = kap0 + ty + 8 * i - dstCol0; regs[i] = (nok && k >= 0 && k < srcK) ? raw[i] * gs[i] : 0.f; }
;     };
;     auto emit = [&](int t, float (&regs)[16]) {
; #pragma unroll
;         for (int i = 0; i < 16; ++i) tile[(ty + 8 * i) * 65 + tx] = regs[i];
;         __syncthreads();
;         int rho0, kap0, n0; coords(t, rho0, kap0, n0);
;         const int tn = t + 2 * gridDim.x;
;         if (tn < ntot) gl(tn, regs);
; #pragma unroll
;         for (int i = 0; i < 8; ++i) { const int row = ty + 8 * i;
;             const float lo = tile[(2 * tx) * 65 + row], hi = tile[(2 * tx + 1) * 65 + row];
;             *(unsigned*)(dst + (size_t)(rho0 + row) * dstLd + kap0 + 2 * tx) = pk_bf16(lo, hi); }
.LBB0_149:
.LBB0_150:
	s_mul_hi_i32 s0, s29, 0x2e8ba2e9
	s_lshr_b32 s1, s0, 31
	s_ashr_i32 s0, s0, 4
	s_add_i32 s0, s0, s1
	s_mul_i32 s1, s0, 0x3ffff50
	s_add_i32 s4, s30, s22
	s_add_i32 s4, s4, s1
	s_and_b32 s1, s4, 0x3fffffc
	s_or_b32 s1, s1, s20
	s_lshl_b32 s4, s1, 6
	ds_read2_b32 v[136:137], v56 offset0:65 offset1:73
	ds_read2_b32 v[138:139], v56 offset1:8
	v_add_u32_e32 v140, s4, v55
	s_lshl_b32 s0, s0, 7
	v_ashrrev_i32_e32 v141, 31, v140
	s_ashr_i32 s1, s0, 31
	v_lshlrev_b64 v[140:141], 12, v[140:141]
	v_lshl_add_u64 v[140:141], s[62:63], 0, v[140:141]
	s_lshl_b64 s[0:1], s[0:1], 1
	v_lshl_add_u64 v[140:141], v[140:141], 0, s[0:1]
	s_waitcnt lgkmcnt(0)
	v_cvt_pk_bf16_f32 v133, v138, v136
	v_lshl_add_u64 v[140:141], v[140:141], 0, v[34:35]
	v_add_u32_e32 v136, s4, v57
	global_store_dword v[140:141], v133, off
	v_cvt_pk_bf16_f32 v133, v139, v137
	v_ashrrev_i32_e32 v137, 31, v136
	v_lshlrev_b64 v[136:137], 12, v[136:137]
	v_lshl_add_u64 v[136:137], s[62:63], 0, v[136:137]
	v_lshl_add_u64 v[136:137], v[136:137], 0, s[0:1]
	v_lshl_add_u64 v[136:137], v[136:137], 0, v[34:35]
	ds_read2_b32 v[138:139], v56 offset0:16 offset1:24
	ds_read2_b32 v[140:141], v56 offset0:81 offset1:89
	global_store_dword v[136:137], v133, off
	v_add_u32_e32 v136, s4, v58
	v_ashrrev_i32_e32 v137, 31, v136
	v_lshlrev_b64 v[136:137], 12, v[136:137]
	v_lshl_add_u64 v[136:137], s[62:63], 0, v[136:137]
	v_lshl_add_u64 v[136:137], v[136:137], 0, s[0:1]
	v_lshl_add_u64 v[136:137], v[136:137], 0, v[34:35]
	s_waitcnt lgkmcnt(0)
	v_cvt_pk_bf16_f32 v133, v138, v140
	global_store_dword v[136:137], v133, off
	v_add_u32_e32 v136, s4, v59
	v_ashrrev_i32_e32 v137, 31, v136
	v_lshlrev_b64 v[136:137], 12, v[136:137]
	v_lshl_add_u64 v[136:137], s[62:63], 0, v[136:137]
	v_lshl_add_u64 v[136:137], v[136:137], 0, s[0:1]
	v_lshl_add_u64 v[136:137], v[136:137], 0, v[34:35]
	v_cvt_pk_bf16_f32 v133, v139, v141
	ds_read2_b32 v[138:139], v56 offset0:32 offset1:40
	ds_read2_b32 v[140:141], v56 offset0:97 offset1:105
	global_store_dword v[136:137], v133, off
	v_add_u32_e32 v136, s4, v60
	v_ashrrev_i32_e32 v137, 31, v136
	v_lshlrev_b64 v[136:137], 12, v[136:137]
	v_lshl_add_u64 v[136:137], s[62:63], 0, v[136:137]
	v_lshl_add_u64 v[136:137], v[136:137], 0, s[0:1]
	v_lshl_add_u64 v[136:137], v[136:137], 0, v[34:35]
	s_waitcnt lgkmcnt(0)
	v_cvt_pk_bf16_f32 v133, v138, v140
	global_store_dword v[136:137], v133, off
	v_add_u32_e32 v136, s4, v61
	v_ashrrev_i32_e32 v137, 31, v136
	v_lshlrev_b64 v[136:137], 12, v[136:137]
	v_lshl_add_u64 v[136:137], s[62:63], 0, v[136:137]
	v_lshl_add_u64 v[136:137], v[136:137], 0, s[0:1]
	v_lshl_add_u64 v[136:137], v[136:137], 0, v[34:35]
	v_cvt_pk_bf16_f32 v133, v139, v141
	ds_read2_b32 v[138:139], v56 offset0:48 offset1:56
	ds_read2_b32 v[140:141], v56 offset0:113 offset1:121
	global_store_dword v[136:137], v133, off
	v_add_u32_e32 v136, s4, v62
	v_ashrrev_i32_e32 v137, 31, v136
	v_lshlrev_b64 v[136:137], 12, v[136:137]
	v_lshl_add_u64 v[136:137], s[62:63], 0, v[136:137]
	v_lshl_add_u64 v[136:137], v[136:137], 0, s[0:1]
	v_lshl_add_u64 v[136:137], v[136:137], 0, v[34:35]
	s_waitcnt lgkmcnt(0)
	v_cvt_pk_bf16_f32 v133, v138, v140
	global_store_dword v[136:137], v133, off
	v_add_u32_e32 v136, s4, v63
	v_ashrrev_i32_e32 v137, 31, v136
	v_lshlrev_b64 v[136:137], 12, v[136:137]
	v_lshl_add_u64 v[136:137], s[62:63], 0, v[136:137]
	v_lshl_add_u64 v[136:137], v[136:137], 0, s[0:1]
	v_lshl_add_u64 v[136:137], v[136:137], 0, v[34:35]
	v_cvt_pk_bf16_f32 v133, v139, v141
	global_store_dword v[136:137], v133, off
	v_cmp_gt_i32_e32 vcc, s26, v52
	v_cmp_gt_u32_e64 s[0:1], s27, v17
	s_waitcnt vmcnt(23)
	v_mul_f32_e32 v18, v93, v18
	s_and_b64 s[0:1], s[0:1], vcc
	v_cndmask_b32_e64 v18, 0, v18, s[0:1]
	v_cmp_gt_u32_e64 s[0:1], s27, v68
	s_waitcnt vmcnt(22)
	v_mul_f32_e32 v17, v91, v33
	s_and_b64 s[0:1], s[0:1], vcc
	v_cndmask_b32_e64 v17, 0, v17, s[0:1]
	v_cmp_gt_u32_e64 s[0:1], s27, v69
	s_waitcnt vmcnt(21)
	v_mul_f32_e32 v20, v89, v20
	s_and_b64 s[0:1], s[0:1], vcc
	v_cndmask_b32_e64 v20, 0, v20, s[0:1]
	v_cmp_gt_u32_e64 s[0:1], s27, v70
	s_waitcnt vmcnt(20)
	v_mul_f32_e32 v19, v87, v19
	s_and_b64 s[0:1], s[0:1], vcc
	v_cndmask_b32_e64 v19, 0, v19, s[0:1]
	v_cmp_gt_u32_e64 s[0:1], s27, v71
	s_waitcnt vmcnt(19)
	v_mul_f32_e32 v22, v85, v22
	s_and_b64 s[0:1], s[0:1], vcc
	v_cndmask_b32_e64 v22, 0, v22, s[0:1]
	v_cmp_gt_u32_e64 s[0:1], s27, v72
	s_waitcnt vmcnt(18)
	v_mul_f32_e32 v31, v83, v31
	s_and_b64 s[0:1], s[0:1], vcc
	s_waitcnt vmcnt(17)
	v_mul_f32_e32 v33, v82, v21
	v_cmp_gt_u32_e64 s[4:5], s27, v73
	v_cndmask_b32_e64 v21, 0, v31, s[0:1]
	v_cmp_gt_u32_e64 s[0:1], s27, v67
	s_waitcnt vmcnt(16)
	v_mul_f32_e32 v28, v81, v28
	v_cmp_gt_u32_e64 s[6:7], s27, v74
	s_and_b64 s[4:5], s[4:5], vcc
	s_and_b64 s[0:1], s[0:1], vcc
	s_waitcnt vmcnt(15)
	v_mul_f32_e32 v31, v95, v32
	v_cmp_gt_u32_e64 s[8:9], s27, v75
	s_waitcnt vmcnt(9)
	v_mul_f32_e32 v37, v84, v24
	v_cndmask_b32_e64 v24, 0, v33, s[4:5]
	s_waitcnt vmcnt(8)
	v_mul_f32_e32 v33, v80, v23
	v_cndmask_b32_e64 v23, 0, v28, s[0:1]
	s_and_b64 s[0:1], s[6:7], vcc
	v_mul_f32_e32 v30, v94, v30
	v_cmp_gt_u32_e64 s[10:11], s27, v76
	v_mul_f32_e32 v32, v88, v26
	v_cndmask_b32_e64 v26, 0, v31, s[0:1]
	s_and_b64 s[0:1], s[8:9], vcc
	v_mul_f32_e32 v29, v92, v29
	v_cmp_gt_u32_e64 s[12:13], s27, v77
	v_mul_f32_e32 v36, v86, v25
	v_cndmask_b32_e64 v25, 0, v30, s[0:1]
	s_and_b64 s[0:1], s[10:11], vcc
	v_mul_f32_e32 v27, v90, v27
	v_cmp_gt_u32_e64 s[14:15], s27, v78
	v_cndmask_b32_e64 v28, 0, v29, s[0:1]
	s_and_b64 s[0:1], s[12:13], vcc
	v_cmp_gt_u32_e64 s[16:17], s27, v79
	v_cndmask_b32_e64 v27, 0, v27, s[0:1]
	s_and_b64 s[0:1], s[14:15], vcc
	v_cmp_gt_u32_e64 s[4:5], s27, v53
	v_cmp_gt_u32_e64 s[18:19], s27, v66
	v_cndmask_b32_e64 v30, 0, v32, s[0:1]
	s_and_b64 s[0:1], s[16:17], vcc
	v_cndmask_b32_e64 v29, 0, v36, s[0:1]
	s_and_b64 s[0:1], s[4:5], vcc
	s_and_b64 vcc, s[18:19], vcc
	v_cndmask_b32_e64 v32, 0, v37, s[0:1]
	v_cndmask_b32_e32 v31, 0, v33, vcc
	s_waitcnt vmcnt(63) expcnt(7) lgkmcnt(15)
	s_barrier

; DEVI unsigned pk_bf16(float lo, float hi) { unsigned r; asm("v_cvt_pk_bf16_f32 %0, %1, %2" : "=v"(r) : "v"(lo), "v"(hi)); return r; }
; DEVI void cvt_job(LAS float* tile, const float* src, int srcK, int srcN, bf16_t* dst, int dstLd, int dstRows, int dstCol0, int mode, const float* gk = nullptr) {
;     ...
;         for (int i = 0; i < 16; ++i) { const int k = kap0 + ty + 8 * i - dstCol0; regs[i] = (nok && k >= 0 && k < srcK) ? raw[i] * gs[i] : 0.f; }
;     };
;     auto emit = [&](int t, float (&regs)[16]) {
; #pragma unroll
;         for (int i = 0; i < 16; ++i) tile[(ty + 8 * i) * 65 + tx] = regs[i];
;         __syncthreads();
;         int rho0, kap0, n0; coords(t, rho0, kap0, n0);
;         const int tn = t + 2 * gridDim.x;
;         if (tn < ntot) gl(tn, regs);
; #pragma unroll
;         for (int i = 0; i < 8; ++i) { const int row = ty + 8 * i;
;             const float lo = tile[(2 * tx) * 65 + row], hi = tile[(2 * tx + 1) * 65 + row];
;             *(unsigned*)(dst + (size_t)(rho0 + row) * dstLd + kap0 + 2 * tx) = pk_bf16(lo, hi); }
.LBB0_156:
.LBB0_157:
	s_mul_hi_i32 s0, s24, 0x2e8ba2e9
	s_lshr_b32 s1, s0, 31
	s_ashr_i32 s0, s0, 4
	s_add_i32 s0, s0, s1
	s_mul_i32 s1, s0, 0x3ffff50
	s_add_i32 s1, s22, s1
	s_and_b32 s1, s1, 0x3fffffc
	s_or_b32 s1, s1, s21
	s_lshl_b32 s4, s1, 6
	ds_read2_b32 v[136:137], v56 offset0:65 offset1:73
	ds_read2_b32 v[138:139], v56 offset1:8
	v_add_u32_e32 v140, s4, v55
	s_lshl_b32 s0, s0, 7
	v_ashrrev_i32_e32 v141, 31, v140
	s_ashr_i32 s1, s0, 31
	v_lshlrev_b64 v[140:141], 12, v[140:141]
	v_lshl_add_u64 v[140:141], s[62:63], 0, v[140:141]
	s_lshl_b64 s[0:1], s[0:1], 1
	v_lshl_add_u64 v[140:141], v[140:141], 0, s[0:1]
	s_waitcnt lgkmcnt(0)
	v_cvt_pk_bf16_f32 v133, v138, v136
	v_lshl_add_u64 v[140:141], v[140:141], 0, v[34:35]
	v_add_u32_e32 v136, s4, v57
	global_store_dword v[140:141], v133, off
	v_cvt_pk_bf16_f32 v133, v139, v137
	v_ashrrev_i32_e32 v137, 31, v136
	v_lshlrev_b64 v[136:137], 12, v[136:137]
	v_lshl_add_u64 v[136:137], s[62:63], 0, v[136:137]
	v_lshl_add_u64 v[136:137], v[136:137], 0, s[0:1]
	v_lshl_add_u64 v[136:137], v[136:137], 0, v[34:35]
	ds_read2_b32 v[138:139], v56 offset0:16 offset1:24
	ds_read2_b32 v[140:141], v56 offset0:81 offset1:89
	global_store_dword v[136:137], v133, off
	v_add_u32_e32 v136, s4, v58
	v_ashrrev_i32_e32 v137, 31, v136
	v_lshlrev_b64 v[136:137], 12, v[136:137]
	v_lshl_add_u64 v[136:137], s[62:63], 0, v[136:137]
	v_lshl_add_u64 v[136:137], v[136:137], 0, s[0:1]
	v_lshl_add_u64 v[136:137], v[136:137], 0, v[34:35]
	s_waitcnt lgkmcnt(0)
	v_cvt_pk_bf16_f32 v133, v138, v140
	global_store_dword v[136:137], v133, off
	v_add_u32_e32 v136, s4, v59
	v_ashrrev_i32_e32 v137, 31, v136
	v_lshlrev_b64 v[136:137], 12, v[136:137]
	v_lshl_add_u64 v[136:137], s[62:63], 0, v[136:137]
	v_lshl_add_u64 v[136:137], v[136:137], 0, s[0:1]
	v_lshl_add_u64 v[136:137], v[136:137], 0, v[34:35]
	v_cvt_pk_bf16_f32 v133, v139, v141
	ds_read2_b32 v[138:139], v56 offset0:32 offset1:40
	ds_read2_b32 v[140:141], v56 offset0:97 offset1:105
	global_store_dword v[136:137], v133, off
	v_add_u32_e32 v136, s4, v60
	v_ashrrev_i32_e32 v137, 31, v136
	v_lshlrev_b64 v[136:137], 12, v[136:137]
	v_lshl_add_u64 v[136:137], s[62:63], 0, v[136:137]
	v_lshl_add_u64 v[136:137], v[136:137], 0, s[0:1]
	v_lshl_add_u64 v[136:137], v[136:137], 0, v[34:35]
	s_waitcnt lgkmcnt(0)
	v_cvt_pk_bf16_f32 v133, v138, v140
	global_store_dword v[136:137], v133, off
	v_add_u32_e32 v136, s4, v61
	v_ashrrev_i32_e32 v137, 31, v136
	v_lshlrev_b64 v[136:137], 12, v[136:137]
	v_lshl_add_u64 v[136:137], s[62:63], 0, v[136:137]
	v_lshl_add_u64 v[136:137], v[136:137], 0, s[0:1]
	v_lshl_add_u64 v[136:137], v[136:137], 0, v[34:35]
	v_cvt_pk_bf16_f32 v133, v139, v141
	ds_read2_b32 v[138:139], v56 offset0:48 offset1:56
	ds_read2_b32 v[140:141], v56 offset0:113 offset1:121
	global_store_dword v[136:137], v133, off
	v_add_u32_e32 v136, s4, v62
	v_ashrrev_i32_e32 v137, 31, v136
	v_lshlrev_b64 v[136:137], 12, v[136:137]
	v_lshl_add_u64 v[136:137], s[62:63], 0, v[136:137]
	v_lshl_add_u64 v[136:137], v[136:137], 0, s[0:1]
	v_lshl_add_u64 v[136:137], v[136:137], 0, v[34:35]
	s_waitcnt lgkmcnt(0)
	v_cvt_pk_bf16_f32 v133, v138, v140
	global_store_dword v[136:137], v133, off
	v_add_u32_e32 v136, s4, v63
	v_ashrrev_i32_e32 v137, 31, v136
	v_lshlrev_b64 v[136:137], 12, v[136:137]
	v_lshl_add_u64 v[136:137], s[62:63], 0, v[136:137]
	v_lshl_add_u64 v[136:137], v[136:137], 0, s[0:1]
	s_add_i32 s29, s33, s24
	v_lshl_add_u64 v[136:137], v[136:137], 0, v[34:35]
	s_cmpk_gt_i32 s29, 0x57f
	v_cvt_pk_bf16_f32 v133, v139, v141
	global_store_dword v[136:137], v133, off
	s_cselect_b32 s98, 1, 0
	v_cmp_gt_i32_e32 vcc, s26, v16
	v_cmp_gt_u32_e64 s[0:1], s27, v1
	s_waitcnt vmcnt(23)
	v_mul_f32_e32 v2, v93, v2
	s_and_b64 s[0:1], s[0:1], vcc
	v_cndmask_b32_e64 v2, 0, v2, s[0:1]
	v_cmp_gt_u32_e64 s[0:1], s27, v68
	s_waitcnt vmcnt(22)
	v_mul_f32_e32 v1, v91, v37
	s_and_b64 s[0:1], s[0:1], vcc
	v_cndmask_b32_e64 v1, 0, v1, s[0:1]
	v_cmp_gt_u32_e64 s[0:1], s27, v69
	s_waitcnt vmcnt(21)
	v_mul_f32_e32 v4, v89, v4
	s_and_b64 s[0:1], s[0:1], vcc
	v_cndmask_b32_e64 v4, 0, v4, s[0:1]
	v_cmp_gt_u32_e64 s[0:1], s27, v70
	s_waitcnt vmcnt(20)
	v_mul_f32_e32 v3, v87, v3
	s_and_b64 s[0:1], s[0:1], vcc
	v_cndmask_b32_e64 v3, 0, v3, s[0:1]
	v_cmp_gt_u32_e64 s[0:1], s27, v71
	s_waitcnt vmcnt(19)
	v_mul_f32_e32 v6, v85, v6
	s_and_b64 s[0:1], s[0:1], vcc
	v_cndmask_b32_e64 v6, 0, v6, s[0:1]
	v_cmp_gt_u32_e64 s[0:1], s27, v72
	s_waitcnt vmcnt(18)
	v_mul_f32_e32 v15, v83, v15
	s_and_b64 s[0:1], s[0:1], vcc
	s_waitcnt vmcnt(17)
	v_mul_f32_e32 v16, v82, v5
	v_cmp_gt_u32_e64 s[4:5], s27, v73
	v_cndmask_b32_e64 v5, 0, v15, s[0:1]
	v_cmp_gt_u32_e64 s[0:1], s27, v67
	s_waitcnt vmcnt(16)
	v_mul_f32_e32 v12, v81, v12
	v_cmp_gt_u32_e64 s[6:7], s27, v74
	s_and_b64 s[4:5], s[4:5], vcc
	s_and_b64 s[0:1], s[0:1], vcc
	s_waitcnt vmcnt(15)
	v_mul_f32_e32 v15, v95, v36
	v_cmp_gt_u32_e64 s[8:9], s27, v75
	s_waitcnt vmcnt(9)
	v_mul_f32_e32 v38, v84, v8
	v_cndmask_b32_e64 v8, 0, v16, s[4:5]
	v_cmp_gt_u32_e64 s[4:5], s27, v33
	s_waitcnt vmcnt(8)
	v_mul_f32_e32 v33, v80, v7
	v_cndmask_b32_e64 v7, 0, v12, s[0:1]
	s_and_b64 s[0:1], s[6:7], vcc
	v_mul_f32_e32 v14, v94, v14
	v_cmp_gt_u32_e64 s[10:11], s27, v76
	v_mul_f32_e32 v36, v88, v10
	v_cndmask_b32_e64 v10, 0, v15, s[0:1]
	s_and_b64 s[0:1], s[8:9], vcc
	v_mul_f32_e32 v13, v92, v13
	v_cmp_gt_u32_e64 s[12:13], s27, v77
	v_mul_f32_e32 v37, v86, v9
	v_cndmask_b32_e64 v9, 0, v14, s[0:1]
	s_and_b64 s[0:1], s[10:11], vcc
	v_mul_f32_e32 v11, v90, v11
	v_cmp_gt_u32_e64 s[14:15], s27, v78
	v_cndmask_b32_e64 v12, 0, v13, s[0:1]
	s_and_b64 s[0:1], s[12:13], vcc
	v_cmp_gt_u32_e64 s[16:17], s27, v79
	v_cndmask_b32_e64 v11, 0, v11, s[0:1]
	s_and_b64 s[0:1], s[14:15], vcc
	v_cmp_gt_u32_e64 s[18:19], s27, v66
	v_cndmask_b32_e64 v14, 0, v36, s[0:1]
	s_and_b64 s[0:1], s[16:17], vcc
	v_cndmask_b32_e64 v13, 0, v37, s[0:1]
	s_and_b64 s[0:1], s[4:5], vcc
	s_and_b64 vcc, s[18:19], vcc
	v_cndmask_b32_e64 v16, 0, v38, s[0:1]
	v_cndmask_b32_e32 v15, 0, v33, vcc
	s_cmp_lg_u32 s98, 0
	s_waitcnt vmcnt(63) expcnt(7) lgkmcnt(15)
	s_barrier
; DEVI void cvt_job(LAS float* tile, const float* src, int srcK, int srcN, bf16_t* dst, int dstLd, int dstRows, int dstCol0, int mode, const float* gk = nullptr) {
;     ...
;         const int n = n0 + tx, nc = n < srcN ? n : srcN - 1;
;         const bool nok = n < srcN;
;         float raw[16], gs[16];
; #pragma unroll
;         for (int i = 0; i < 16; ++i) { const int k = kap0 + ty + 8 * i - dstCol0; const int kc = k < 0 ? 0 : (k < srcK ? k : srcK - 1);
;             raw[i] = __builtin_nontemporal_load(src + (size_t)kc * srcN + nc); }
;         if (gk) {
; #pragma unroll
;             for (int i = 0; i < 16; ++i) { const int k = kap0 + ty + 8 * i - dstCol0; const int kc = k < 0 ? 0 : (k < srcK ? k : srcK - 1); gs[i] = gk[kc]; }
;         } else {
; #pragma unroll
;             for (int i = 0; i < 16; ++i) gs[i] = 1.0f;
;         }
; #pragma unroll
;         for (int i = 0; i < 16; ++i) { const int k = kap0 + ty + 8 * i - dstCol0; regs[i] = (nok && k >= 0 && k < srcK) ? raw[i] * gs[i] : 0.f; }
;     };
;     auto emit = [&](int t, float (&regs)[16]) {
; #pragma unroll
;         for (int i = 0; i < 16; ++i) tile[(ty + 8 * i) * 65 + tx] = regs[i];
;         __syncthreads();
;         int rho0, kap0, n0; coords(t, rho0, kap0, n0);
;         const int tn = t + 2 * gridDim.x;
;         if (tn < ntot) gl(tn, regs);
	s_cbranch_scc1 .LBB0_151
	s_add_i32 s0, s31, s24
	s_cmpk_gt_i32 s0, 0x57f
	ds_write_b32 v64, v18
	ds_write_b32 v64, v17 offset:2080
	ds_write_b32 v64, v20 offset:4160
	ds_write_b32 v64, v19 offset:6240
	ds_write_b32 v64, v22 offset:8320
	ds_write_b32 v64, v21 offset:10400
	ds_write_b32 v64, v24 offset:12480
	ds_write_b32 v64, v23 offset:14560
	ds_write_b32 v64, v26 offset:16640
	ds_write_b32 v64, v25 offset:18720
	ds_write_b32 v64, v28 offset:20800
	ds_write_b32 v64, v27 offset:22880
	ds_write_b32 v64, v30 offset:24960
	ds_write_b32 v64, v29 offset:27040
	ds_write_b32 v64, v32 offset:29120
	ds_write_b32 v64, v31 offset:31200
	s_waitcnt lgkmcnt(0)
	s_barrier
	s_cbranch_scc1 .LBB0_150
	s_mul_hi_i32 s0, s0, 0x2e8ba2e9
	s_lshr_b32 s1, s0, 31
	s_ashr_i32 s0, s0, 4
	s_add_i32 s0, s0, s1
	s_mul_i32 s4, s33, 6
	s_mul_i32 s1, s0, 0x3ffff50
	s_add_i32 s4, s4, s22
	s_add_i32 s4, s4, s1
	s_and_b32 s1, s4, 0x3fffffc
	s_or_b32 s1, s1, s20
	s_lshl_b32 s1, s1, 6
	s_ashr_i32 s4, s1, 1
	s_and_b32 s4, s4, 0xffffff80
	s_and_b32 s1, s1, 64
	s_or_b32 s1, s1, s4
	v_or_b32_e32 v52, s1, v54
	v_min_i32_e32 v18, 0x15ff, v52
	v_lshl_add_u32 v17, s0, 7, v55
	v_ashrrev_i32_e32 v19, 31, v18
	v_lshl_add_u64 v[94:95], v[18:19], 2, s[54:55]
	v_med3_i32 v18, v17, 0, v65
	v_add_u32_e32 v68, 8, v17
	v_add_u32_e32 v69, 16, v17
	v_add_u32_e32 v70, 24, v17
	v_add_u32_e32 v71, 32, v17
	v_add_u32_e32 v72, 40, v17
	v_add_u32_e32 v73, 48, v17
	v_add_u32_e32 v67, 56, v17
	v_mad_u64_u32 v[36:37], s[0:1], v18, s25, v[94:95]
	v_med3_i32 v20, v68, 0, v65
	v_med3_i32 v22, v69, 0, v65
	v_med3_i32 v24, v70, 0, v65
	v_med3_i32 v26, v71, 0, v65
	v_med3_i32 v28, v72, 0, v65
	v_med3_i32 v30, v73, 0, v65
	v_med3_i32 v32, v67, 0, v65
	v_add_u32_e32 v74, 64, v17
	v_mad_u64_u32 v[38:39], s[0:1], v20, s25, v[94:95]
	v_mad_u64_u32 v[40:41], s[0:1], v22, s25, v[94:95]
	v_mad_u64_u32 v[42:43], s[0:1], v24, s25, v[94:95]
	v_mad_u64_u32 v[44:45], s[0:1], v26, s25, v[94:95]
	v_mad_u64_u32 v[46:47], s[0:1], v28, s25, v[94:95]
	v_mad_u64_u32 v[48:49], s[0:1], v30, s25, v[94:95]
	v_mad_u64_u32 v[50:51], s[0:1], v32, s25, v[94:95]
	global_load_dword v93, v[36:37], off nt
	global_load_dword v91, v[38:39], off nt
	global_load_dword v89, v[40:41], off nt
	global_load_dword v87, v[42:43], off nt
	global_load_dword v85, v[44:45], off nt
	global_load_dword v83, v[46:47], off nt
	global_load_dword v82, v[48:49], off nt
	global_load_dword v81, v[50:51], off nt
	v_med3_i32 v36, v74, 0, v65
	v_add_u32_e32 v75, 0x48, v17
	v_add_u32_e32 v76, 0x50, v17
	v_add_u32_e32 v77, 0x58, v17
	v_add_u32_e32 v78, 0x60, v17
	v_add_u32_e32 v79, 0x68, v17
	v_add_u32_e32 v53, 0x70, v17
	v_add_u32_e32 v66, 0x78, v17
	v_mad_u64_u32 v[96:97], s[0:1], v36, s25, v[94:95]
	v_med3_i32 v38, v75, 0, v65
	v_med3_i32 v40, v76, 0, v65
	v_med3_i32 v42, v77, 0, v65
	v_med3_i32 v44, v78, 0, v65
	v_med3_i32 v46, v79, 0, v65
	v_med3_i32 v48, v53, 0, v65
	v_med3_i32 v50, v66, 0, v65
	v_mad_u64_u32 v[98:99], s[0:1], v38, s25, v[94:95]
	v_mad_u64_u32 v[100:101], s[0:1], v40, s25, v[94:95]
	v_mad_u64_u32 v[102:103], s[0:1], v42, s25, v[94:95]
	v_mad_u64_u32 v[104:105], s[0:1], v44, s25, v[94:95]
	v_mad_u64_u32 v[106:107], s[0:1], v46, s25, v[94:95]
	v_mad_u64_u32 v[108:109], s[0:1], v48, s25, v[94:95]
	v_mad_u64_u32 v[110:111], s[0:1], v50, s25, v[94:95]
	global_load_dword v95, v[96:97], off nt
	global_load_dword v94, v[98:99], off nt
	global_load_dword v92, v[100:101], off nt
	global_load_dword v90, v[102:103], off nt
	global_load_dword v88, v[104:105], off nt
	global_load_dword v86, v[106:107], off nt
	global_load_dword v84, v[108:109], off nt
	global_load_dword v80, v[110:111], off nt
	v_readlane_b32 s0, v240, 48
	v_readlane_b32 s1, v240, 49
	s_and_b64 vcc, exec, s[0:1]
	s_cbranch_vccz .LBB0_148
	v_mov_b32_e32 v23, 1.0
	v_mov_b32_e32 v24, 1.0
	v_mov_b32_e32 v25, 1.0
	v_mov_b32_e32 v26, 1.0
	v_mov_b32_e32 v27, 1.0
	v_mov_b32_e32 v29, 1.0
	v_mov_b32_e32 v30, 1.0
	v_mov_b32_e32 v32, 1.0
	v_mov_b32_e32 v28, 1.0
	v_mov_b32_e32 v21, 1.0
	v_mov_b32_e32 v31, 1.0
	v_mov_b32_e32 v22, 1.0
	v_mov_b32_e32 v19, 1.0
	v_mov_b32_e32 v20, 1.0
	v_mov_b32_e32 v33, 1.0
	v_mov_b32_e32 v18, 1.0
	s_branch .LBB0_149

; DEVI unsigned pk_bf16(float lo, float hi) { unsigned r; asm("v_cvt_pk_bf16_f32 %0, %1, %2" : "=v"(r) : "v"(lo), "v"(hi)); return r; }
; DEVI void cvt_job(LAS float* tile, const float* src, int srcK, int srcN, bf16_t* dst, int dstLd, int dstRows, int dstCol0, int mode, const float* gk = nullptr) {
;     ...
;         for (int i = 0; i < 16; ++i) { const int k = kap0 + ty + 8 * i - dstCol0; regs[i] = (nok && k >= 0 && k < srcK) ? raw[i] * gs[i] : 0.f; }
;     };
;     auto emit = [&](int t, float (&regs)[16]) {
; #pragma unroll
;         for (int i = 0; i < 16; ++i) tile[(ty + 8 * i) * 65 + tx] = regs[i];
;         __syncthreads();
;         int rho0, kap0, n0; coords(t, rho0, kap0, n0);
;         const int tn = t + 2 * gridDim.x;
;         if (tn < ntot) gl(tn, regs);
; #pragma unroll
;         for (int i = 0; i < 8; ++i) { const int row = ty + 8 * i;
;             const float lo = tile[(2 * tx) * 65 + row], hi = tile[(2 * tx + 1) * 65 + row];
;             *(unsigned*)(dst + (size_t)(rho0 + row) * dstLd + kap0 + 2 * tx) = pk_bf16(lo, hi); }
.LBB0_174:
.LBB0_175:
	s_mul_hi_i32 s0, s29, 0x2e8ba2e9
	s_lshr_b32 s1, s0, 31
	s_ashr_i32 s0, s0, 4
	s_add_i32 s0, s0, s1
	s_mul_i32 s1, s0, 0x3ffff50
	s_add_i32 s4, s30, s23
	s_add_i32 s4, s4, s1
	s_and_b32 s1, s4, 0x3fffffc
	s_or_b32 s1, s1, s21
	s_lshl_b32 s1, s1, 6
	s_or_b32 s4, s1, 0x80
	ds_read2_b32 v[136:137], v56 offset0:65 offset1:73
	ds_read2_b32 v[138:139], v56 offset1:8
	v_add_u32_e32 v140, s4, v55
	s_lshl_b32 s0, s0, 7
	v_ashrrev_i32_e32 v141, 31, v140
	s_ashr_i32 s1, s0, 31
	v_lshlrev_b64 v[140:141], 12, v[140:141]
	v_lshl_add_u64 v[140:141], s[62:63], 0, v[140:141]
	s_lshl_b64 s[0:1], s[0:1], 1
	v_lshl_add_u64 v[140:141], v[140:141], 0, s[0:1]
	s_waitcnt lgkmcnt(0)
	v_cvt_pk_bf16_f32 v133, v138, v136
	v_lshl_add_u64 v[140:141], v[140:141], 0, v[34:35]
	v_add_u32_e32 v136, s4, v57
	global_store_dword v[140:141], v133, off
	v_cvt_pk_bf16_f32 v133, v139, v137
	v_ashrrev_i32_e32 v137, 31, v136
	v_lshlrev_b64 v[136:137], 12, v[136:137]
	v_lshl_add_u64 v[136:137], s[62:63], 0, v[136:137]
	v_lshl_add_u64 v[136:137], v[136:137], 0, s[0:1]
	v_lshl_add_u64 v[136:137], v[136:137], 0, v[34:35]
	ds_read2_b32 v[138:139], v56 offset0:16 offset1:24
	ds_read2_b32 v[140:141], v56 offset0:81 offset1:89
	global_store_dword v[136:137], v133, off
	v_add_u32_e32 v136, s4, v58
	v_ashrrev_i32_e32 v137, 31, v136
	v_lshlrev_b64 v[136:137], 12, v[136:137]
	v_lshl_add_u64 v[136:137], s[62:63], 0, v[136:137]
	v_lshl_add_u64 v[136:137], v[136:137], 0, s[0:1]
	v_lshl_add_u64 v[136:137], v[136:137], 0, v[34:35]
	s_waitcnt lgkmcnt(0)
	v_cvt_pk_bf16_f32 v133, v138, v140
	global_store_dword v[136:137], v133, off
	v_add_u32_e32 v136, s4, v59
	v_ashrrev_i32_e32 v137, 31, v136
	v_lshlrev_b64 v[136:137], 12, v[136:137]
	v_lshl_add_u64 v[136:137], s[62:63], 0, v[136:137]
	v_lshl_add_u64 v[136:137], v[136:137], 0, s[0:1]
	v_lshl_add_u64 v[136:137], v[136:137], 0, v[34:35]
	v_cvt_pk_bf16_f32 v133, v139, v141
	ds_read2_b32 v[138:139], v56 offset0:32 offset1:40
	ds_read2_b32 v[140:141], v56 offset0:97 offset1:105
	global_store_dword v[136:137], v133, off
	v_add_u32_e32 v136, s4, v60
	v_ashrrev_i32_e32 v137, 31, v136
	v_lshlrev_b64 v[136:137], 12, v[136:137]
	v_lshl_add_u64 v[136:137], s[62:63], 0, v[136:137]
	v_lshl_add_u64 v[136:137], v[136:137], 0, s[0:1]
	v_lshl_add_u64 v[136:137], v[136:137], 0, v[34:35]
	s_waitcnt lgkmcnt(0)
	v_cvt_pk_bf16_f32 v133, v138, v140
	global_store_dword v[136:137], v133, off
	v_add_u32_e32 v136, s4, v61
	v_ashrrev_i32_e32 v137, 31, v136
	v_lshlrev_b64 v[136:137], 12, v[136:137]
	v_lshl_add_u64 v[136:137], s[62:63], 0, v[136:137]
	v_lshl_add_u64 v[136:137], v[136:137], 0, s[0:1]
	v_lshl_add_u64 v[136:137], v[136:137], 0, v[34:35]
	v_cvt_pk_bf16_f32 v133, v139, v141
	ds_read2_b32 v[138:139], v56 offset0:48 offset1:56
	ds_read2_b32 v[140:141], v56 offset0:113 offset1:121
	global_store_dword v[136:137], v133, off
	v_add_u32_e32 v136, s4, v62
	v_ashrrev_i32_e32 v137, 31, v136
	v_lshlrev_b64 v[136:137], 12, v[136:137]
	v_lshl_add_u64 v[136:137], s[62:63], 0, v[136:137]
	v_lshl_add_u64 v[136:137], v[136:137], 0, s[0:1]
	v_lshl_add_u64 v[136:137], v[136:137], 0, v[34:35]
	s_waitcnt lgkmcnt(0)
	v_cvt_pk_bf16_f32 v133, v138, v140
	global_store_dword v[136:137], v133, off
	v_add_u32_e32 v136, s4, v63
	v_ashrrev_i32_e32 v137, 31, v136
	v_lshlrev_b64 v[136:137], 12, v[136:137]
	v_lshl_add_u64 v[136:137], s[62:63], 0, v[136:137]
	v_lshl_add_u64 v[136:137], v[136:137], 0, s[0:1]
	v_lshl_add_u64 v[136:137], v[136:137], 0, v[34:35]
	v_cvt_pk_bf16_f32 v133, v139, v141
	global_store_dword v[136:137], v133, off
	v_cmp_gt_i32_e32 vcc, s26, v52
	v_cmp_gt_u32_e64 s[0:1], s27, v17
	s_waitcnt vmcnt(23)
	v_mul_f32_e32 v18, v93, v18
	s_and_b64 s[0:1], s[0:1], vcc
	v_cndmask_b32_e64 v18, 0, v18, s[0:1]
	v_cmp_gt_u32_e64 s[0:1], s27, v68
	s_waitcnt vmcnt(22)
	v_mul_f32_e32 v17, v91, v33
	s_and_b64 s[0:1], s[0:1], vcc
	v_cndmask_b32_e64 v17, 0, v17, s[0:1]
	v_cmp_gt_u32_e64 s[0:1], s27, v69
	s_waitcnt vmcnt(21)
	v_mul_f32_e32 v20, v89, v20
	s_and_b64 s[0:1], s[0:1], vcc
	v_cndmask_b32_e64 v20, 0, v20, s[0:1]
	v_cmp_gt_u32_e64 s[0:1], s27, v70
	s_waitcnt vmcnt(20)
	v_mul_f32_e32 v19, v87, v19
	s_and_b64 s[0:1], s[0:1], vcc
	v_cndmask_b32_e64 v19, 0, v19, s[0:1]
	v_cmp_gt_u32_e64 s[0:1], s27, v71
	s_waitcnt vmcnt(19)
	v_mul_f32_e32 v22, v85, v22
	s_and_b64 s[0:1], s[0:1], vcc
	v_cndmask_b32_e64 v22, 0, v22, s[0:1]
	v_cmp_gt_u32_e64 s[0:1], s27, v72
	s_waitcnt vmcnt(18)
	v_mul_f32_e32 v31, v83, v31
	s_and_b64 s[0:1], s[0:1], vcc
	s_waitcnt vmcnt(17)
	v_mul_f32_e32 v33, v82, v21
	v_cmp_gt_u32_e64 s[4:5], s27, v73
	v_cndmask_b32_e64 v21, 0, v31, s[0:1]
	v_cmp_gt_u32_e64 s[0:1], s27, v67
	s_waitcnt vmcnt(16)
	v_mul_f32_e32 v28, v81, v28
	v_cmp_gt_u32_e64 s[6:7], s27, v74
	s_and_b64 s[4:5], s[4:5], vcc
	s_and_b64 s[0:1], s[0:1], vcc
	s_waitcnt vmcnt(15)
	v_mul_f32_e32 v31, v95, v32
	v_cmp_gt_u32_e64 s[8:9], s27, v75
	s_waitcnt vmcnt(9)
	v_mul_f32_e32 v37, v84, v24
	v_cndmask_b32_e64 v24, 0, v33, s[4:5]
	s_waitcnt vmcnt(8)
	v_mul_f32_e32 v33, v80, v23
	v_cndmask_b32_e64 v23, 0, v28, s[0:1]
	s_and_b64 s[0:1], s[6:7], vcc
	v_mul_f32_e32 v30, v94, v30
	v_cmp_gt_u32_e64 s[10:11], s27, v76
	v_mul_f32_e32 v32, v88, v26
	v_cndmask_b32_e64 v26, 0, v31, s[0:1]
	s_and_b64 s[0:1], s[8:9], vcc
	v_mul_f32_e32 v29, v92, v29
	v_cmp_gt_u32_e64 s[12:13], s27, v77
	v_mul_f32_e32 v36, v86, v25
	v_cndmask_b32_e64 v25, 0, v30, s[0:1]
	s_and_b64 s[0:1], s[10:11], vcc
	v_mul_f32_e32 v27, v90, v27
	v_cmp_gt_u32_e64 s[14:15], s27, v78
	v_cndmask_b32_e64 v28, 0, v29, s[0:1]
	s_and_b64 s[0:1], s[12:13], vcc
	v_cmp_gt_u32_e64 s[16:17], s27, v79
	v_cndmask_b32_e64 v27, 0, v27, s[0:1]
	s_and_b64 s[0:1], s[14:15], vcc
	v_cmp_gt_u32_e64 s[4:5], s27, v53
	v_cmp_gt_u32_e64 s[18:19], s27, v66
	v_cndmask_b32_e64 v30, 0, v32, s[0:1]
	s_and_b64 s[0:1], s[16:17], vcc
	v_cndmask_b32_e64 v29, 0, v36, s[0:1]
	s_and_b64 s[0:1], s[4:5], vcc
	s_and_b64 vcc, s[18:19], vcc
	v_cndmask_b32_e64 v32, 0, v37, s[0:1]
	v_cndmask_b32_e32 v31, 0, v33, vcc
	s_waitcnt vmcnt(63) expcnt(7) lgkmcnt(15)
	s_barrier

; DEVI unsigned pk_bf16(float lo, float hi) { unsigned r; asm("v_cvt_pk_bf16_f32 %0, %1, %2" : "=v"(r) : "v"(lo), "v"(hi)); return r; }
; DEVI void cvt_job(LAS float* tile, const float* src, int srcK, int srcN, bf16_t* dst, int dstLd, int dstRows, int dstCol0, int mode, const float* gk = nullptr) {
;     ...
;         for (int i = 0; i < 16; ++i) { const int k = kap0 + ty + 8 * i - dstCol0; regs[i] = (nok && k >= 0 && k < srcK) ? raw[i] * gs[i] : 0.f; }
;     };
;     auto emit = [&](int t, float (&regs)[16]) {
; #pragma unroll
;         for (int i = 0; i < 16; ++i) tile[(ty + 8 * i) * 65 + tx] = regs[i];
;         __syncthreads();
;         int rho0, kap0, n0; coords(t, rho0, kap0, n0);
;         const int tn = t + 2 * gridDim.x;
;         if (tn < ntot) gl(tn, regs);
; #pragma unroll
;         for (int i = 0; i < 8; ++i) { const int row = ty + 8 * i;
;             const float lo = tile[(2 * tx) * 65 + row], hi = tile[(2 * tx + 1) * 65 + row];
;             *(unsigned*)(dst + (size_t)(rho0 + row) * dstLd + kap0 + 2 * tx) = pk_bf16(lo, hi); }
.LBB0_181:
.LBB0_182:
	s_mul_hi_i32 s0, s20, 0x2e8ba2e9
	s_lshr_b32 s1, s0, 31
	s_ashr_i32 s0, s0, 4
	s_add_i32 s0, s0, s1
	s_mul_i32 s1, s0, 0x3ffff50
	s_add_i32 s1, s23, s1
	s_and_b32 s1, s1, 0x3fffffc
	s_or_b32 s1, s1, s22
	s_lshl_b32 s1, s1, 6
	s_or_b32 s4, s1, 0x80
	ds_read2_b32 v[136:137], v56 offset0:65 offset1:73
	ds_read2_b32 v[138:139], v56 offset1:8
	v_add_u32_e32 v140, s4, v55
	s_lshl_b32 s0, s0, 7
	v_ashrrev_i32_e32 v141, 31, v140
	s_ashr_i32 s1, s0, 31
	v_lshlrev_b64 v[140:141], 12, v[140:141]
	v_lshl_add_u64 v[140:141], s[62:63], 0, v[140:141]
	s_lshl_b64 s[0:1], s[0:1], 1
	v_lshl_add_u64 v[140:141], v[140:141], 0, s[0:1]
	s_waitcnt lgkmcnt(0)
	v_cvt_pk_bf16_f32 v133, v138, v136
	v_lshl_add_u64 v[140:141], v[140:141], 0, v[34:35]
	v_add_u32_e32 v136, s4, v57
	global_store_dword v[140:141], v133, off
	v_cvt_pk_bf16_f32 v133, v139, v137
	v_ashrrev_i32_e32 v137, 31, v136
	v_lshlrev_b64 v[136:137], 12, v[136:137]
	v_lshl_add_u64 v[136:137], s[62:63], 0, v[136:137]
	v_lshl_add_u64 v[136:137], v[136:137], 0, s[0:1]
	v_lshl_add_u64 v[136:137], v[136:137], 0, v[34:35]
	ds_read2_b32 v[138:139], v56 offset0:16 offset1:24
	ds_read2_b32 v[140:141], v56 offset0:81 offset1:89
	global_store_dword v[136:137], v133, off
	v_add_u32_e32 v136, s4, v58
	v_ashrrev_i32_e32 v137, 31, v136
	v_lshlrev_b64 v[136:137], 12, v[136:137]
	v_lshl_add_u64 v[136:137], s[62:63], 0, v[136:137]
	v_lshl_add_u64 v[136:137], v[136:137], 0, s[0:1]
	v_lshl_add_u64 v[136:137], v[136:137], 0, v[34:35]
	s_waitcnt lgkmcnt(0)
	v_cvt_pk_bf16_f32 v133, v138, v140
	global_store_dword v[136:137], v133, off
	v_add_u32_e32 v136, s4, v59
	v_ashrrev_i32_e32 v137, 31, v136
	v_lshlrev_b64 v[136:137], 12, v[136:137]
	v_lshl_add_u64 v[136:137], s[62:63], 0, v[136:137]
	v_lshl_add_u64 v[136:137], v[136:137], 0, s[0:1]
	v_lshl_add_u64 v[136:137], v[136:137], 0, v[34:35]
	v_cvt_pk_bf16_f32 v133, v139, v141
	ds_read2_b32 v[138:139], v56 offset0:32 offset1:40
	ds_read2_b32 v[140:141], v56 offset0:97 offset1:105
	global_store_dword v[136:137], v133, off
	v_add_u32_e32 v136, s4, v60
	v_ashrrev_i32_e32 v137, 31, v136
	v_lshlrev_b64 v[136:137], 12, v[136:137]
	v_lshl_add_u64 v[136:137], s[62:63], 0, v[136:137]
	v_lshl_add_u64 v[136:137], v[136:137], 0, s[0:1]
	v_lshl_add_u64 v[136:137], v[136:137], 0, v[34:35]
	s_waitcnt lgkmcnt(0)
	v_cvt_pk_bf16_f32 v133, v138, v140
	global_store_dword v[136:137], v133, off
	v_add_u32_e32 v136, s4, v61
	v_ashrrev_i32_e32 v137, 31, v136
	v_lshlrev_b64 v[136:137], 12, v[136:137]
	v_lshl_add_u64 v[136:137], s[62:63], 0, v[136:137]
	v_lshl_add_u64 v[136:137], v[136:137], 0, s[0:1]
	v_lshl_add_u64 v[136:137], v[136:137], 0, v[34:35]
	v_cvt_pk_bf16_f32 v133, v139, v141
	ds_read2_b32 v[138:139], v56 offset0:48 offset1:56
	ds_read2_b32 v[140:141], v56 offset0:113 offset1:121
	global_store_dword v[136:137], v133, off
	v_add_u32_e32 v136, s4, v62
	v_ashrrev_i32_e32 v137, 31, v136
	v_lshlrev_b64 v[136:137], 12, v[136:137]
	v_lshl_add_u64 v[136:137], s[62:63], 0, v[136:137]
	v_lshl_add_u64 v[136:137], v[136:137], 0, s[0:1]
	v_lshl_add_u64 v[136:137], v[136:137], 0, v[34:35]
	s_waitcnt lgkmcnt(0)
	v_cvt_pk_bf16_f32 v133, v138, v140
	global_store_dword v[136:137], v133, off
	v_add_u32_e32 v136, s4, v63
	v_ashrrev_i32_e32 v137, 31, v136
	v_lshlrev_b64 v[136:137], 12, v[136:137]
	v_lshl_add_u64 v[136:137], s[62:63], 0, v[136:137]
	v_lshl_add_u64 v[136:137], v[136:137], 0, s[0:1]
	s_add_i32 s29, s33, s20
	v_lshl_add_u64 v[136:137], v[136:137], 0, v[34:35]
	s_cmpk_gt_i32 s29, 0x57f
	v_cvt_pk_bf16_f32 v133, v139, v141
	global_store_dword v[136:137], v133, off
	s_cselect_b32 s98, 1, 0
	v_cmp_gt_i32_e32 vcc, s26, v16
	v_cmp_gt_u32_e64 s[0:1], s27, v1
	s_waitcnt vmcnt(23)
	v_mul_f32_e32 v2, v93, v2
	s_and_b64 s[0:1], s[0:1], vcc
	v_cndmask_b32_e64 v2, 0, v2, s[0:1]
	v_cmp_gt_u32_e64 s[0:1], s27, v68
	s_waitcnt vmcnt(22)
	v_mul_f32_e32 v1, v91, v37
	s_and_b64 s[0:1], s[0:1], vcc
	v_cndmask_b32_e64 v1, 0, v1, s[0:1]
	v_cmp_gt_u32_e64 s[0:1], s27, v69
	s_waitcnt vmcnt(21)
	v_mul_f32_e32 v4, v89, v4
	s_and_b64 s[0:1], s[0:1], vcc
	v_cndmask_b32_e64 v4, 0, v4, s[0:1]
	v_cmp_gt_u32_e64 s[0:1], s27, v70
	s_waitcnt vmcnt(20)
	v_mul_f32_e32 v3, v87, v3
	s_and_b64 s[0:1], s[0:1], vcc
	v_cndmask_b32_e64 v3, 0, v3, s[0:1]
	v_cmp_gt_u32_e64 s[0:1], s27, v71
	s_waitcnt vmcnt(19)
	v_mul_f32_e32 v6, v85, v6
	s_and_b64 s[0:1], s[0:1], vcc
	v_cndmask_b32_e64 v6, 0, v6, s[0:1]
	v_cmp_gt_u32_e64 s[0:1], s27, v72
	s_waitcnt vmcnt(18)
	v_mul_f32_e32 v15, v83, v15
	s_and_b64 s[0:1], s[0:1], vcc
	s_waitcnt vmcnt(17)
	v_mul_f32_e32 v16, v82, v5
	v_cmp_gt_u32_e64 s[4:5], s27, v73
	v_cndmask_b32_e64 v5, 0, v15, s[0:1]
	v_cmp_gt_u32_e64 s[0:1], s27, v67
	s_waitcnt vmcnt(16)
	v_mul_f32_e32 v12, v81, v12
	v_cmp_gt_u32_e64 s[6:7], s27, v74
	s_and_b64 s[4:5], s[4:5], vcc
	s_and_b64 s[0:1], s[0:1], vcc
	s_waitcnt vmcnt(15)
	v_mul_f32_e32 v15, v95, v36
	v_cmp_gt_u32_e64 s[8:9], s27, v75
	s_waitcnt vmcnt(9)
	v_mul_f32_e32 v38, v84, v8
	v_cndmask_b32_e64 v8, 0, v16, s[4:5]
	v_cmp_gt_u32_e64 s[4:5], s27, v33
	s_waitcnt vmcnt(8)
	v_mul_f32_e32 v33, v80, v7
	v_cndmask_b32_e64 v7, 0, v12, s[0:1]
	s_and_b64 s[0:1], s[6:7], vcc
	v_mul_f32_e32 v14, v94, v14
	v_cmp_gt_u32_e64 s[10:11], s27, v76
	v_mul_f32_e32 v36, v88, v10
	v_cndmask_b32_e64 v10, 0, v15, s[0:1]
	s_and_b64 s[0:1], s[8:9], vcc
	v_mul_f32_e32 v13, v92, v13
	v_cmp_gt_u32_e64 s[12:13], s27, v77
	v_mul_f32_e32 v37, v86, v9
	v_cndmask_b32_e64 v9, 0, v14, s[0:1]
	s_and_b64 s[0:1], s[10:11], vcc
	v_mul_f32_e32 v11, v90, v11
	v_cmp_gt_u32_e64 s[14:15], s27, v78
	v_cndmask_b32_e64 v12, 0, v13, s[0:1]
	s_and_b64 s[0:1], s[12:13], vcc
	v_cmp_gt_u32_e64 s[16:17], s27, v79
	v_cndmask_b32_e64 v11, 0, v11, s[0:1]
	s_and_b64 s[0:1], s[14:15], vcc
	v_cmp_gt_u32_e64 s[18:19], s27, v66
	v_cndmask_b32_e64 v14, 0, v36, s[0:1]
	s_and_b64 s[0:1], s[16:17], vcc
	v_cndmask_b32_e64 v13, 0, v37, s[0:1]
	s_and_b64 s[0:1], s[4:5], vcc
	s_and_b64 vcc, s[18:19], vcc
	v_cndmask_b32_e64 v16, 0, v38, s[0:1]
	v_cndmask_b32_e32 v15, 0, v33, vcc
	s_cmp_lg_u32 s98, 0
	s_waitcnt vmcnt(63) expcnt(7) lgkmcnt(15)
	s_barrier
; DEVI void cvt_job(LAS float* tile, const float* src, int srcK, int srcN, bf16_t* dst, int dstLd, int dstRows, int dstCol0, int mode, const float* gk = nullptr) {
;     ...
;         const int n = n0 + tx, nc = n < srcN ? n : srcN - 1;
;         const bool nok = n < srcN;
;         float raw[16], gs[16];
; #pragma unroll
;         for (int i = 0; i < 16; ++i) { const int k = kap0 + ty + 8 * i - dstCol0; const int kc = k < 0 ? 0 : (k < srcK ? k : srcK - 1);
;             raw[i] = __builtin_nontemporal_load(src + (size_t)kc * srcN + nc); }
;         if (gk) {
; #pragma unroll
;             for (int i = 0; i < 16; ++i) { const int k = kap0 + ty + 8 * i - dstCol0; const int kc = k < 0 ? 0 : (k < srcK ? k : srcK - 1); gs[i] = gk[kc]; }
;         } else {
; #pragma unroll
;             for (int i = 0; i < 16; ++i) gs[i] = 1.0f;
;         }
; #pragma unroll
;         for (int i = 0; i < 16; ++i) { const int k = kap0 + ty + 8 * i - dstCol0; regs[i] = (nok && k >= 0 && k < srcK) ? raw[i] * gs[i] : 0.f; }
;     };
;     auto emit = [&](int t, float (&regs)[16]) {
; #pragma unroll
;         for (int i = 0; i < 16; ++i) tile[(ty + 8 * i) * 65 + tx] = regs[i];
;         __syncthreads();
;         int rho0, kap0, n0; coords(t, rho0, kap0, n0);
;         const int tn = t + 2 * gridDim.x;
;         if (tn < ntot) gl(tn, regs);
	s_cbranch_scc1 .LBB0_176
	s_add_i32 s0, s31, s20
	s_cmpk_gt_i32 s0, 0x57f
	ds_write_b32 v64, v18
	ds_write_b32 v64, v17 offset:2080
	ds_write_b32 v64, v20 offset:4160
	ds_write_b32 v64, v19 offset:6240
	ds_write_b32 v64, v22 offset:8320
	ds_write_b32 v64, v21 offset:10400
	ds_write_b32 v64, v24 offset:12480
	ds_write_b32 v64, v23 offset:14560
	ds_write_b32 v64, v26 offset:16640
	ds_write_b32 v64, v25 offset:18720
	ds_write_b32 v64, v28 offset:20800
	ds_write_b32 v64, v27 offset:22880
	ds_write_b32 v64, v30 offset:24960
	ds_write_b32 v64, v29 offset:27040
	ds_write_b32 v64, v32 offset:29120
	ds_write_b32 v64, v31 offset:31200
	s_waitcnt lgkmcnt(0)
	s_barrier
	s_cbranch_scc1 .LBB0_175
	s_mul_hi_i32 s0, s0, 0x2e8ba2e9
	s_lshr_b32 s1, s0, 31
	s_ashr_i32 s0, s0, 4
	s_add_i32 s0, s0, s1
	s_mul_i32 s4, s33, 6
	s_mul_i32 s1, s0, 0x3ffff50
	s_add_i32 s4, s4, s23
	s_add_i32 s4, s4, s1
	s_and_b32 s1, s4, 0x3fffffc
	s_or_b32 s1, s1, s21
	s_lshl_b32 s1, s1, 6
	s_ashr_i32 s4, s1, 1
	s_and_b32 s4, s4, 0xffffff80
	s_and_b32 s1, s1, 64
	s_or_b32 s1, s1, s4
	v_or_b32_e32 v52, s1, v54
	v_min_i32_e32 v18, 0x15ff, v52
	v_lshl_add_u32 v17, s0, 7, v55
	v_ashrrev_i32_e32 v19, 31, v18
	v_lshl_add_u64 v[94:95], v[18:19], 2, s[56:57]
	v_med3_i32 v18, v17, 0, v65
	v_add_u32_e32 v68, 8, v17
	v_add_u32_e32 v69, 16, v17
	v_add_u32_e32 v70, 24, v17
	v_add_u32_e32 v71, 32, v17
	v_add_u32_e32 v72, 40, v17
	v_add_u32_e32 v73, 48, v17
	v_add_u32_e32 v67, 56, v17
	v_mad_u64_u32 v[36:37], s[0:1], v18, s25, v[94:95]
	v_med3_i32 v20, v68, 0, v65
	v_med3_i32 v22, v69, 0, v65
	v_med3_i32 v24, v70, 0, v65
	v_med3_i32 v26, v71, 0, v65
	v_med3_i32 v28, v72, 0, v65
	v_med3_i32 v30, v73, 0, v65
	v_med3_i32 v32, v67, 0, v65
	v_add_u32_e32 v74, 64, v17
	v_mad_u64_u32 v[38:39], s[0:1], v20, s25, v[94:95]
	v_mad_u64_u32 v[40:41], s[0:1], v22, s25, v[94:95]
	v_mad_u64_u32 v[42:43], s[0:1], v24, s25, v[94:95]
	v_mad_u64_u32 v[44:45], s[0:1], v26, s25, v[94:95]
	v_mad_u64_u32 v[46:47], s[0:1], v28, s25, v[94:95]
	v_mad_u64_u32 v[48:49], s[0:1], v30, s25, v[94:95]
	v_mad_u64_u32 v[50:51], s[0:1], v32, s25, v[94:95]
	global_load_dword v93, v[36:37], off nt
	global_load_dword v91, v[38:39], off nt
	global_load_dword v89, v[40:41], off nt
	global_load_dword v87, v[42:43], off nt
	global_load_dword v85, v[44:45], off nt
	global_load_dword v83, v[46:47], off nt
	global_load_dword v82, v[48:49], off nt
	global_load_dword v81, v[50:51], off nt
	v_med3_i32 v36, v74, 0, v65
	v_add_u32_e32 v75, 0x48, v17
	v_add_u32_e32 v76, 0x50, v17
	v_add_u32_e32 v77, 0x58, v17
	v_add_u32_e32 v78, 0x60, v17
	v_add_u32_e32 v79, 0x68, v17
	v_add_u32_e32 v53, 0x70, v17
	v_add_u32_e32 v66, 0x78, v17
	v_mad_u64_u32 v[96:97], s[0:1], v36, s25, v[94:95]
	v_med3_i32 v38, v75, 0, v65
	v_med3_i32 v40, v76, 0, v65
	v_med3_i32 v42, v77, 0, v65
	v_med3_i32 v44, v78, 0, v65
	v_med3_i32 v46, v79, 0, v65
	v_med3_i32 v48, v53, 0, v65
	v_med3_i32 v50, v66, 0, v65
	v_mad_u64_u32 v[98:99], s[0:1], v38, s25, v[94:95]
	v_mad_u64_u32 v[100:101], s[0:1], v40, s25, v[94:95]
	v_mad_u64_u32 v[102:103], s[0:1], v42, s25, v[94:95]
	v_mad_u64_u32 v[104:105], s[0:1], v44, s25, v[94:95]
	v_mad_u64_u32 v[106:107], s[0:1], v46, s25, v[94:95]
	v_mad_u64_u32 v[108:109], s[0:1], v48, s25, v[94:95]
	v_mad_u64_u32 v[110:111], s[0:1], v50, s25, v[94:95]
	global_load_dword v95, v[96:97], off nt
	global_load_dword v94, v[98:99], off nt
	global_load_dword v92, v[100:101], off nt
	global_load_dword v90, v[102:103], off nt
	global_load_dword v88, v[104:105], off nt
	global_load_dword v86, v[106:107], off nt
	global_load_dword v84, v[108:109], off nt
	global_load_dword v80, v[110:111], off nt
	v_readlane_b32 s0, v240, 48
	v_readlane_b32 s1, v240, 49
	s_and_b64 vcc, exec, s[0:1]
	s_cbranch_vccz .LBB0_173
	v_mov_b32_e32 v23, 1.0
	v_mov_b32_e32 v24, 1.0
	v_mov_b32_e32 v25, 1.0
	v_mov_b32_e32 v26, 1.0
	v_mov_b32_e32 v27, 1.0
	v_mov_b32_e32 v29, 1.0
	v_mov_b32_e32 v30, 1.0
	v_mov_b32_e32 v32, 1.0
	v_mov_b32_e32 v28, 1.0
	v_mov_b32_e32 v21, 1.0
	v_mov_b32_e32 v31, 1.0
	v_mov_b32_e32 v22, 1.0
	v_mov_b32_e32 v19, 1.0
	v_mov_b32_e32 v20, 1.0
	v_mov_b32_e32 v33, 1.0
	v_mov_b32_e32 v18, 1.0
	s_branch .LBB0_174

; DEVI unsigned pk_bf16(float lo, float hi) { unsigned r; asm("v_cvt_pk_bf16_f32 %0, %1, %2" : "=v"(r) : "v"(lo), "v"(hi)); return r; }
; DEVI void cvt_job(LAS float* tile, const float* src, int srcK, int srcN, bf16_t* dst, int dstLd, int dstRows, int dstCol0, int mode, const float* gk = nullptr) {
;     ...
;         for (int i = 0; i < 16; ++i) { const int k = kap0 + ty + 8 * i - dstCol0; regs[i] = (nok && k >= 0 && k < srcK) ? raw[i] * gs[i] : 0.f; }
;     };
;     auto emit = [&](int t, float (&regs)[16]) {
; #pragma unroll
;         for (int i = 0; i < 16; ++i) tile[(ty + 8 * i) * 65 + tx] = regs[i];
;         __syncthreads();
;         int rho0, kap0, n0; coords(t, rho0, kap0, n0);
;         const int tn = t + 2 * gridDim.x;
;         if (tn < ntot) gl(tn, regs);
; #pragma unroll
;         for (int i = 0; i < 8; ++i) { const int row = ty + 8 * i;
;             const float lo = tile[(2 * tx) * 65 + row], hi = tile[(2 * tx + 1) * 65 + row];
;             *(unsigned*)(dst + (size_t)(rho0 + row) * dstLd + kap0 + 2 * tx) = pk_bf16(lo, hi); }
.LBB0_224:
	ds_read2_b32 v[142:143], v35 offset0:65 offset1:73
	ds_read2_b32 v[144:145], v35 offset1:8
	s_ashr_i32 s0, s29, 31
	s_lshr_b32 s0, s0, 27
	s_add_i32 s29, s29, s0
	s_ashr_i32 s4, s29, 5
	s_lshl_b32 s0, s4, 7
	s_waitcnt lgkmcnt(0)
	v_cvt_pk_bf16_f32 v142, v144, v142
	v_add_u32_e32 v144, s23, v37
	s_lshl_b32 s4, s4, 11
	v_subrev_u32_e32 v150, s4, v144
	v_readlane_b32 s4, v238, 59
	v_readlane_b32 s5, v238, 60
	s_ashr_i32 s1, s0, 31
	s_lshl_b64 s[0:1], s[0:1], 1
	v_mov_b64_e32 v[146:147], s[4:5]
	v_mad_i64_i32 v[148:149], s[4:5], v150, s27, v[146:147]
	v_lshl_add_u64 v[148:149], v[148:149], 0, s[0:1]
	v_lshl_add_u64 v[148:149], v[148:149], 0, v[32:33]
	global_store_dword v[148:149], v142, off
	v_cvt_pk_bf16_f32 v151, v145, v143
	ds_read2_b32 v[142:143], v35 offset0:16 offset1:24
	ds_read2_b32 v[144:145], v35 offset0:81 offset1:89
	v_add_u32_e32 v148, 8, v150
	v_mad_i64_i32 v[148:149], s[4:5], v148, s27, v[146:147]
	v_lshl_add_u64 v[148:149], v[148:149], 0, s[0:1]
	v_lshl_add_u64 v[148:149], v[148:149], 0, v[32:33]
	s_waitcnt lgkmcnt(0)
	v_cvt_pk_bf16_f32 v142, v142, v144
	v_add_u32_e32 v144, 16, v150
	global_store_dword v[148:149], v151, off
	v_mad_i64_i32 v[148:149], s[4:5], v144, s27, v[146:147]
	v_lshl_add_u64 v[148:149], v[148:149], 0, s[0:1]
	v_lshl_add_u64 v[148:149], v[148:149], 0, v[32:33]
	global_store_dword v[148:149], v142, off
	v_cvt_pk_bf16_f32 v151, v143, v145
	ds_read2_b32 v[142:143], v35 offset0:32 offset1:40
	ds_read2_b32 v[144:145], v35 offset0:97 offset1:105
	v_add_u32_e32 v148, 24, v150
	v_mad_i64_i32 v[148:149], s[4:5], v148, s27, v[146:147]
	v_lshl_add_u64 v[148:149], v[148:149], 0, s[0:1]
	v_lshl_add_u64 v[148:149], v[148:149], 0, v[32:33]
	s_waitcnt lgkmcnt(0)
	v_cvt_pk_bf16_f32 v142, v142, v144
	v_add_u32_e32 v144, 32, v150
	global_store_dword v[148:149], v151, off
	v_mad_i64_i32 v[148:149], s[4:5], v144, s27, v[146:147]
	v_lshl_add_u64 v[148:149], v[148:149], 0, s[0:1]
	v_lshl_add_u64 v[148:149], v[148:149], 0, v[32:33]
	global_store_dword v[148:149], v142, off
	v_cvt_pk_bf16_f32 v151, v143, v145
	ds_read2_b32 v[142:143], v35 offset0:48 offset1:56
	ds_read2_b32 v[144:145], v35 offset0:113 offset1:121
	v_add_u32_e32 v148, 40, v150
	v_mad_i64_i32 v[148:149], s[4:5], v148, s27, v[146:147]
	v_lshl_add_u64 v[148:149], v[148:149], 0, s[0:1]
	v_lshl_add_u64 v[148:149], v[148:149], 0, v[32:33]
	s_waitcnt lgkmcnt(0)
	v_cvt_pk_bf16_f32 v142, v142, v144
	v_add_u32_e32 v144, 48, v150
	global_store_dword v[148:149], v151, off
	v_mad_i64_i32 v[148:149], s[4:5], v144, s27, v[146:147]
	v_lshl_add_u64 v[148:149], v[148:149], 0, s[0:1]
	v_lshl_add_u64 v[148:149], v[148:149], 0, v[32:33]
	global_store_dword v[148:149], v142, off
	v_add_u32_e32 v142, 56, v150
	v_cvt_pk_bf16_f32 v144, v143, v145
	v_mad_i64_i32 v[142:143], s[4:5], v142, s27, v[146:147]
	v_lshl_add_u64 v[142:143], v[142:143], 0, s[0:1]
	v_lshl_add_u64 v[142:143], v[142:143], 0, v[32:33]
	global_store_dword v[142:143], v144, off
	v_cmp_gt_u32_e64 s[0:1], s26, v45
	s_and_b64 s[0:1], s[0:1], vcc
	v_cmp_gt_u32_e64 s[4:5], s26, v52
	v_cmp_gt_u32_e64 s[6:7], s26, v43
	v_cmp_gt_u32_e64 s[20:21], s26, v22
	v_cmp_gt_u32_e64 s[8:9], s26, v60
	v_cmp_gt_u32_e64 s[10:11], s26, v61
	v_cmp_gt_u32_e64 s[12:13], s26, v62
	v_cmp_gt_u32_e64 s[14:15], s26, v63
	v_cmp_gt_u32_e64 s[16:17], s26, v64
	v_cmp_gt_u32_e64 s[18:19], s26, v65
	s_waitcnt vmcnt(23)
	v_cndmask_b32_e64 v16, 0, v53, s[0:1]
	v_cmp_gt_u32_e64 s[0:1], s26, v46
	s_and_b64 s[0:1], s[0:1], vcc
	s_waitcnt vmcnt(22)
	v_cndmask_b32_e64 v17, 0, v54, s[0:1]
	v_cmp_gt_u32_e64 s[0:1], s26, v47
	s_and_b64 s[0:1], s[0:1], vcc
	s_waitcnt vmcnt(21)
	v_cndmask_b32_e64 v18, 0, v55, s[0:1]
	v_cmp_gt_u32_e64 s[0:1], s26, v48
	s_and_b64 s[0:1], s[0:1], vcc
	s_waitcnt vmcnt(20)
	v_cndmask_b32_e64 v19, 0, v56, s[0:1]
	v_cmp_gt_u32_e64 s[0:1], s26, v49
	s_and_b64 s[0:1], s[0:1], vcc
	s_waitcnt vmcnt(19)
	v_cndmask_b32_e64 v20, 0, v57, s[0:1]
	v_cmp_gt_u32_e64 s[0:1], s26, v50
	s_and_b64 s[0:1], s[0:1], vcc
	s_waitcnt vmcnt(18)
	v_cndmask_b32_e64 v21, 0, v58, s[0:1]
	v_cmp_gt_u32_e64 s[0:1], s26, v51
	s_and_b64 s[0:1], s[0:1], vcc
	s_waitcnt vmcnt(17)
	v_cndmask_b32_e64 v22, 0, v59, s[0:1]
	s_and_b64 s[0:1], s[4:5], vcc
	s_waitcnt vmcnt(16)
	v_cndmask_b32_e64 v23, 0, v42, s[0:1]
	s_and_b64 s[0:1], s[6:7], vcc
	s_waitcnt vmcnt(15)
	v_cndmask_b32_e64 v24, 0, v66, s[0:1]
	s_and_b64 s[0:1], s[8:9], vcc
	s_waitcnt vmcnt(14)
	v_cndmask_b32_e64 v25, 0, v67, s[0:1]
	s_and_b64 s[0:1], s[10:11], vcc
	s_waitcnt vmcnt(12)
	v_cndmask_b32_e64 v26, 0, v30, s[0:1]
	s_and_b64 s[0:1], s[12:13], vcc
	s_waitcnt vmcnt(11)
	v_cndmask_b32_e64 v27, 0, v31, s[0:1]
	s_and_b64 s[0:1], s[14:15], vcc
	v_cndmask_b32_e64 v28, 0, v68, s[0:1]
	s_and_b64 s[0:1], s[16:17], vcc
	s_waitcnt vmcnt(10)
	v_cndmask_b32_e64 v29, 0, v29, s[0:1]
	s_and_b64 s[0:1], s[18:19], vcc
	s_and_b64 vcc, s[20:21], vcc
	s_waitcnt vmcnt(9)
	v_cndmask_b32_e64 v30, 0, v69, s[0:1]
	s_waitcnt vmcnt(8)
	v_cndmask_b32_e32 v31, 0, v70, vcc
	s_waitcnt vmcnt(63) expcnt(7) lgkmcnt(15)
	s_barrier

; DEVI unsigned pk_bf16(float lo, float hi) { unsigned r; asm("v_cvt_pk_bf16_f32 %0, %1, %2" : "=v"(r) : "v"(lo), "v"(hi)); return r; }
; DEVI void cvt_job(LAS float* tile, const float* src, int srcK, int srcN, bf16_t* dst, int dstLd, int dstRows, int dstCol0, int mode, const float* gk = nullptr) {
;     ...
;         for (int i = 0; i < 16; ++i) { const int k = kap0 + ty + 8 * i - dstCol0; regs[i] = (nok && k >= 0 && k < srcK) ? raw[i] * gs[i] : 0.f; }
;     };
;     auto emit = [&](int t, float (&regs)[16]) {
; #pragma unroll
;         for (int i = 0; i < 16; ++i) tile[(ty + 8 * i) * 65 + tx] = regs[i];
;         __syncthreads();
;         int rho0, kap0, n0; coords(t, rho0, kap0, n0);
;         const int tn = t + 2 * gridDim.x;
;         if (tn < ntot) gl(tn, regs);
; #pragma unroll
;         for (int i = 0; i < 8; ++i) { const int row = ty + 8 * i;
;             const float lo = tile[(2 * tx) * 65 + row], hi = tile[(2 * tx + 1) * 65 + row];
;             *(unsigned*)(dst + (size_t)(rho0 + row) * dstLd + kap0 + 2 * tx) = pk_bf16(lo, hi); }
.LBB0_228:
	ds_read2_b32 v[142:143], v35 offset0:65 offset1:73
	ds_read2_b32 v[144:145], v35 offset1:8
	s_ashr_i32 s0, s22, 31
	s_lshr_b32 s0, s0, 27
	s_add_i32 s0, s22, s0
	s_ashr_i32 s4, s0, 5
	s_lshl_b32 s0, s4, 7
	s_waitcnt lgkmcnt(0)
	v_cvt_pk_bf16_f32 v142, v144, v142
	v_add_u32_e32 v144, s23, v38
	s_lshl_b32 s4, s4, 11
	v_subrev_u32_e32 v150, s4, v144
	v_readlane_b32 s4, v238, 59
	v_readlane_b32 s5, v238, 60
	s_ashr_i32 s1, s0, 31
	s_lshl_b64 s[0:1], s[0:1], 1
	v_mov_b64_e32 v[146:147], s[4:5]
	v_mad_i64_i32 v[148:149], s[4:5], v150, s27, v[146:147]
	v_lshl_add_u64 v[148:149], v[148:149], 0, s[0:1]
	v_lshl_add_u64 v[148:149], v[148:149], 0, v[32:33]
	global_store_dword v[148:149], v142, off
	v_cvt_pk_bf16_f32 v151, v145, v143
	ds_read2_b32 v[142:143], v35 offset0:16 offset1:24
	ds_read2_b32 v[144:145], v35 offset0:81 offset1:89
	v_add_u32_e32 v148, 8, v150
	v_mad_i64_i32 v[148:149], s[4:5], v148, s27, v[146:147]
	v_lshl_add_u64 v[148:149], v[148:149], 0, s[0:1]
	v_lshl_add_u64 v[148:149], v[148:149], 0, v[32:33]
	s_waitcnt lgkmcnt(0)
	v_cvt_pk_bf16_f32 v142, v142, v144
	v_add_u32_e32 v144, 16, v150
	global_store_dword v[148:149], v151, off
	v_mad_i64_i32 v[148:149], s[4:5], v144, s27, v[146:147]
	v_lshl_add_u64 v[148:149], v[148:149], 0, s[0:1]
	v_lshl_add_u64 v[148:149], v[148:149], 0, v[32:33]
	global_store_dword v[148:149], v142, off
	v_cvt_pk_bf16_f32 v151, v143, v145
	ds_read2_b32 v[142:143], v35 offset0:32 offset1:40
	ds_read2_b32 v[144:145], v35 offset0:97 offset1:105
	v_add_u32_e32 v148, 24, v150
	v_mad_i64_i32 v[148:149], s[4:5], v148, s27, v[146:147]
	v_lshl_add_u64 v[148:149], v[148:149], 0, s[0:1]
	v_lshl_add_u64 v[148:149], v[148:149], 0, v[32:33]
	s_waitcnt lgkmcnt(0)
	v_cvt_pk_bf16_f32 v142, v142, v144
	v_add_u32_e32 v144, 32, v150
	global_store_dword v[148:149], v151, off
	v_mad_i64_i32 v[148:149], s[4:5], v144, s27, v[146:147]
	v_lshl_add_u64 v[148:149], v[148:149], 0, s[0:1]
	v_lshl_add_u64 v[148:149], v[148:149], 0, v[32:33]
	global_store_dword v[148:149], v142, off
	v_cvt_pk_bf16_f32 v151, v143, v145
	ds_read2_b32 v[142:143], v35 offset0:48 offset1:56
	ds_read2_b32 v[144:145], v35 offset0:113 offset1:121
	v_add_u32_e32 v148, 40, v150
	v_mad_i64_i32 v[148:149], s[4:5], v148, s27, v[146:147]
	v_lshl_add_u64 v[148:149], v[148:149], 0, s[0:1]
	v_lshl_add_u64 v[148:149], v[148:149], 0, v[32:33]
	s_waitcnt lgkmcnt(0)
	v_cvt_pk_bf16_f32 v142, v142, v144
	v_add_u32_e32 v144, 48, v150
	global_store_dword v[148:149], v151, off
	v_mad_i64_i32 v[148:149], s[4:5], v144, s27, v[146:147]
	v_lshl_add_u64 v[148:149], v[148:149], 0, s[0:1]
	v_lshl_add_u64 v[148:149], v[148:149], 0, v[32:33]
	global_store_dword v[148:149], v142, off
	v_add_u32_e32 v142, 56, v150
	v_cvt_pk_bf16_f32 v144, v143, v145
	v_mad_i64_i32 v[142:143], s[4:5], v142, s27, v[146:147]
	v_lshl_add_u64 v[142:143], v[142:143], 0, s[0:1]
	s_add_i32 s29, s33, s22
	v_lshl_add_u64 v[142:143], v[142:143], 0, v[32:33]
	s_cmpk_gt_i32 s29, 0x57f
	global_store_dword v[142:143], v144, off
	s_cselect_b32 s98, 1, 0
	s_mov_b64 s[100:101], vcc
	v_cmp_gt_u32_e64 s[0:1], s26, v45
	s_and_b64 s[0:1], s[0:1], vcc
	v_cmp_gt_u32_e64 s[4:5], s26, v52
	v_cmp_gt_u32_e64 s[6:7], s26, v43
	v_cmp_gt_u32_e64 s[20:21], s26, v6
	v_cmp_gt_u32_e64 s[8:9], s26, v60
	v_cmp_gt_u32_e64 s[10:11], s26, v61
	v_cmp_gt_u32_e64 s[12:13], s26, v62
	v_cmp_gt_u32_e64 s[14:15], s26, v63
	v_cmp_gt_u32_e64 s[16:17], s26, v64
	v_cmp_gt_u32_e64 s[18:19], s26, v65
	s_waitcnt vmcnt(23)
	v_cndmask_b32_e64 v0, 0, v53, s[0:1]
	v_cmp_gt_u32_e64 s[0:1], s26, v46
	s_and_b64 s[0:1], s[0:1], vcc
	s_waitcnt vmcnt(22)
	v_cndmask_b32_e64 v1, 0, v54, s[0:1]
	v_cmp_gt_u32_e64 s[0:1], s26, v47
	s_and_b64 s[0:1], s[0:1], vcc
	s_waitcnt vmcnt(21)
	v_cndmask_b32_e64 v2, 0, v55, s[0:1]
	v_cmp_gt_u32_e64 s[0:1], s26, v48
	s_and_b64 s[0:1], s[0:1], vcc
	s_waitcnt vmcnt(20)
	v_cndmask_b32_e64 v3, 0, v56, s[0:1]
	v_cmp_gt_u32_e64 s[0:1], s26, v49
	s_and_b64 s[0:1], s[0:1], vcc
	s_waitcnt vmcnt(19)
	v_cndmask_b32_e64 v4, 0, v57, s[0:1]
	v_cmp_gt_u32_e64 s[0:1], s26, v50
	s_and_b64 s[0:1], s[0:1], vcc
	s_waitcnt vmcnt(18)
	v_cndmask_b32_e64 v5, 0, v58, s[0:1]
	v_cmp_gt_u32_e64 s[0:1], s26, v51
	s_and_b64 s[0:1], s[0:1], vcc
	s_waitcnt vmcnt(17)
	v_cndmask_b32_e64 v6, 0, v59, s[0:1]
	s_and_b64 s[0:1], s[4:5], vcc
	s_waitcnt vmcnt(16)
	v_cndmask_b32_e64 v7, 0, v42, s[0:1]
	s_and_b64 s[0:1], s[6:7], vcc
	s_waitcnt vmcnt(15)
	v_cndmask_b32_e64 v8, 0, v66, s[0:1]
	s_and_b64 s[0:1], s[8:9], vcc
	s_waitcnt vmcnt(14)
	v_cndmask_b32_e64 v9, 0, v67, s[0:1]
	s_and_b64 s[0:1], s[10:11], vcc
	s_waitcnt vmcnt(12)
	v_cndmask_b32_e64 v10, 0, v14, s[0:1]
	s_and_b64 s[0:1], s[12:13], vcc
	s_waitcnt vmcnt(11)
	v_cndmask_b32_e64 v11, 0, v15, s[0:1]
	s_and_b64 s[0:1], s[14:15], vcc
	v_cndmask_b32_e64 v12, 0, v68, s[0:1]
	s_and_b64 s[0:1], s[16:17], vcc
	s_waitcnt vmcnt(10)
	v_cndmask_b32_e64 v13, 0, v13, s[0:1]
	s_and_b64 s[0:1], s[18:19], vcc
	s_and_b64 vcc, s[20:21], vcc
	s_waitcnt vmcnt(9)
	v_cndmask_b32_e64 v14, 0, v69, s[0:1]
	s_waitcnt vmcnt(8)
	v_cndmask_b32_e32 v15, 0, v70, vcc
	s_mov_b64 vcc, s[100:101]
	s_cmp_lg_u32 s98, 0
	s_waitcnt vmcnt(63) expcnt(7) lgkmcnt(15)
	s_barrier
; DEVI void cvt_job(LAS float* tile, const float* src, int srcK, int srcN, bf16_t* dst, int dstLd, int dstRows, int dstCol0, int mode, const float* gk = nullptr) {
;     ...
;         const int n = n0 + tx, nc = n < srcN ? n : srcN - 1;
;         const bool nok = n < srcN;
;         float raw[16], gs[16];
; #pragma unroll
;         for (int i = 0; i < 16; ++i) { const int k = kap0 + ty + 8 * i - dstCol0; const int kc = k < 0 ? 0 : (k < srcK ? k : srcK - 1);
;             raw[i] = __builtin_nontemporal_load(src + (size_t)kc * srcN + nc); }
;         if (gk) {
; #pragma unroll
;             for (int i = 0; i < 16; ++i) { const int k = kap0 + ty + 8 * i - dstCol0; const int kc = k < 0 ? 0 : (k < srcK ? k : srcK - 1); gs[i] = gk[kc]; }
;         } else {
; #pragma unroll
;             for (int i = 0; i < 16; ++i) gs[i] = 1.0f;
;         }
; #pragma unroll
;         for (int i = 0; i < 16; ++i) { const int k = kap0 + ty + 8 * i - dstCol0; regs[i] = (nok && k >= 0 && k < srcK) ? raw[i] * gs[i] : 0.f; }
;     };
;     auto emit = [&](int t, float (&regs)[16]) {
; #pragma unroll
;         for (int i = 0; i < 16; ++i) tile[(ty + 8 * i) * 65 + tx] = regs[i];
;         __syncthreads();
;         int rho0, kap0, n0; coords(t, rho0, kap0, n0);
;         const int tn = t + 2 * gridDim.x;
;         if (tn < ntot) gl(tn, regs);
	s_cbranch_scc1 .LBB0_225
	s_add_i32 s0, s31, s22
	s_cmpk_gt_i32 s0, 0x57f
	ds_write_b32 v40, v16
	ds_write_b32 v40, v17 offset:2080
	ds_write_b32 v40, v18 offset:4160
	ds_write_b32 v40, v19 offset:6240
	ds_write_b32 v40, v20 offset:8320
	ds_write_b32 v40, v21 offset:10400
	ds_write_b32 v40, v22 offset:12480
	ds_write_b32 v40, v23 offset:14560
	ds_write_b32 v40, v24 offset:16640
	ds_write_b32 v40, v25 offset:18720
	ds_write_b32 v40, v26 offset:20800
	ds_write_b32 v40, v27 offset:22880
	ds_write_b32 v40, v28 offset:24960
	ds_write_b32 v40, v29 offset:27040
	ds_write_b32 v40, v30 offset:29120
	ds_write_b32 v40, v31 offset:31200
	s_waitcnt lgkmcnt(0)
	s_barrier
	s_cbranch_scc1 .LBB0_224
	s_ashr_i32 s1, s0, 31
	s_lshr_b32 s1, s1, 27
	s_add_i32 s0, s0, s1
	s_ashr_i32 s0, s0, 5
	v_add_u32_e32 v16, s23, v36
	s_lshl_b32 s1, s0, 11
	v_subrev_u32_e32 v44, s1, v16
	v_lshl_add_u32 v45, s0, 7, v34
	v_min_i32_e32 v16, 0x7ff, v44
	v_add_u32_e32 v52, 56, v45
	v_ashrrev_i32_e32 v17, 31, v16
	v_med3_i32 v18, v45, 0, v41
	v_add_u32_e32 v46, 8, v45
	v_add_u32_e32 v47, 16, v45
	v_add_u32_e32 v48, 24, v45
	v_add_u32_e32 v49, 32, v45
	v_add_u32_e32 v50, 40, v45
	v_add_u32_e32 v51, 48, v45
	v_med3_i32 v42, v52, 0, v41
	v_lshl_add_u64 v[16:17], v[16:17], 2, s[58:59]
	v_lshlrev_b32_e32 v18, 13, v18
	v_mov_b32_e32 v19, v33
	v_med3_i32 v20, v46, 0, v41
	v_med3_i32 v22, v47, 0, v41
	v_med3_i32 v24, v48, 0, v41
	v_med3_i32 v26, v49, 0, v41
	v_med3_i32 v28, v50, 0, v41
	v_med3_i32 v30, v51, 0, v41
	v_lshlrev_b32_e32 v42, 13, v42
	v_mov_b32_e32 v43, v33
	v_lshl_add_u64 v[18:19], v[16:17], 0, v[18:19]
	v_lshlrev_b32_e32 v20, 13, v20
	v_mov_b32_e32 v21, v33
	v_lshlrev_b32_e32 v22, 13, v22
	v_mov_b32_e32 v23, v33
	v_lshlrev_b32_e32 v24, 13, v24
	v_mov_b32_e32 v25, v33
	v_lshlrev_b32_e32 v26, 13, v26
	v_mov_b32_e32 v27, v33
	v_lshlrev_b32_e32 v28, 13, v28
	v_mov_b32_e32 v29, v33
	v_lshlrev_b32_e32 v30, 13, v30
	v_mov_b32_e32 v31, v33
	v_lshl_add_u64 v[42:43], v[16:17], 0, v[42:43]
	v_lshl_add_u64 v[20:21], v[16:17], 0, v[20:21]
	v_lshl_add_u64 v[22:23], v[16:17], 0, v[22:23]
	v_lshl_add_u64 v[24:25], v[16:17], 0, v[24:25]
	v_lshl_add_u64 v[26:27], v[16:17], 0, v[26:27]
	v_lshl_add_u64 v[28:29], v[16:17], 0, v[28:29]
	v_lshl_add_u64 v[30:31], v[16:17], 0, v[30:31]
	global_load_dword v53, v[18:19], off nt
	global_load_dword v54, v[20:21], off nt
	global_load_dword v55, v[22:23], off nt
	global_load_dword v56, v[24:25], off nt
	global_load_dword v57, v[26:27], off nt
	global_load_dword v58, v[28:29], off nt
	global_load_dword v59, v[30:31], off nt
	s_nop 0
	global_load_dword v42, v[42:43], off nt
	v_add_u32_e32 v43, 64, v45
	v_med3_i32 v18, v43, 0, v41
	v_add_u32_e32 v60, 0x48, v45
	v_add_u32_e32 v63, 0x60, v45
	v_lshlrev_b32_e32 v18, 13, v18
	v_mov_b32_e32 v19, v33
	v_med3_i32 v20, v60, 0, v41
	v_add_u32_e32 v61, 0x50, v45
	v_add_u32_e32 v62, 0x58, v45
	v_med3_i32 v26, v63, 0, v41
	v_add_u32_e32 v64, 0x68, v45
	v_add_u32_e32 v65, 0x70, v45
	v_lshl_add_u64 v[18:19], v[16:17], 0, v[18:19]
	v_lshlrev_b32_e32 v20, 13, v20
	v_mov_b32_e32 v21, v33
	v_med3_i32 v22, v61, 0, v41
	v_med3_i32 v24, v62, 0, v41
	v_lshlrev_b32_e32 v26, 13, v26
	v_mov_b32_e32 v27, v33
	v_med3_i32 v28, v64, 0, v41
	v_med3_i32 v30, v65, 0, v41
	v_lshl_add_u64 v[20:21], v[16:17], 0, v[20:21]
	v_lshlrev_b32_e32 v22, 13, v22
	v_mov_b32_e32 v23, v33
	v_lshlrev_b32_e32 v24, 13, v24
	v_mov_b32_e32 v25, v33
	v_lshl_add_u64 v[26:27], v[16:17], 0, v[26:27]
	v_lshlrev_b32_e32 v28, 13, v28
	v_mov_b32_e32 v29, v33
	v_lshlrev_b32_e32 v30, 13, v30
	global_load_dword v66, v[18:19], off nt
	global_load_dword v67, v[20:21], off nt
	global_load_dword v68, v[26:27], off nt
	v_mov_b32_e32 v31, v33
	v_lshl_add_u64 v[22:23], v[16:17], 0, v[22:23]
	v_lshl_add_u64 v[24:25], v[16:17], 0, v[24:25]
	v_lshl_add_u64 v[28:29], v[16:17], 0, v[28:29]
	v_lshl_add_u64 v[18:19], v[16:17], 0, v[30:31]
	global_load_dword v30, v[22:23], off nt
	global_load_dword v31, v[24:25], off nt
	v_mov_b32_e32 v21, v33
	global_load_dword v29, v[28:29], off nt
	v_cmp_gt_i32_e32 vcc, s25, v44
	global_load_dword v69, v[18:19], off nt
	v_add_u32_e32 v22, 0x78, v45
	v_med3_i32 v20, v22, 0, v41
	v_lshlrev_b32_e32 v20, 13, v20
	v_lshl_add_u64 v[16:17], v[16:17], 0, v[20:21]
	global_load_dword v70, v[16:17], off nt
	s_branch .LBB0_224

; DEVI unsigned pk_bf16(float lo, float hi) { unsigned r; asm("v_cvt_pk_bf16_f32 %0, %1, %2" : "=v"(r) : "v"(lo), "v"(hi)); return r; }
; DEVI void cvt_job(LAS float* tile, const float* src, int srcK, int srcN, bf16_t* dst, int dstLd, int dstRows, int dstCol0, int mode, const float* gk = nullptr) {
;     ...
;         for (int i = 0; i < 16; ++i) { const int k = kap0 + ty + 8 * i - dstCol0; regs[i] = (nok && k >= 0 && k < srcK) ? raw[i] * gs[i] : 0.f; }
;     };
;     auto emit = [&](int t, float (&regs)[16]) {
; #pragma unroll
;         for (int i = 0; i < 16; ++i) tile[(ty + 8 * i) * 65 + tx] = regs[i];
;         __syncthreads();
;         int rho0, kap0, n0; coords(t, rho0, kap0, n0);
;         const int tn = t + 2 * gridDim.x;
;         if (tn < ntot) gl(tn, regs);
; #pragma unroll
;         for (int i = 0; i < 8; ++i) { const int row = ty + 8 * i;
;             const float lo = tile[(2 * tx) * 65 + row], hi = tile[(2 * tx + 1) * 65 + row];
;             *(unsigned*)(dst + (size_t)(rho0 + row) * dstLd + kap0 + 2 * tx) = pk_bf16(lo, hi); }
.LBB0_336:
.LBB0_337:
	s_mul_hi_i32 s4, s8, 0x2e8ba2e9
	s_lshr_b32 s8, s4, 31
	s_ashr_i32 s4, s4, 4
	s_add_i32 s8, s4, s8
	s_mul_i32 s4, s8, 0x3ffff50
	s_add_i32 s9, s30, s7
	s_add_i32 s9, s9, s4
	s_and_b32 s4, s9, 0x3fffffc
	s_or_b32 s4, s4, s5
	s_lshl_b32 s4, s4, 6
	ds_read2_b32 v[134:135], v52 offset0:65 offset1:73
	ds_read2_b32 v[136:137], v52 offset1:8
	v_add_u32_e32 v138, s4, v51
	s_lshl_b32 s8, s8, 7
	v_ashrrev_i32_e32 v139, 31, v138
	s_ashr_i32 s9, s8, 31
	v_lshlrev_b64 v[138:139], 12, v[138:139]
	v_lshl_add_u64 v[138:139], s[62:63], 0, v[138:139]
	s_lshl_b64 s[8:9], s[8:9], 1
	v_lshl_add_u64 v[138:139], v[138:139], 0, s[8:9]
	s_waitcnt lgkmcnt(0)
	v_cvt_pk_bf16_f32 v134, v136, v134
	v_lshl_add_u64 v[138:139], v[138:139], 0, v[32:33]
	global_store_dword v[138:139], v134, off
	v_add_u32_e32 v134, s4, v53
	v_cvt_pk_bf16_f32 v136, v137, v135
	v_ashrrev_i32_e32 v135, 31, v134
	v_lshlrev_b64 v[134:135], 12, v[134:135]
	v_lshl_add_u64 v[134:135], s[62:63], 0, v[134:135]
	v_lshl_add_u64 v[134:135], v[134:135], 0, s[8:9]
	v_lshl_add_u64 v[134:135], v[134:135], 0, v[32:33]
	global_store_dword v[134:135], v136, off
	ds_read2_b32 v[134:135], v52 offset0:16 offset1:24
	ds_read2_b32 v[136:137], v52 offset0:81 offset1:89
	v_add_u32_e32 v138, s4, v54
	v_ashrrev_i32_e32 v139, 31, v138
	v_lshlrev_b64 v[138:139], 12, v[138:139]
	v_lshl_add_u64 v[138:139], s[62:63], 0, v[138:139]
	v_lshl_add_u64 v[138:139], v[138:139], 0, s[8:9]
	s_waitcnt lgkmcnt(0)
	v_cvt_pk_bf16_f32 v134, v134, v136
	v_lshl_add_u64 v[138:139], v[138:139], 0, v[32:33]
	global_store_dword v[138:139], v134, off
	v_add_u32_e32 v134, s4, v55
	v_cvt_pk_bf16_f32 v136, v135, v137
	v_ashrrev_i32_e32 v135, 31, v134
	v_lshlrev_b64 v[134:135], 12, v[134:135]
	v_lshl_add_u64 v[134:135], s[62:63], 0, v[134:135]
	v_lshl_add_u64 v[134:135], v[134:135], 0, s[8:9]
	v_lshl_add_u64 v[134:135], v[134:135], 0, v[32:33]
	global_store_dword v[134:135], v136, off
	ds_read2_b32 v[134:135], v52 offset0:32 offset1:40
	ds_read2_b32 v[136:137], v52 offset0:97 offset1:105
	v_add_u32_e32 v138, s4, v56
	v_ashrrev_i32_e32 v139, 31, v138
	v_lshlrev_b64 v[138:139], 12, v[138:139]
	v_lshl_add_u64 v[138:139], s[62:63], 0, v[138:139]
	v_lshl_add_u64 v[138:139], v[138:139], 0, s[8:9]
	s_waitcnt lgkmcnt(0)
	v_cvt_pk_bf16_f32 v134, v134, v136
	v_lshl_add_u64 v[138:139], v[138:139], 0, v[32:33]
	global_store_dword v[138:139], v134, off
	v_add_u32_e32 v134, s4, v57
	v_cvt_pk_bf16_f32 v136, v135, v137
	v_ashrrev_i32_e32 v135, 31, v134
	v_lshlrev_b64 v[134:135], 12, v[134:135]
	v_lshl_add_u64 v[134:135], s[62:63], 0, v[134:135]
	v_lshl_add_u64 v[134:135], v[134:135], 0, s[8:9]
	v_lshl_add_u64 v[134:135], v[134:135], 0, v[32:33]
	global_store_dword v[134:135], v136, off
	ds_read2_b32 v[134:135], v52 offset0:48 offset1:56
	ds_read2_b32 v[136:137], v52 offset0:113 offset1:121
	v_add_u32_e32 v138, s4, v58
	v_ashrrev_i32_e32 v139, 31, v138
	v_lshlrev_b64 v[138:139], 12, v[138:139]
	v_lshl_add_u64 v[138:139], s[62:63], 0, v[138:139]
	v_lshl_add_u64 v[138:139], v[138:139], 0, s[8:9]
	s_waitcnt lgkmcnt(0)
	v_cvt_pk_bf16_f32 v134, v134, v136
	v_lshl_add_u64 v[138:139], v[138:139], 0, v[32:33]
	global_store_dword v[138:139], v134, off
	v_add_u32_e32 v134, s4, v59
	v_cvt_pk_bf16_f32 v136, v135, v137
	v_ashrrev_i32_e32 v135, 31, v134
	v_lshlrev_b64 v[134:135], 12, v[134:135]
	v_lshl_add_u64 v[134:135], s[62:63], 0, v[134:135]
	v_lshl_add_u64 v[134:135], v[134:135], 0, s[8:9]
	v_lshl_add_u64 v[134:135], v[134:135], 0, v[32:33]
	global_store_dword v[134:135], v136, off
	v_cmp_gt_i32_e32 vcc, s12, v63
	v_cmp_gt_u32_e64 s[36:37], s13, v62
	s_waitcnt vmcnt(23)
	v_mul_f32_e32 v16, v65, v16
	s_and_b64 s[36:37], s[36:37], vcc
	v_cndmask_b32_e64 v16, 0, v16, s[36:37]
	v_cmp_gt_u32_e64 s[36:37], s13, v64
	s_waitcnt vmcnt(22)
	v_mul_f32_e32 v17, v67, v17
	s_and_b64 s[36:37], s[36:37], vcc
	v_cndmask_b32_e64 v17, 0, v17, s[36:37]
	v_cmp_gt_u32_e64 s[36:37], s13, v66
	s_waitcnt vmcnt(21)
	v_mul_f32_e32 v18, v69, v18
	s_and_b64 s[36:37], s[36:37], vcc
	v_cndmask_b32_e64 v18, 0, v18, s[36:37]
	v_cmp_gt_u32_e64 s[36:37], s13, v68
	s_waitcnt vmcnt(20)
	v_mul_f32_e32 v19, v71, v19
	s_and_b64 s[36:37], s[36:37], vcc
	v_cndmask_b32_e64 v19, 0, v19, s[36:37]
	v_cmp_gt_u32_e64 s[36:37], s13, v70
	s_waitcnt vmcnt(19)
	v_mul_f32_e32 v20, v73, v20
	s_and_b64 s[36:37], s[36:37], vcc
	v_cndmask_b32_e64 v20, 0, v20, s[36:37]
	v_cmp_gt_u32_e64 s[36:37], s13, v72
	s_waitcnt vmcnt(18)
	v_mul_f32_e32 v21, v75, v21
	s_and_b64 s[36:37], s[36:37], vcc
	v_cndmask_b32_e64 v21, 0, v21, s[36:37]
	v_cmp_gt_u32_e64 s[36:37], s13, v74
	s_waitcnt vmcnt(17)
	v_mul_f32_e32 v22, v77, v22
	s_and_b64 s[36:37], s[36:37], vcc
	v_cndmask_b32_e64 v22, 0, v22, s[36:37]
	v_cmp_gt_u32_e64 s[36:37], s13, v76
	s_waitcnt vmcnt(16)
	v_mul_f32_e32 v23, v80, v23
	s_and_b64 s[36:37], s[36:37], vcc
	v_cndmask_b32_e64 v23, 0, v23, s[36:37]
	v_cmp_gt_u32_e64 s[36:37], s13, v78
	s_waitcnt vmcnt(15)
	v_mul_f32_e32 v24, v81, v24
	s_and_b64 s[36:37], s[36:37], vcc
	v_cndmask_b32_e64 v24, 0, v24, s[36:37]
	v_cmp_gt_u32_e64 s[36:37], s13, v79
	s_waitcnt vmcnt(14)
	v_mul_f32_e32 v25, v83, v25
	s_and_b64 s[36:37], s[36:37], vcc
	v_cndmask_b32_e64 v25, 0, v25, s[36:37]
	v_cmp_gt_u32_e64 s[36:37], s13, v82
	s_waitcnt vmcnt(13)
	v_mul_f32_e32 v26, v85, v26
	s_and_b64 s[36:37], s[36:37], vcc
	v_cndmask_b32_e64 v26, 0, v26, s[36:37]
	v_cmp_gt_u32_e64 s[36:37], s13, v84
	s_waitcnt vmcnt(12)
	v_mul_f32_e32 v27, v87, v27
	s_and_b64 s[36:37], s[36:37], vcc
	v_cndmask_b32_e64 v27, 0, v27, s[36:37]
	v_cmp_gt_u32_e64 s[36:37], s13, v86
	s_waitcnt vmcnt(11)
	v_mul_f32_e32 v28, v89, v28
	s_and_b64 s[36:37], s[36:37], vcc
	v_cndmask_b32_e64 v28, 0, v28, s[36:37]
	v_cmp_gt_u32_e64 s[36:37], s13, v88
	s_waitcnt vmcnt(10)
	v_mul_f32_e32 v29, v91, v29
	s_and_b64 s[36:37], s[36:37], vcc
	v_cndmask_b32_e64 v29, 0, v29, s[36:37]
	v_cmp_gt_u32_e64 s[36:37], s13, v90
	s_waitcnt vmcnt(9)
	v_mul_f32_e32 v30, v93, v30
	s_and_b64 s[36:37], s[36:37], vcc
	v_cndmask_b32_e64 v30, 0, v30, s[36:37]
	v_cmp_gt_u32_e64 s[36:37], s13, v92
	s_waitcnt vmcnt(8)
	v_mul_f32_e32 v31, v94, v31
	s_and_b64 vcc, s[36:37], vcc
	v_cndmask_b32_e32 v31, 0, v31, vcc
	s_barrier

; DEVI unsigned pk_bf16(float lo, float hi) { unsigned r; asm("v_cvt_pk_bf16_f32 %0, %1, %2" : "=v"(r) : "v"(lo), "v"(hi)); return r; }
; DEVI void cvt_job(LAS float* tile, const float* src, int srcK, int srcN, bf16_t* dst, int dstLd, int dstRows, int dstCol0, int mode, const float* gk = nullptr) {
;     ...
;         for (int i = 0; i < 16; ++i) { const int k = kap0 + ty + 8 * i - dstCol0; regs[i] = (nok && k >= 0 && k < srcK) ? raw[i] * gs[i] : 0.f; }
;     };
;     auto emit = [&](int t, float (&regs)[16]) {
; #pragma unroll
;         for (int i = 0; i < 16; ++i) tile[(ty + 8 * i) * 65 + tx] = regs[i];
;         __syncthreads();
;         int rho0, kap0, n0; coords(t, rho0, kap0, n0);
;         const int tn = t + 2 * gridDim.x;
;         if (tn < ntot) gl(tn, regs);
; #pragma unroll
;         for (int i = 0; i < 8; ++i) { const int row = ty + 8 * i;
;             const float lo = tile[(2 * tx) * 65 + row], hi = tile[(2 * tx + 1) * 65 + row];
;             *(unsigned*)(dst + (size_t)(rho0 + row) * dstLd + kap0 + 2 * tx) = pk_bf16(lo, hi); }
.LBB0_343:
.LBB0_344:
	s_mul_hi_i32 s8, s4, 0x2e8ba2e9
	s_lshr_b32 s9, s8, 31
	s_ashr_i32 s8, s8, 4
	s_add_i32 s8, s8, s9
	s_mul_i32 s9, s8, 0x3ffff50
	s_add_i32 s9, s7, s9
	s_and_b32 s9, s9, 0x3fffffc
	s_or_b32 s9, s9, s6
	s_lshl_b32 s15, s9, 6
	ds_read2_b32 v[134:135], v52 offset0:65 offset1:73
	ds_read2_b32 v[136:137], v52 offset1:8
	v_add_u32_e32 v138, s15, v51
	s_lshl_b32 s8, s8, 7
	v_ashrrev_i32_e32 v139, 31, v138
	s_ashr_i32 s9, s8, 31
	v_lshlrev_b64 v[138:139], 12, v[138:139]
	v_lshl_add_u64 v[138:139], s[62:63], 0, v[138:139]
	s_lshl_b64 s[8:9], s[8:9], 1
	v_lshl_add_u64 v[138:139], v[138:139], 0, s[8:9]
	s_waitcnt lgkmcnt(0)
	v_cvt_pk_bf16_f32 v134, v136, v134
	v_lshl_add_u64 v[138:139], v[138:139], 0, v[32:33]
	global_store_dword v[138:139], v134, off
	v_add_u32_e32 v134, s15, v53
	v_cvt_pk_bf16_f32 v136, v137, v135
	v_ashrrev_i32_e32 v135, 31, v134
	v_lshlrev_b64 v[134:135], 12, v[134:135]
	v_lshl_add_u64 v[134:135], s[62:63], 0, v[134:135]
	v_lshl_add_u64 v[134:135], v[134:135], 0, s[8:9]
	v_lshl_add_u64 v[134:135], v[134:135], 0, v[32:33]
	global_store_dword v[134:135], v136, off
	ds_read2_b32 v[134:135], v52 offset0:16 offset1:24
	ds_read2_b32 v[136:137], v52 offset0:81 offset1:89
	v_add_u32_e32 v138, s15, v54
	v_ashrrev_i32_e32 v139, 31, v138
	v_lshlrev_b64 v[138:139], 12, v[138:139]
	v_lshl_add_u64 v[138:139], s[62:63], 0, v[138:139]
	v_lshl_add_u64 v[138:139], v[138:139], 0, s[8:9]
	s_waitcnt lgkmcnt(0)
	v_cvt_pk_bf16_f32 v134, v134, v136
	v_lshl_add_u64 v[138:139], v[138:139], 0, v[32:33]
	global_store_dword v[138:139], v134, off
	v_add_u32_e32 v134, s15, v55
	v_cvt_pk_bf16_f32 v136, v135, v137
	v_ashrrev_i32_e32 v135, 31, v134
	v_lshlrev_b64 v[134:135], 12, v[134:135]
	v_lshl_add_u64 v[134:135], s[62:63], 0, v[134:135]
	v_lshl_add_u64 v[134:135], v[134:135], 0, s[8:9]
	v_lshl_add_u64 v[134:135], v[134:135], 0, v[32:33]
	global_store_dword v[134:135], v136, off
	ds_read2_b32 v[134:135], v52 offset0:32 offset1:40
	ds_read2_b32 v[136:137], v52 offset0:97 offset1:105
	v_add_u32_e32 v138, s15, v56
	v_ashrrev_i32_e32 v139, 31, v138
	v_lshlrev_b64 v[138:139], 12, v[138:139]
	v_lshl_add_u64 v[138:139], s[62:63], 0, v[138:139]
	v_lshl_add_u64 v[138:139], v[138:139], 0, s[8:9]
	s_waitcnt lgkmcnt(0)
	v_cvt_pk_bf16_f32 v134, v134, v136
	v_lshl_add_u64 v[138:139], v[138:139], 0, v[32:33]
	global_store_dword v[138:139], v134, off
	v_add_u32_e32 v134, s15, v57
	v_cvt_pk_bf16_f32 v136, v135, v137
	v_ashrrev_i32_e32 v135, 31, v134
	v_lshlrev_b64 v[134:135], 12, v[134:135]
	v_lshl_add_u64 v[134:135], s[62:63], 0, v[134:135]
	v_lshl_add_u64 v[134:135], v[134:135], 0, s[8:9]
	v_lshl_add_u64 v[134:135], v[134:135], 0, v[32:33]
	global_store_dword v[134:135], v136, off
	ds_read2_b32 v[134:135], v52 offset0:48 offset1:56
	ds_read2_b32 v[136:137], v52 offset0:113 offset1:121
	v_add_u32_e32 v138, s15, v58
	v_ashrrev_i32_e32 v139, 31, v138
	v_lshlrev_b64 v[138:139], 12, v[138:139]
	v_lshl_add_u64 v[138:139], s[62:63], 0, v[138:139]
	v_lshl_add_u64 v[138:139], v[138:139], 0, s[8:9]
	s_waitcnt lgkmcnt(0)
	v_cvt_pk_bf16_f32 v134, v134, v136
	v_lshl_add_u64 v[138:139], v[138:139], 0, v[32:33]
	global_store_dword v[138:139], v134, off
	v_add_u32_e32 v134, s15, v59
	v_cvt_pk_bf16_f32 v136, v135, v137
	v_ashrrev_i32_e32 v135, 31, v134
	v_lshlrev_b64 v[134:135], 12, v[134:135]
	v_lshl_add_u64 v[134:135], s[62:63], 0, v[134:135]
	v_lshl_add_u64 v[134:135], v[134:135], 0, s[8:9]
	s_add_i32 s8, s33, s4
	v_lshl_add_u64 v[134:135], v[134:135], 0, v[32:33]
	s_cmpk_gt_i32 s8, 0x57f
	global_store_dword v[134:135], v136, off
	s_cselect_b32 s98, 1, 0
	v_cmp_gt_i32_e32 vcc, s12, v63
	v_cmp_gt_u32_e64 s[36:37], s13, v62
	s_waitcnt vmcnt(23)
	v_mul_f32_e32 v0, v65, v0
	s_and_b64 s[36:37], s[36:37], vcc
	v_cndmask_b32_e64 v0, 0, v0, s[36:37]
	v_cmp_gt_u32_e64 s[36:37], s13, v64
	s_waitcnt vmcnt(22)
	v_mul_f32_e32 v1, v67, v1
	s_and_b64 s[36:37], s[36:37], vcc
	v_cndmask_b32_e64 v1, 0, v1, s[36:37]
	v_cmp_gt_u32_e64 s[36:37], s13, v66
	s_waitcnt vmcnt(21)
	v_mul_f32_e32 v2, v69, v2
	s_and_b64 s[36:37], s[36:37], vcc
	v_cndmask_b32_e64 v2, 0, v2, s[36:37]
	v_cmp_gt_u32_e64 s[36:37], s13, v68
	s_waitcnt vmcnt(20)
	v_mul_f32_e32 v3, v71, v3
	s_and_b64 s[36:37], s[36:37], vcc
	v_cndmask_b32_e64 v3, 0, v3, s[36:37]
	v_cmp_gt_u32_e64 s[36:37], s13, v70
	s_waitcnt vmcnt(19)
	v_mul_f32_e32 v4, v73, v4
	s_and_b64 s[36:37], s[36:37], vcc
	v_cndmask_b32_e64 v4, 0, v4, s[36:37]
	v_cmp_gt_u32_e64 s[36:37], s13, v72
	s_waitcnt vmcnt(18)
	v_mul_f32_e32 v5, v75, v5
	s_and_b64 s[36:37], s[36:37], vcc
	v_cndmask_b32_e64 v5, 0, v5, s[36:37]
	v_cmp_gt_u32_e64 s[36:37], s13, v74
	s_waitcnt vmcnt(17)
	v_mul_f32_e32 v6, v77, v6
	s_and_b64 s[36:37], s[36:37], vcc
	v_cndmask_b32_e64 v6, 0, v6, s[36:37]
	v_cmp_gt_u32_e64 s[36:37], s13, v76
	s_waitcnt vmcnt(16)
	v_mul_f32_e32 v7, v80, v7
	s_and_b64 s[36:37], s[36:37], vcc
	v_cndmask_b32_e64 v7, 0, v7, s[36:37]
	v_cmp_gt_u32_e64 s[36:37], s13, v78
	s_waitcnt vmcnt(15)
	v_mul_f32_e32 v8, v81, v8
	s_and_b64 s[36:37], s[36:37], vcc
	v_cndmask_b32_e64 v8, 0, v8, s[36:37]
	v_cmp_gt_u32_e64 s[36:37], s13, v79
	s_waitcnt vmcnt(14)
	v_mul_f32_e32 v9, v83, v9
	s_and_b64 s[36:37], s[36:37], vcc
	v_cndmask_b32_e64 v9, 0, v9, s[36:37]
	v_cmp_gt_u32_e64 s[36:37], s13, v82
	s_waitcnt vmcnt(13)
	v_mul_f32_e32 v10, v85, v10
	s_and_b64 s[36:37], s[36:37], vcc
	v_cndmask_b32_e64 v10, 0, v10, s[36:37]
	v_cmp_gt_u32_e64 s[36:37], s13, v84
	s_waitcnt vmcnt(12)
	v_mul_f32_e32 v11, v87, v11
	s_and_b64 s[36:37], s[36:37], vcc
	v_cndmask_b32_e64 v11, 0, v11, s[36:37]
	v_cmp_gt_u32_e64 s[36:37], s13, v86
	s_waitcnt vmcnt(11)
	v_mul_f32_e32 v12, v89, v12
	s_and_b64 s[36:37], s[36:37], vcc
	v_cndmask_b32_e64 v12, 0, v12, s[36:37]
	v_cmp_gt_u32_e64 s[36:37], s13, v88
	s_waitcnt vmcnt(10)
	v_mul_f32_e32 v13, v91, v13
	s_and_b64 s[36:37], s[36:37], vcc
	v_cndmask_b32_e64 v13, 0, v13, s[36:37]
	v_cmp_gt_u32_e64 s[36:37], s13, v90
	s_waitcnt vmcnt(9)
	v_mul_f32_e32 v14, v93, v14
	s_and_b64 s[36:37], s[36:37], vcc
	v_cndmask_b32_e64 v14, 0, v14, s[36:37]
	v_cmp_gt_u32_e64 s[36:37], s13, v92
	s_waitcnt vmcnt(8)
	v_mul_f32_e32 v15, v94, v15
	s_and_b64 vcc, s[36:37], vcc
	v_cndmask_b32_e32 v15, 0, v15, vcc
	s_cmp_lg_u32 s98, 0
	s_barrier
; DEVI void cvt_job(LAS float* tile, const float* src, int srcK, int srcN, bf16_t* dst, int dstLd, int dstRows, int dstCol0, int mode, const float* gk = nullptr) {
;     ...
;         const int n = n0 + tx, nc = n < srcN ? n : srcN - 1;
;         const bool nok = n < srcN;
;         float raw[16], gs[16];
; #pragma unroll
;         for (int i = 0; i < 16; ++i) { const int k = kap0 + ty + 8 * i - dstCol0; const int kc = k < 0 ? 0 : (k < srcK ? k : srcK - 1);
;             raw[i] = __builtin_nontemporal_load(src + (size_t)kc * srcN + nc); }
;         if (gk) {
; #pragma unroll
;             for (int i = 0; i < 16; ++i) { const int k = kap0 + ty + 8 * i - dstCol0; const int kc = k < 0 ? 0 : (k < srcK ? k : srcK - 1); gs[i] = gk[kc]; }
;         } else {
; #pragma unroll
;             for (int i = 0; i < 16; ++i) gs[i] = 1.0f;
;         }
; #pragma unroll
;         for (int i = 0; i < 16; ++i) { const int k = kap0 + ty + 8 * i - dstCol0; regs[i] = (nok && k >= 0 && k < srcK) ? raw[i] * gs[i] : 0.f; }
;     };
;     auto emit = [&](int t, float (&regs)[16]) {
; #pragma unroll
;         for (int i = 0; i < 16; ++i) tile[(ty + 8 * i) * 65 + tx] = regs[i];
;         __syncthreads();
;         int rho0, kap0, n0; coords(t, rho0, kap0, n0);
;         const int tn = t + 2 * gridDim.x;
;         if (tn < ntot) gl(tn, regs);
	s_cbranch_scc1 .LBB0_338
	s_add_i32 s4, s31, s4
	s_cmpk_gt_i32 s4, 0x57f
	ds_write_b32 v60, v16
	ds_write_b32 v60, v17 offset:2080
	ds_write_b32 v60, v18 offset:4160
	ds_write_b32 v60, v19 offset:6240
	ds_write_b32 v60, v20 offset:8320
	ds_write_b32 v60, v21 offset:10400
	ds_write_b32 v60, v22 offset:12480
	ds_write_b32 v60, v23 offset:14560
	ds_write_b32 v60, v24 offset:16640
	ds_write_b32 v60, v25 offset:18720
	ds_write_b32 v60, v26 offset:20800
	ds_write_b32 v60, v27 offset:22880
	ds_write_b32 v60, v28 offset:24960
	ds_write_b32 v60, v29 offset:27040
	ds_write_b32 v60, v30 offset:29120
	ds_write_b32 v60, v31 offset:31200
	s_waitcnt lgkmcnt(0)
	s_barrier
	s_cbranch_scc1 .LBB0_337
	s_mul_hi_i32 s4, s4, 0x2e8ba2e9
	s_lshr_b32 s9, s4, 31
	s_ashr_i32 s4, s4, 4
	s_add_i32 s4, s4, s9
	s_mul_i32 s9, s4, 0x3ffff50
	s_add_i32 s15, s96, s7
	s_add_i32 s15, s15, s9
	s_and_b32 s9, s15, 0x3fffffc
	s_or_b32 s9, s9, s5
	s_lshl_b32 s9, s9, 6
	s_ashr_i32 s15, s9, 1
	s_and_b32 s15, s15, 0xffffff80
	s_and_b32 s9, s9, 64
	s_or_b32 s9, s9, s15
	v_or_b32_e32 v63, s9, v50
	v_min_i32_e32 v16, 0x15ff, v63
	v_lshl_add_u32 v62, s4, 7, v51
	v_ashrrev_i32_e32 v17, 31, v16
	v_lshl_add_u64 v[94:95], v[16:17], 2, s[0:1]
	v_med3_i32 v16, v62, 0, v61
	v_mad_u64_u32 v[18:19], s[16:17], v16, s11, v[94:95]
	v_add_u32_e32 v64, 8, v62
	global_load_dword v65, v[18:19], off nt
	v_med3_i32 v18, v64, 0, v61
	v_mad_u64_u32 v[20:21], s[16:17], v18, s11, v[94:95]
	v_add_u32_e32 v66, 16, v62
	global_load_dword v67, v[20:21], off nt
	v_med3_i32 v20, v66, 0, v61
	v_mad_u64_u32 v[22:23], s[16:17], v20, s11, v[94:95]
	v_add_u32_e32 v68, 24, v62
	global_load_dword v69, v[22:23], off nt
	v_med3_i32 v22, v68, 0, v61
	v_mad_u64_u32 v[24:25], s[16:17], v22, s11, v[94:95]
	v_add_u32_e32 v70, 32, v62
	global_load_dword v71, v[24:25], off nt
	v_med3_i32 v24, v70, 0, v61
	v_mad_u64_u32 v[26:27], s[16:17], v24, s11, v[94:95]
	v_add_u32_e32 v72, 40, v62
	global_load_dword v73, v[26:27], off nt
	v_med3_i32 v26, v72, 0, v61
	v_mad_u64_u32 v[28:29], s[16:17], v26, s11, v[94:95]
	v_add_u32_e32 v74, 48, v62
	global_load_dword v75, v[28:29], off nt
	v_med3_i32 v28, v74, 0, v61
	v_mad_u64_u32 v[30:31], s[16:17], v28, s11, v[94:95]
	v_add_u32_e32 v76, 56, v62
	global_load_dword v77, v[30:31], off nt
	v_med3_i32 v30, v76, 0, v61
	v_mad_u64_u32 v[34:35], s[16:17], v30, s11, v[94:95]
	v_add_u32_e32 v78, 64, v62
	global_load_dword v80, v[34:35], off nt
	v_med3_i32 v34, v78, 0, v61
	v_mad_u64_u32 v[36:37], s[16:17], v34, s11, v[94:95]
	v_add_u32_e32 v79, 0x48, v62
	global_load_dword v81, v[36:37], off nt
	v_med3_i32 v36, v79, 0, v61
	v_mad_u64_u32 v[38:39], s[16:17], v36, s11, v[94:95]
	v_add_u32_e32 v82, 0x50, v62
	global_load_dword v83, v[38:39], off nt
	v_med3_i32 v38, v82, 0, v61
	v_mad_u64_u32 v[40:41], s[16:17], v38, s11, v[94:95]
	v_add_u32_e32 v84, 0x58, v62
	global_load_dword v85, v[40:41], off nt
	v_med3_i32 v40, v84, 0, v61
	v_mad_u64_u32 v[42:43], s[16:17], v40, s11, v[94:95]
	v_add_u32_e32 v86, 0x60, v62
	global_load_dword v87, v[42:43], off nt
	v_med3_i32 v42, v86, 0, v61
	v_mad_u64_u32 v[44:45], s[16:17], v42, s11, v[94:95]
	v_add_u32_e32 v88, 0x68, v62
	global_load_dword v89, v[44:45], off nt
	v_med3_i32 v44, v88, 0, v61
	v_mad_u64_u32 v[46:47], s[16:17], v44, s11, v[94:95]
	v_add_u32_e32 v90, 0x70, v62
	global_load_dword v91, v[46:47], off nt
	v_med3_i32 v46, v90, 0, v61
	v_mad_u64_u32 v[48:49], s[16:17], v46, s11, v[94:95]
	v_add_u32_e32 v92, 0x78, v62
	global_load_dword v93, v[48:49], off nt
	v_med3_i32 v48, v92, 0, v61
	v_mad_u64_u32 v[94:95], s[16:17], v48, s11, v[94:95]
	global_load_dword v94, v[94:95], off nt
	v_readlane_b32 s16, v240, 48
	v_readlane_b32 s17, v240, 49
	s_and_b64 vcc, exec, s[16:17]
	s_cbranch_vccz .LBB0_335
	v_mov_b32_e32 v31, 1.0
	v_mov_b32_e32 v30, 1.0
	v_mov_b32_e32 v29, 1.0
	v_mov_b32_e32 v28, 1.0
	v_mov_b32_e32 v27, 1.0
	v_mov_b32_e32 v26, 1.0
	v_mov_b32_e32 v25, 1.0
	v_mov_b32_e32 v24, 1.0
	v_mov_b32_e32 v23, 1.0
	v_mov_b32_e32 v22, 1.0
	v_mov_b32_e32 v21, 1.0
	v_mov_b32_e32 v20, 1.0
	v_mov_b32_e32 v19, 1.0
	v_mov_b32_e32 v18, 1.0
	v_mov_b32_e32 v17, 1.0
	v_mov_b32_e32 v16, 1.0
	s_branch .LBB0_336

; DEVI unsigned pk_bf16(float lo, float hi) { unsigned r; asm("v_cvt_pk_bf16_f32 %0, %1, %2" : "=v"(r) : "v"(lo), "v"(hi)); return r; }
; DEVI void cvt_job(LAS float* tile, const float* src, int srcK, int srcN, bf16_t* dst, int dstLd, int dstRows, int dstCol0, int mode, const float* gk = nullptr) {
;     ...
;         for (int i = 0; i < 16; ++i) { const int k = kap0 + ty + 8 * i - dstCol0; regs[i] = (nok && k >= 0 && k < srcK) ? raw[i] * gs[i] : 0.f; }
;     };
;     auto emit = [&](int t, float (&regs)[16]) {
; #pragma unroll
;         for (int i = 0; i < 16; ++i) tile[(ty + 8 * i) * 65 + tx] = regs[i];
;         __syncthreads();
;         int rho0, kap0, n0; coords(t, rho0, kap0, n0);
;         const int tn = t + 2 * gridDim.x;
;         if (tn < ntot) gl(tn, regs);
; #pragma unroll
;         for (int i = 0; i < 8; ++i) { const int row = ty + 8 * i;
;             const float lo = tile[(2 * tx) * 65 + row], hi = tile[(2 * tx + 1) * 65 + row];
;             *(unsigned*)(dst + (size_t)(rho0 + row) * dstLd + kap0 + 2 * tx) = pk_bf16(lo, hi); }
.LBB0_361:
.LBB0_362:
	s_mul_hi_i32 s4, s8, 0x2e8ba2e9
	s_lshr_b32 s8, s4, 31
	s_ashr_i32 s4, s4, 4
	s_add_i32 s8, s4, s8
	s_mul_i32 s4, s8, 0x3ffff50
	s_add_i32 s9, s30, s7
	s_add_i32 s9, s9, s4
	s_and_b32 s4, s9, 0x3fffffc
	s_or_b32 s4, s4, s5
	s_lshl_b32 s4, s4, 6
	s_bitset1_b32 s4, 7
	ds_read2_b32 v[134:135], v52 offset0:65 offset1:73
	ds_read2_b32 v[136:137], v52 offset1:8
	v_add_u32_e32 v138, s4, v51
	s_lshl_b32 s8, s8, 7
	v_ashrrev_i32_e32 v139, 31, v138
	s_ashr_i32 s9, s8, 31
	v_lshlrev_b64 v[138:139], 12, v[138:139]
	v_lshl_add_u64 v[138:139], s[62:63], 0, v[138:139]
	s_lshl_b64 s[8:9], s[8:9], 1
	v_lshl_add_u64 v[138:139], v[138:139], 0, s[8:9]
	s_waitcnt lgkmcnt(0)
	v_cvt_pk_bf16_f32 v134, v136, v134
	v_lshl_add_u64 v[138:139], v[138:139], 0, v[32:33]
	global_store_dword v[138:139], v134, off
	v_add_u32_e32 v134, s4, v53
	v_cvt_pk_bf16_f32 v136, v137, v135
	v_ashrrev_i32_e32 v135, 31, v134
	v_lshlrev_b64 v[134:135], 12, v[134:135]
	v_lshl_add_u64 v[134:135], s[62:63], 0, v[134:135]
	v_lshl_add_u64 v[134:135], v[134:135], 0, s[8:9]
	v_lshl_add_u64 v[134:135], v[134:135], 0, v[32:33]
	global_store_dword v[134:135], v136, off
	ds_read2_b32 v[134:135], v52 offset0:16 offset1:24
	ds_read2_b32 v[136:137], v52 offset0:81 offset1:89
	v_add_u32_e32 v138, s4, v54
	v_ashrrev_i32_e32 v139, 31, v138
	v_lshlrev_b64 v[138:139], 12, v[138:139]
	v_lshl_add_u64 v[138:139], s[62:63], 0, v[138:139]
	v_lshl_add_u64 v[138:139], v[138:139], 0, s[8:9]
	s_waitcnt lgkmcnt(0)
	v_cvt_pk_bf16_f32 v134, v134, v136
	v_lshl_add_u64 v[138:139], v[138:139], 0, v[32:33]
	global_store_dword v[138:139], v134, off
	v_add_u32_e32 v134, s4, v55
	v_cvt_pk_bf16_f32 v136, v135, v137
	v_ashrrev_i32_e32 v135, 31, v134
	v_lshlrev_b64 v[134:135], 12, v[134:135]
	v_lshl_add_u64 v[134:135], s[62:63], 0, v[134:135]
	v_lshl_add_u64 v[134:135], v[134:135], 0, s[8:9]
	v_lshl_add_u64 v[134:135], v[134:135], 0, v[32:33]
	global_store_dword v[134:135], v136, off
	ds_read2_b32 v[134:135], v52 offset0:32 offset1:40
	ds_read2_b32 v[136:137], v52 offset0:97 offset1:105
	v_add_u32_e32 v138, s4, v56
	v_ashrrev_i32_e32 v139, 31, v138
	v_lshlrev_b64 v[138:139], 12, v[138:139]
	v_lshl_add_u64 v[138:139], s[62:63], 0, v[138:139]
	v_lshl_add_u64 v[138:139], v[138:139], 0, s[8:9]
	s_waitcnt lgkmcnt(0)
	v_cvt_pk_bf16_f32 v134, v134, v136
	v_lshl_add_u64 v[138:139], v[138:139], 0, v[32:33]
	global_store_dword v[138:139], v134, off
	v_add_u32_e32 v134, s4, v57
	v_cvt_pk_bf16_f32 v136, v135, v137
	v_ashrrev_i32_e32 v135, 31, v134
	v_lshlrev_b64 v[134:135], 12, v[134:135]
	v_lshl_add_u64 v[134:135], s[62:63], 0, v[134:135]
	v_lshl_add_u64 v[134:135], v[134:135], 0, s[8:9]
	v_lshl_add_u64 v[134:135], v[134:135], 0, v[32:33]
	global_store_dword v[134:135], v136, off
	ds_read2_b32 v[134:135], v52 offset0:48 offset1:56
	ds_read2_b32 v[136:137], v52 offset0:113 offset1:121
	v_add_u32_e32 v138, s4, v58
	v_ashrrev_i32_e32 v139, 31, v138
	v_lshlrev_b64 v[138:139], 12, v[138:139]
	v_lshl_add_u64 v[138:139], s[62:63], 0, v[138:139]
	v_lshl_add_u64 v[138:139], v[138:139], 0, s[8:9]
	s_waitcnt lgkmcnt(0)
	v_cvt_pk_bf16_f32 v134, v134, v136
	v_lshl_add_u64 v[138:139], v[138:139], 0, v[32:33]
	global_store_dword v[138:139], v134, off
	v_add_u32_e32 v134, s4, v59
	v_cvt_pk_bf16_f32 v136, v135, v137
	v_ashrrev_i32_e32 v135, 31, v134
	v_lshlrev_b64 v[134:135], 12, v[134:135]
	v_lshl_add_u64 v[134:135], s[62:63], 0, v[134:135]
	v_lshl_add_u64 v[134:135], v[134:135], 0, s[8:9]
	v_lshl_add_u64 v[134:135], v[134:135], 0, v[32:33]
	global_store_dword v[134:135], v136, off
	v_cmp_gt_i32_e32 vcc, s12, v63
	v_cmp_gt_u32_e64 s[36:37], s13, v62
	s_waitcnt vmcnt(23)
	v_mul_f32_e32 v16, v65, v16
	s_and_b64 s[36:37], s[36:37], vcc
	v_cndmask_b32_e64 v16, 0, v16, s[36:37]
	v_cmp_gt_u32_e64 s[36:37], s13, v64
	s_waitcnt vmcnt(22)
	v_mul_f32_e32 v17, v67, v17
	s_and_b64 s[36:37], s[36:37], vcc
	v_cndmask_b32_e64 v17, 0, v17, s[36:37]
	v_cmp_gt_u32_e64 s[36:37], s13, v66
	s_waitcnt vmcnt(21)
	v_mul_f32_e32 v18, v69, v18
	s_and_b64 s[36:37], s[36:37], vcc
	v_cndmask_b32_e64 v18, 0, v18, s[36:37]
	v_cmp_gt_u32_e64 s[36:37], s13, v68
	s_waitcnt vmcnt(20)
	v_mul_f32_e32 v19, v71, v19
	s_and_b64 s[36:37], s[36:37], vcc
	v_cndmask_b32_e64 v19, 0, v19, s[36:37]
	v_cmp_gt_u32_e64 s[36:37], s13, v70
	s_waitcnt vmcnt(19)
	v_mul_f32_e32 v20, v73, v20
	s_and_b64 s[36:37], s[36:37], vcc
	v_cndmask_b32_e64 v20, 0, v20, s[36:37]
	v_cmp_gt_u32_e64 s[36:37], s13, v72
	s_waitcnt vmcnt(18)
	v_mul_f32_e32 v21, v75, v21
	s_and_b64 s[36:37], s[36:37], vcc
	v_cndmask_b32_e64 v21, 0, v21, s[36:37]
	v_cmp_gt_u32_e64 s[36:37], s13, v74
	s_waitcnt vmcnt(17)
	v_mul_f32_e32 v22, v77, v22
	s_and_b64 s[36:37], s[36:37], vcc
	v_cndmask_b32_e64 v22, 0, v22, s[36:37]
	v_cmp_gt_u32_e64 s[36:37], s13, v76
	s_waitcnt vmcnt(16)
	v_mul_f32_e32 v23, v80, v23
	s_and_b64 s[36:37], s[36:37], vcc
	v_cndmask_b32_e64 v23, 0, v23, s[36:37]
	v_cmp_gt_u32_e64 s[36:37], s13, v78
	s_waitcnt vmcnt(15)
	v_mul_f32_e32 v24, v81, v24
	s_and_b64 s[36:37], s[36:37], vcc
	v_cndmask_b32_e64 v24, 0, v24, s[36:37]
	v_cmp_gt_u32_e64 s[36:37], s13, v79
	s_waitcnt vmcnt(14)
	v_mul_f32_e32 v25, v83, v25
	s_and_b64 s[36:37], s[36:37], vcc
	v_cndmask_b32_e64 v25, 0, v25, s[36:37]
	v_cmp_gt_u32_e64 s[36:37], s13, v82
	s_waitcnt vmcnt(13)
	v_mul_f32_e32 v26, v85, v26
	s_and_b64 s[36:37], s[36:37], vcc
	v_cndmask_b32_e64 v26, 0, v26, s[36:37]
	v_cmp_gt_u32_e64 s[36:37], s13, v84
	s_waitcnt vmcnt(12)
	v_mul_f32_e32 v27, v87, v27
	s_and_b64 s[36:37], s[36:37], vcc
	v_cndmask_b32_e64 v27, 0, v27, s[36:37]
	v_cmp_gt_u32_e64 s[36:37], s13, v86
	s_waitcnt vmcnt(11)
	v_mul_f32_e32 v28, v89, v28
	s_and_b64 s[36:37], s[36:37], vcc
	v_cndmask_b32_e64 v28, 0, v28, s[36:37]
	v_cmp_gt_u32_e64 s[36:37], s13, v88
	s_waitcnt vmcnt(10)
	v_mul_f32_e32 v29, v91, v29
	s_and_b64 s[36:37], s[36:37], vcc
	v_cndmask_b32_e64 v29, 0, v29, s[36:37]
	v_cmp_gt_u32_e64 s[36:37], s13, v90
	s_waitcnt vmcnt(9)
	v_mul_f32_e32 v30, v93, v30
	s_and_b64 s[36:37], s[36:37], vcc
	v_cndmask_b32_e64 v30, 0, v30, s[36:37]
	v_cmp_gt_u32_e64 s[36:37], s13, v92
	s_waitcnt vmcnt(8)
	v_mul_f32_e32 v31, v94, v31
	s_and_b64 vcc, s[36:37], vcc
	v_cndmask_b32_e32 v31, 0, v31, vcc
	s_barrier

; DEVI unsigned pk_bf16(float lo, float hi) { unsigned r; asm("v_cvt_pk_bf16_f32 %0, %1, %2" : "=v"(r) : "v"(lo), "v"(hi)); return r; }
; DEVI void cvt_job(LAS float* tile, const float* src, int srcK, int srcN, bf16_t* dst, int dstLd, int dstRows, int dstCol0, int mode, const float* gk = nullptr) {
;     ...
;         for (int i = 0; i < 16; ++i) { const int k = kap0 + ty + 8 * i - dstCol0; regs[i] = (nok && k >= 0 && k < srcK) ? raw[i] * gs[i] : 0.f; }
;     };
;     auto emit = [&](int t, float (&regs)[16]) {
; #pragma unroll
;         for (int i = 0; i < 16; ++i) tile[(ty + 8 * i) * 65 + tx] = regs[i];
;         __syncthreads();
;         int rho0, kap0, n0; coords(t, rho0, kap0, n0);
;         const int tn = t + 2 * gridDim.x;
;         if (tn < ntot) gl(tn, regs);
; #pragma unroll
;         for (int i = 0; i < 8; ++i) { const int row = ty + 8 * i;
;             const float lo = tile[(2 * tx) * 65 + row], hi = tile[(2 * tx + 1) * 65 + row];
;             *(unsigned*)(dst + (size_t)(rho0 + row) * dstLd + kap0 + 2 * tx) = pk_bf16(lo, hi); }
.LBB0_368:
.LBB0_369:
	s_mul_hi_i32 s8, s4, 0x2e8ba2e9
	s_lshr_b32 s9, s8, 31
	s_ashr_i32 s8, s8, 4
	s_add_i32 s8, s8, s9
	s_mul_i32 s9, s8, 0x3ffff50
	s_add_i32 s9, s7, s9
	s_and_b32 s9, s9, 0x3fffffc
	s_or_b32 s9, s9, s6
	s_lshl_b32 s15, s9, 6
	s_bitset1_b32 s15, 7
	ds_read2_b32 v[134:135], v52 offset0:65 offset1:73
	ds_read2_b32 v[136:137], v52 offset1:8
	v_add_u32_e32 v138, s15, v51
	s_lshl_b32 s8, s8, 7
	v_ashrrev_i32_e32 v139, 31, v138
	s_ashr_i32 s9, s8, 31
	v_lshlrev_b64 v[138:139], 12, v[138:139]
	v_lshl_add_u64 v[138:139], s[62:63], 0, v[138:139]
	s_lshl_b64 s[8:9], s[8:9], 1
	v_lshl_add_u64 v[138:139], v[138:139], 0, s[8:9]
	s_waitcnt lgkmcnt(0)
	v_cvt_pk_bf16_f32 v134, v136, v134
	v_lshl_add_u64 v[138:139], v[138:139], 0, v[32:33]
	global_store_dword v[138:139], v134, off
	v_add_u32_e32 v134, s15, v53
	v_cvt_pk_bf16_f32 v136, v137, v135
	v_ashrrev_i32_e32 v135, 31, v134
	v_lshlrev_b64 v[134:135], 12, v[134:135]
	v_lshl_add_u64 v[134:135], s[62:63], 0, v[134:135]
	v_lshl_add_u64 v[134:135], v[134:135], 0, s[8:9]
	v_lshl_add_u64 v[134:135], v[134:135], 0, v[32:33]
	global_store_dword v[134:135], v136, off
	ds_read2_b32 v[134:135], v52 offset0:16 offset1:24
	ds_read2_b32 v[136:137], v52 offset0:81 offset1:89
	v_add_u32_e32 v138, s15, v54
	v_ashrrev_i32_e32 v139, 31, v138
	v_lshlrev_b64 v[138:139], 12, v[138:139]
	v_lshl_add_u64 v[138:139], s[62:63], 0, v[138:139]
	v_lshl_add_u64 v[138:139], v[138:139], 0, s[8:9]
	s_waitcnt lgkmcnt(0)
	v_cvt_pk_bf16_f32 v134, v134, v136
	v_lshl_add_u64 v[138:139], v[138:139], 0, v[32:33]
	global_store_dword v[138:139], v134, off
	v_add_u32_e32 v134, s15, v55
	v_cvt_pk_bf16_f32 v136, v135, v137
	v_ashrrev_i32_e32 v135, 31, v134
	v_lshlrev_b64 v[134:135], 12, v[134:135]
	v_lshl_add_u64 v[134:135], s[62:63], 0, v[134:135]
	v_lshl_add_u64 v[134:135], v[134:135], 0, s[8:9]
	v_lshl_add_u64 v[134:135], v[134:135], 0, v[32:33]
	global_store_dword v[134:135], v136, off
	ds_read2_b32 v[134:135], v52 offset0:32 offset1:40
	ds_read2_b32 v[136:137], v52 offset0:97 offset1:105
	v_add_u32_e32 v138, s15, v56
	v_ashrrev_i32_e32 v139, 31, v138
	v_lshlrev_b64 v[138:139], 12, v[138:139]
	v_lshl_add_u64 v[138:139], s[62:63], 0, v[138:139]
	v_lshl_add_u64 v[138:139], v[138:139], 0, s[8:9]
	s_waitcnt lgkmcnt(0)
	v_cvt_pk_bf16_f32 v134, v134, v136
	v_lshl_add_u64 v[138:139], v[138:139], 0, v[32:33]
	global_store_dword v[138:139], v134, off
	v_add_u32_e32 v134, s15, v57
	v_cvt_pk_bf16_f32 v136, v135, v137
	v_ashrrev_i32_e32 v135, 31, v134
	v_lshlrev_b64 v[134:135], 12, v[134:135]
	v_lshl_add_u64 v[134:135], s[62:63], 0, v[134:135]
	v_lshl_add_u64 v[134:135], v[134:135], 0, s[8:9]
	v_lshl_add_u64 v[134:135], v[134:135], 0, v[32:33]
	global_store_dword v[134:135], v136, off
	ds_read2_b32 v[134:135], v52 offset0:48 offset1:56
	ds_read2_b32 v[136:137], v52 offset0:113 offset1:121
	v_add_u32_e32 v138, s15, v58
	v_ashrrev_i32_e32 v139, 31, v138
	v_lshlrev_b64 v[138:139], 12, v[138:139]
	v_lshl_add_u64 v[138:139], s[62:63], 0, v[138:139]
	v_lshl_add_u64 v[138:139], v[138:139], 0, s[8:9]
	s_waitcnt lgkmcnt(0)
	v_cvt_pk_bf16_f32 v134, v134, v136
	v_lshl_add_u64 v[138:139], v[138:139], 0, v[32:33]
	global_store_dword v[138:139], v134, off
	v_add_u32_e32 v134, s15, v59
	v_cvt_pk_bf16_f32 v136, v135, v137
	v_ashrrev_i32_e32 v135, 31, v134
	v_lshlrev_b64 v[134:135], 12, v[134:135]
	v_lshl_add_u64 v[134:135], s[62:63], 0, v[134:135]
	v_lshl_add_u64 v[134:135], v[134:135], 0, s[8:9]
	s_add_i32 s8, s33, s4
	v_lshl_add_u64 v[134:135], v[134:135], 0, v[32:33]
	s_cmpk_gt_i32 s8, 0x57f
	global_store_dword v[134:135], v136, off
	s_cselect_b32 s98, 1, 0
	v_cmp_gt_i32_e32 vcc, s12, v63
	v_cmp_gt_u32_e64 s[36:37], s13, v62
	s_waitcnt vmcnt(23)
	v_mul_f32_e32 v0, v65, v0
	s_and_b64 s[36:37], s[36:37], vcc
	v_cndmask_b32_e64 v0, 0, v0, s[36:37]
	v_cmp_gt_u32_e64 s[36:37], s13, v64
	s_waitcnt vmcnt(22)
	v_mul_f32_e32 v1, v67, v1
	s_and_b64 s[36:37], s[36:37], vcc
	v_cndmask_b32_e64 v1, 0, v1, s[36:37]
	v_cmp_gt_u32_e64 s[36:37], s13, v66
	s_waitcnt vmcnt(21)
	v_mul_f32_e32 v2, v69, v2
	s_and_b64 s[36:37], s[36:37], vcc
	v_cndmask_b32_e64 v2, 0, v2, s[36:37]
	v_cmp_gt_u32_e64 s[36:37], s13, v68
	s_waitcnt vmcnt(20)
	v_mul_f32_e32 v3, v71, v3
	s_and_b64 s[36:37], s[36:37], vcc
	v_cndmask_b32_e64 v3, 0, v3, s[36:37]
	v_cmp_gt_u32_e64 s[36:37], s13, v70
	s_waitcnt vmcnt(19)
	v_mul_f32_e32 v4, v73, v4
	s_and_b64 s[36:37], s[36:37], vcc
	v_cndmask_b32_e64 v4, 0, v4, s[36:37]
	v_cmp_gt_u32_e64 s[36:37], s13, v72
	s_waitcnt vmcnt(18)
	v_mul_f32_e32 v5, v75, v5
	s_and_b64 s[36:37], s[36:37], vcc
	v_cndmask_b32_e64 v5, 0, v5, s[36:37]
	v_cmp_gt_u32_e64 s[36:37], s13, v74
	s_waitcnt vmcnt(17)
	v_mul_f32_e32 v6, v77, v6
	s_and_b64 s[36:37], s[36:37], vcc
	v_cndmask_b32_e64 v6, 0, v6, s[36:37]
	v_cmp_gt_u32_e64 s[36:37], s13, v76
	s_waitcnt vmcnt(16)
	v_mul_f32_e32 v7, v80, v7
	s_and_b64 s[36:37], s[36:37], vcc
	v_cndmask_b32_e64 v7, 0, v7, s[36:37]
	v_cmp_gt_u32_e64 s[36:37], s13, v78
	s_waitcnt vmcnt(15)
	v_mul_f32_e32 v8, v81, v8
	s_and_b64 s[36:37], s[36:37], vcc
	v_cndmask_b32_e64 v8, 0, v8, s[36:37]
	v_cmp_gt_u32_e64 s[36:37], s13, v79
	s_waitcnt vmcnt(14)
	v_mul_f32_e32 v9, v83, v9
	s_and_b64 s[36:37], s[36:37], vcc
	v_cndmask_b32_e64 v9, 0, v9, s[36:37]
	v_cmp_gt_u32_e64 s[36:37], s13, v82
	s_waitcnt vmcnt(13)
	v_mul_f32_e32 v10, v85, v10
	s_and_b64 s[36:37], s[36:37], vcc
	v_cndmask_b32_e64 v10, 0, v10, s[36:37]
	v_cmp_gt_u32_e64 s[36:37], s13, v84
	s_waitcnt vmcnt(12)
	v_mul_f32_e32 v11, v87, v11
	s_and_b64 s[36:37], s[36:37], vcc
	v_cndmask_b32_e64 v11, 0, v11, s[36:37]
	v_cmp_gt_u32_e64 s[36:37], s13, v86
	s_waitcnt vmcnt(11)
	v_mul_f32_e32 v12, v89, v12
	s_and_b64 s[36:37], s[36:37], vcc
	v_cndmask_b32_e64 v12, 0, v12, s[36:37]
	v_cmp_gt_u32_e64 s[36:37], s13, v88
	s_waitcnt vmcnt(10)
	v_mul_f32_e32 v13, v91, v13
	s_and_b64 s[36:37], s[36:37], vcc
	v_cndmask_b32_e64 v13, 0, v13, s[36:37]
	v_cmp_gt_u32_e64 s[36:37], s13, v90
	s_waitcnt vmcnt(9)
	v_mul_f32_e32 v14, v93, v14
	s_and_b64 s[36:37], s[36:37], vcc
	v_cndmask_b32_e64 v14, 0, v14, s[36:37]
	v_cmp_gt_u32_e64 s[36:37], s13, v92
	s_waitcnt vmcnt(8)
	v_mul_f32_e32 v15, v94, v15
	s_and_b64 vcc, s[36:37], vcc
	v_cndmask_b32_e32 v15, 0, v15, vcc
	s_cmp_lg_u32 s98, 0
	s_barrier
; DEVI void cvt_job(LAS float* tile, const float* src, int srcK, int srcN, bf16_t* dst, int dstLd, int dstRows, int dstCol0, int mode, const float* gk = nullptr) {
;     ...
;         const int n = n0 + tx, nc = n < srcN ? n : srcN - 1;
;         const bool nok = n < srcN;
;         float raw[16], gs[16];
; #pragma unroll
;         for (int i = 0; i < 16; ++i) { const int k = kap0 + ty + 8 * i - dstCol0; const int kc = k < 0 ? 0 : (k < srcK ? k : srcK - 1);
;             raw[i] = __builtin_nontemporal_load(src + (size_t)kc * srcN + nc); }
;         if (gk) {
; #pragma unroll
;             for (int i = 0; i < 16; ++i) { const int k = kap0 + ty + 8 * i - dstCol0; const int kc = k < 0 ? 0 : (k < srcK ? k : srcK - 1); gs[i] = gk[kc]; }
;         } else {
; #pragma unroll
;             for (int i = 0; i < 16; ++i) gs[i] = 1.0f;
;         }
; #pragma unroll
;         for (int i = 0; i < 16; ++i) { const int k = kap0 + ty + 8 * i - dstCol0; regs[i] = (nok && k >= 0 && k < srcK) ? raw[i] * gs[i] : 0.f; }
;     };
;     auto emit = [&](int t, float (&regs)[16]) {
; #pragma unroll
;         for (int i = 0; i < 16; ++i) tile[(ty + 8 * i) * 65 + tx] = regs[i];
;         __syncthreads();
;         int rho0, kap0, n0; coords(t, rho0, kap0, n0);
;         const int tn = t + 2 * gridDim.x;
;         if (tn < ntot) gl(tn, regs);
	s_cbranch_scc1 .LBB0_363
	s_add_i32 s4, s31, s4
	s_cmpk_gt_i32 s4, 0x57f
	ds_write_b32 v60, v16
	ds_write_b32 v60, v17 offset:2080
	ds_write_b32 v60, v18 offset:4160
	ds_write_b32 v60, v19 offset:6240
	ds_write_b32 v60, v20 offset:8320
	ds_write_b32 v60, v21 offset:10400
	ds_write_b32 v60, v22 offset:12480
	ds_write_b32 v60, v23 offset:14560
	ds_write_b32 v60, v24 offset:16640
	ds_write_b32 v60, v25 offset:18720
	ds_write_b32 v60, v26 offset:20800
	ds_write_b32 v60, v27 offset:22880
	ds_write_b32 v60, v28 offset:24960
	ds_write_b32 v60, v29 offset:27040
	ds_write_b32 v60, v30 offset:29120
	ds_write_b32 v60, v31 offset:31200
	s_waitcnt lgkmcnt(0)
	s_barrier
	s_cbranch_scc1 .LBB0_362
	s_mul_hi_i32 s4, s4, 0x2e8ba2e9
	s_lshr_b32 s9, s4, 31
	s_ashr_i32 s4, s4, 4
	s_add_i32 s4, s4, s9
	s_mul_i32 s9, s4, 0x3ffff50
	s_add_i32 s15, s96, s7
	s_add_i32 s15, s15, s9
	s_and_b32 s9, s15, 0x3fffffc
	s_or_b32 s9, s9, s5
	s_lshl_b32 s9, s9, 6
	s_ashr_i32 s15, s9, 1
	s_and_b32 s15, s15, 0xffffff80
	s_and_b32 s9, s9, 64
	s_or_b32 s9, s9, s15
	v_or_b32_e32 v63, s9, v50
	v_min_i32_e32 v16, 0x15ff, v63
	v_lshl_add_u32 v62, s4, 7, v51
	v_ashrrev_i32_e32 v17, 31, v16
	v_lshl_add_u64 v[94:95], v[16:17], 2, s[0:1]
	v_med3_i32 v16, v62, 0, v61
	v_mad_u64_u32 v[18:19], s[16:17], v16, s11, v[94:95]
	v_add_u32_e32 v64, 8, v62
	global_load_dword v65, v[18:19], off nt
	v_med3_i32 v18, v64, 0, v61
	v_mad_u64_u32 v[20:21], s[16:17], v18, s11, v[94:95]
	v_add_u32_e32 v66, 16, v62
	global_load_dword v67, v[20:21], off nt
	v_med3_i32 v20, v66, 0, v61
	v_mad_u64_u32 v[22:23], s[16:17], v20, s11, v[94:95]
	v_add_u32_e32 v68, 24, v62
	global_load_dword v69, v[22:23], off nt
	v_med3_i32 v22, v68, 0, v61
	v_mad_u64_u32 v[24:25], s[16:17], v22, s11, v[94:95]
	v_add_u32_e32 v70, 32, v62
	global_load_dword v71, v[24:25], off nt
	v_med3_i32 v24, v70, 0, v61
	v_mad_u64_u32 v[26:27], s[16:17], v24, s11, v[94:95]
	v_add_u32_e32 v72, 40, v62
	global_load_dword v73, v[26:27], off nt
	v_med3_i32 v26, v72, 0, v61
	v_mad_u64_u32 v[28:29], s[16:17], v26, s11, v[94:95]
	v_add_u32_e32 v74, 48, v62
	global_load_dword v75, v[28:29], off nt
	v_med3_i32 v28, v74, 0, v61
	v_mad_u64_u32 v[30:31], s[16:17], v28, s11, v[94:95]
	v_add_u32_e32 v76, 56, v62
	global_load_dword v77, v[30:31], off nt
	v_med3_i32 v30, v76, 0, v61
	v_mad_u64_u32 v[34:35], s[16:17], v30, s11, v[94:95]
	v_add_u32_e32 v78, 64, v62
	global_load_dword v80, v[34:35], off nt
	v_med3_i32 v34, v78, 0, v61
	v_mad_u64_u32 v[36:37], s[16:17], v34, s11, v[94:95]
	v_add_u32_e32 v79, 0x48, v62
	global_load_dword v81, v[36:37], off nt
	v_med3_i32 v36, v79, 0, v61
	v_mad_u64_u32 v[38:39], s[16:17], v36, s11, v[94:95]
	v_add_u32_e32 v82, 0x50, v62
	global_load_dword v83, v[38:39], off nt
	v_med3_i32 v38, v82, 0, v61
	v_mad_u64_u32 v[40:41], s[16:17], v38, s11, v[94:95]
	v_add_u32_e32 v84, 0x58, v62
	global_load_dword v85, v[40:41], off nt
	v_med3_i32 v40, v84, 0, v61
	v_mad_u64_u32 v[42:43], s[16:17], v40, s11, v[94:95]
	v_add_u32_e32 v86, 0x60, v62
	global_load_dword v87, v[42:43], off nt
	v_med3_i32 v42, v86, 0, v61
	v_mad_u64_u32 v[44:45], s[16:17], v42, s11, v[94:95]
	v_add_u32_e32 v88, 0x68, v62
	global_load_dword v89, v[44:45], off nt
	v_med3_i32 v44, v88, 0, v61
	v_mad_u64_u32 v[46:47], s[16:17], v44, s11, v[94:95]
	v_add_u32_e32 v90, 0x70, v62
	global_load_dword v91, v[46:47], off nt
	v_med3_i32 v46, v90, 0, v61
	v_mad_u64_u32 v[48:49], s[16:17], v46, s11, v[94:95]
	v_add_u32_e32 v92, 0x78, v62
	global_load_dword v93, v[48:49], off nt
	v_med3_i32 v48, v92, 0, v61
	v_mad_u64_u32 v[94:95], s[16:17], v48, s11, v[94:95]
	global_load_dword v94, v[94:95], off nt
	v_readlane_b32 s16, v240, 48
	v_readlane_b32 s17, v240, 49
	s_and_b64 vcc, exec, s[16:17]
	s_cbranch_vccz .LBB0_360
	v_mov_b32_e32 v31, 1.0
	v_mov_b32_e32 v30, 1.0
	v_mov_b32_e32 v29, 1.0
	v_mov_b32_e32 v28, 1.0
	v_mov_b32_e32 v27, 1.0
	v_mov_b32_e32 v26, 1.0
	v_mov_b32_e32 v25, 1.0
	v_mov_b32_e32 v24, 1.0
	v_mov_b32_e32 v23, 1.0
	v_mov_b32_e32 v22, 1.0
	v_mov_b32_e32 v21, 1.0
	v_mov_b32_e32 v20, 1.0
	v_mov_b32_e32 v19, 1.0
	v_mov_b32_e32 v18, 1.0
	v_mov_b32_e32 v17, 1.0
	v_mov_b32_e32 v16, 1.0
	s_branch .LBB0_361

; DEVI unsigned pk_bf16(float lo, float hi) { unsigned r; asm("v_cvt_pk_bf16_f32 %0, %1, %2" : "=v"(r) : "v"(lo), "v"(hi)); return r; }
; DEVI void cvt_job(LAS float* tile, const float* src, int srcK, int srcN, bf16_t* dst, int dstLd, int dstRows, int dstCol0, int mode, const float* gk = nullptr) {
;     ...
;         for (int i = 0; i < 16; ++i) { const int k = kap0 + ty + 8 * i - dstCol0; const int kc = k < 0 ? 0 : (k < srcK ? k : srcK - 1);
;             raw[i] = __builtin_nontemporal_load(src + (size_t)kc * srcN + nc); }
;         if (gk) {
; #pragma unroll
;             for (int i = 0; i < 16; ++i) { const int k = kap0 + ty + 8 * i - dstCol0; const int kc = k < 0 ? 0 : (k < srcK ? k : srcK - 1); gs[i] = gk[kc]; }
;         } else {
; #pragma unroll
;             for (int i = 0; i < 16; ++i) gs[i] = 1.0f;
;         }
; #pragma unroll
;         for (int i = 0; i < 16; ++i) { const int k = kap0 + ty + 8 * i - dstCol0; regs[i] = (nok && k >= 0 && k < srcK) ? raw[i] * gs[i] : 0.f; }
;     ...
;         for (int i = 0; i < 8; ++i) { const int row = ty + 8 * i;
;             const float lo = tile[(2 * tx) * 65 + row], hi = tile[(2 * tx + 1) * 65 + row];
;             *(unsigned*)(dst + (size_t)(rho0 + row) * dstLd + kap0 + 2 * tx) = pk_bf16(lo, hi); }
.LBB0_1411:
	ds_read2_b32 v[142:143], v35 offset0:65 offset1:73
	ds_read2_b32 v[144:145], v35 offset1:8
	s_ashr_i32 s4, s8, 31
	s_lshr_b32 s4, s4, 27
	s_add_i32 s8, s8, s4
	s_ashr_i32 s4, s8, 5
	v_readlane_b32 s14, v238, 59
	s_lshl_b32 s8, s4, 7
	s_waitcnt lgkmcnt(0)
	v_cvt_pk_bf16_f32 v142, v144, v142
	v_add_u32_e32 v144, s5, v37
	s_lshl_b32 s4, s4, 11
	v_readlane_b32 s15, v238, 60
	s_ashr_i32 s9, s8, 31
	v_subrev_u32_e32 v150, s4, v144
	v_mov_b64_e32 v[146:147], s[14:15]
	v_mad_i64_i32 v[148:149], s[14:15], v150, s11, v[146:147]
	s_lshl_b64 s[8:9], s[8:9], 1
	v_lshl_add_u64 v[148:149], v[148:149], 0, s[8:9]
	v_lshl_add_u64 v[148:149], v[148:149], 0, v[32:33]
	global_store_dword v[148:149], v142, off
	v_add_u32_e32 v142, 8, v150
	v_cvt_pk_bf16_f32 v144, v145, v143
	v_mad_i64_i32 v[142:143], s[14:15], v142, s11, v[146:147]
	v_lshl_add_u64 v[142:143], v[142:143], 0, s[8:9]
	v_lshl_add_u64 v[142:143], v[142:143], 0, v[32:33]
	global_store_dword v[142:143], v144, off
	ds_read2_b32 v[142:143], v35 offset0:16 offset1:24
	ds_read2_b32 v[144:145], v35 offset0:81 offset1:89
	s_waitcnt lgkmcnt(0)
	v_cvt_pk_bf16_f32 v142, v142, v144
	v_add_u32_e32 v144, 16, v150
	v_mad_i64_i32 v[148:149], s[14:15], v144, s11, v[146:147]
	v_lshl_add_u64 v[148:149], v[148:149], 0, s[8:9]
	v_lshl_add_u64 v[148:149], v[148:149], 0, v[32:33]
	global_store_dword v[148:149], v142, off
	v_add_u32_e32 v142, 24, v150
	v_cvt_pk_bf16_f32 v144, v143, v145
	v_mad_i64_i32 v[142:143], s[14:15], v142, s11, v[146:147]
	v_lshl_add_u64 v[142:143], v[142:143], 0, s[8:9]
	v_lshl_add_u64 v[142:143], v[142:143], 0, v[32:33]
	global_store_dword v[142:143], v144, off
	ds_read2_b32 v[142:143], v35 offset0:32 offset1:40
	ds_read2_b32 v[144:145], v35 offset0:97 offset1:105
	s_waitcnt lgkmcnt(0)
	v_cvt_pk_bf16_f32 v142, v142, v144
	v_add_u32_e32 v144, 32, v150
	v_mad_i64_i32 v[148:149], s[14:15], v144, s11, v[146:147]
	v_lshl_add_u64 v[148:149], v[148:149], 0, s[8:9]
	v_lshl_add_u64 v[148:149], v[148:149], 0, v[32:33]
	global_store_dword v[148:149], v142, off
	v_add_u32_e32 v142, 40, v150
	v_cvt_pk_bf16_f32 v144, v143, v145
	v_mad_i64_i32 v[142:143], s[14:15], v142, s11, v[146:147]
	v_lshl_add_u64 v[142:143], v[142:143], 0, s[8:9]
	v_lshl_add_u64 v[142:143], v[142:143], 0, v[32:33]
	global_store_dword v[142:143], v144, off
	ds_read2_b32 v[142:143], v35 offset0:48 offset1:56
	ds_read2_b32 v[144:145], v35 offset0:113 offset1:121
	s_waitcnt lgkmcnt(0)
	v_cvt_pk_bf16_f32 v142, v142, v144
	v_add_u32_e32 v144, 48, v150
	v_mad_i64_i32 v[148:149], s[14:15], v144, s11, v[146:147]
	v_lshl_add_u64 v[148:149], v[148:149], 0, s[8:9]
	v_lshl_add_u64 v[148:149], v[148:149], 0, v[32:33]
	global_store_dword v[148:149], v142, off
	v_add_u32_e32 v142, 56, v150
	v_cvt_pk_bf16_f32 v144, v143, v145
	v_mad_i64_i32 v[142:143], s[14:15], v142, s11, v[146:147]
	v_lshl_add_u64 v[142:143], v[142:143], 0, s[8:9]
	v_lshl_add_u64 v[142:143], v[142:143], 0, v[32:33]
	global_store_dword v[142:143], v144, off
	v_cmp_gt_i32_e32 vcc, s7, v44
	v_cmp_gt_u32_e64 s[36:37], s10, v45
	s_and_b64 s[36:37], s[36:37], vcc
	s_waitcnt vmcnt(23)
	v_cndmask_b32_e64 v16, 0, v53, s[36:37]
	v_cmp_gt_u32_e64 s[36:37], s10, v46
	s_and_b64 s[36:37], s[36:37], vcc
	s_waitcnt vmcnt(22)
	v_cndmask_b32_e64 v17, 0, v54, s[36:37]
	v_cmp_gt_u32_e64 s[36:37], s10, v47
	s_and_b64 s[36:37], s[36:37], vcc
	s_waitcnt vmcnt(21)
	v_cndmask_b32_e64 v18, 0, v55, s[36:37]
	v_cmp_gt_u32_e64 s[36:37], s10, v48
	s_and_b64 s[36:37], s[36:37], vcc
	s_waitcnt vmcnt(20)
	v_cndmask_b32_e64 v19, 0, v56, s[36:37]
	v_cmp_gt_u32_e64 s[36:37], s10, v49
	s_and_b64 s[36:37], s[36:37], vcc
	s_waitcnt vmcnt(19)
	v_cndmask_b32_e64 v20, 0, v57, s[36:37]
	v_cmp_gt_u32_e64 s[36:37], s10, v50
	s_and_b64 s[36:37], s[36:37], vcc
	s_waitcnt vmcnt(18)
	v_cndmask_b32_e64 v21, 0, v28, s[36:37]
	v_cmp_gt_u32_e64 s[36:37], s10, v51
	s_and_b64 s[36:37], s[36:37], vcc
	s_waitcnt vmcnt(17)
	v_cndmask_b32_e64 v22, 0, v29, s[36:37]
	v_cmp_gt_u32_e64 s[36:37], s10, v52
	s_and_b64 s[36:37], s[36:37], vcc
	s_waitcnt vmcnt(16)
	v_cndmask_b32_e64 v23, 0, v30, s[36:37]
	v_cmp_gt_u32_e64 s[36:37], s10, v31
	s_and_b64 s[36:37], s[36:37], vcc
	s_waitcnt vmcnt(15)
	v_cndmask_b32_e64 v24, 0, v60, s[36:37]
	v_cmp_gt_u32_e64 s[36:37], s10, v42
	s_and_b64 s[36:37], s[36:37], vcc
	s_waitcnt vmcnt(14)
	v_cndmask_b32_e64 v25, 0, v61, s[36:37]
	v_cmp_gt_u32_e64 s[36:37], s10, v43
	s_and_b64 s[36:37], s[36:37], vcc
	s_waitcnt vmcnt(13)
	v_cndmask_b32_e64 v26, 0, v62, s[36:37]
	v_cmp_gt_u32_e64 s[36:37], s10, v58
	s_and_b64 s[36:37], s[36:37], vcc
	s_waitcnt vmcnt(12)
	v_cndmask_b32_e64 v27, 0, v63, s[36:37]
	v_cmp_gt_u32_e64 s[36:37], s10, v59
	s_and_b64 s[36:37], s[36:37], vcc
	s_waitcnt vmcnt(11)
	v_cndmask_b32_e64 v28, 0, v64, s[36:37]
	v_cmp_gt_u32_e64 s[36:37], s10, v65
	s_and_b64 s[36:37], s[36:37], vcc
	s_waitcnt vmcnt(10)
	v_cndmask_b32_e64 v29, 0, v67, s[36:37]
	v_cmp_gt_u32_e64 s[36:37], s10, v66
	s_and_b64 s[36:37], s[36:37], vcc
	s_waitcnt vmcnt(9)
	v_cndmask_b32_e64 v30, 0, v68, s[36:37]
	v_cmp_gt_u32_e64 s[36:37], s10, v69
	s_and_b64 vcc, s[36:37], vcc
	s_waitcnt vmcnt(8)
	v_cndmask_b32_e32 v31, 0, v70, vcc
	s_barrier

; DEVI int obid() { int b = __builtin_amdgcn_workgroup_id_x(); asm volatile("" : "+s"(b)); return b; }
; DEVI unsigned pk_bf16(float lo, float hi) { unsigned r; asm("v_cvt_pk_bf16_f32 %0, %1, %2" : "=v"(r) : "v"(lo), "v"(hi)); return r; }
; DEVI void cvt_job(LAS float* tile, const float* src, int srcK, int srcN, bf16_t* dst, int dstLd, int dstRows, int dstCol0, int mode, const float* gk = nullptr) {
;     ...
;         for (int i = 0; i < 16; ++i) { const int k = kap0 + ty + 8 * i - dstCol0; const int kc = k < 0 ? 0 : (k < srcK ? k : srcK - 1);
;             raw[i] = __builtin_nontemporal_load(src + (size_t)kc * srcN + nc); }
;         if (gk) {
; #pragma unroll
;             for (int i = 0; i < 16; ++i) { const int k = kap0 + ty + 8 * i - dstCol0; const int kc = k < 0 ? 0 : (k < srcK ? k : srcK - 1); gs[i] = gk[kc]; }
;         } else {
; #pragma unroll
;             for (int i = 0; i < 16; ++i) gs[i] = 1.0f;
;         }
; #pragma unroll
;         for (int i = 0; i < 16; ++i) { const int k = kap0 + ty + 8 * i - dstCol0; regs[i] = (nok && k >= 0 && k < srcK) ? raw[i] * gs[i] : 0.f; }
;     ...
;         for (int i = 0; i < 8; ++i) { const int row = ty + 8 * i;
;             const float lo = tile[(2 * tx) * 65 + row], hi = tile[(2 * tx + 1) * 65 + row];
;             *(unsigned*)(dst + (size_t)(rho0 + row) * dstLd + kap0 + 2 * tx) = pk_bf16(lo, hi); }
;         __syncthreads();
;     };
;     const int G = gridDim.x;
;     int t = obid();
;     if (t < ntot) gl(t, regsA);
;     if (t + G < ntot) gl(t + G, regsB);
;     while (t < ntot) {
;         emit(t, regsA);
;         if (t + G < ntot) emit(t + G, regsB);
;         t += 2 * G;
.LBB0_1415:
	ds_read2_b32 v[142:143], v35 offset0:65 offset1:73
	ds_read2_b32 v[144:145], v35 offset1:8
	s_ashr_i32 s8, s4, 31
	s_lshr_b32 s8, s8, 27
	s_add_i32 s8, s4, s8
	s_ashr_i32 s13, s8, 5
	v_readlane_b32 s14, v238, 59
	s_lshl_b32 s8, s13, 7
	s_waitcnt lgkmcnt(0)
	v_cvt_pk_bf16_f32 v142, v144, v142
	v_add_u32_e32 v144, s5, v38
	s_lshl_b32 s13, s13, 11
	v_readlane_b32 s15, v238, 60
	s_ashr_i32 s9, s8, 31
	v_subrev_u32_e32 v150, s13, v144
	v_mov_b64_e32 v[146:147], s[14:15]
	v_mad_i64_i32 v[148:149], s[14:15], v150, s11, v[146:147]
	s_lshl_b64 s[8:9], s[8:9], 1
	v_lshl_add_u64 v[148:149], v[148:149], 0, s[8:9]
	v_lshl_add_u64 v[148:149], v[148:149], 0, v[32:33]
	global_store_dword v[148:149], v142, off
	v_add_u32_e32 v142, 8, v150
	v_cvt_pk_bf16_f32 v144, v145, v143
	v_mad_i64_i32 v[142:143], s[14:15], v142, s11, v[146:147]
	v_lshl_add_u64 v[142:143], v[142:143], 0, s[8:9]
	v_lshl_add_u64 v[142:143], v[142:143], 0, v[32:33]
	global_store_dword v[142:143], v144, off
	ds_read2_b32 v[142:143], v35 offset0:16 offset1:24
	ds_read2_b32 v[144:145], v35 offset0:81 offset1:89
	s_waitcnt lgkmcnt(0)
	v_cvt_pk_bf16_f32 v142, v142, v144
	v_add_u32_e32 v144, 16, v150
	v_mad_i64_i32 v[148:149], s[14:15], v144, s11, v[146:147]
	v_lshl_add_u64 v[148:149], v[148:149], 0, s[8:9]
	v_lshl_add_u64 v[148:149], v[148:149], 0, v[32:33]
	global_store_dword v[148:149], v142, off
	v_add_u32_e32 v142, 24, v150
	v_cvt_pk_bf16_f32 v144, v143, v145
	v_mad_i64_i32 v[142:143], s[14:15], v142, s11, v[146:147]
	v_lshl_add_u64 v[142:143], v[142:143], 0, s[8:9]
	v_lshl_add_u64 v[142:143], v[142:143], 0, v[32:33]
	global_store_dword v[142:143], v144, off
	ds_read2_b32 v[142:143], v35 offset0:32 offset1:40
	ds_read2_b32 v[144:145], v35 offset0:97 offset1:105
	s_waitcnt lgkmcnt(0)
	v_cvt_pk_bf16_f32 v142, v142, v144
	v_add_u32_e32 v144, 32, v150
	v_mad_i64_i32 v[148:149], s[14:15], v144, s11, v[146:147]
	v_lshl_add_u64 v[148:149], v[148:149], 0, s[8:9]
	v_lshl_add_u64 v[148:149], v[148:149], 0, v[32:33]
	global_store_dword v[148:149], v142, off
	v_add_u32_e32 v142, 40, v150
	v_cvt_pk_bf16_f32 v144, v143, v145
	v_mad_i64_i32 v[142:143], s[14:15], v142, s11, v[146:147]
	v_lshl_add_u64 v[142:143], v[142:143], 0, s[8:9]
	v_lshl_add_u64 v[142:143], v[142:143], 0, v[32:33]
	global_store_dword v[142:143], v144, off
	ds_read2_b32 v[142:143], v35 offset0:48 offset1:56
	ds_read2_b32 v[144:145], v35 offset0:113 offset1:121
	s_waitcnt lgkmcnt(0)
	v_cvt_pk_bf16_f32 v142, v142, v144
	v_add_u32_e32 v144, 48, v150
	v_mad_i64_i32 v[148:149], s[14:15], v144, s11, v[146:147]
	v_lshl_add_u64 v[148:149], v[148:149], 0, s[8:9]
	v_lshl_add_u64 v[148:149], v[148:149], 0, v[32:33]
	global_store_dword v[148:149], v142, off
	v_add_u32_e32 v142, 56, v150
	v_cvt_pk_bf16_f32 v144, v143, v145
	v_mad_i64_i32 v[142:143], s[14:15], v142, s11, v[146:147]
	v_lshl_add_u64 v[142:143], v[142:143], 0, s[8:9]
	s_add_i32 s8, s33, s4
	v_lshl_add_u64 v[142:143], v[142:143], 0, v[32:33]
	s_cmpk_gt_i32 s8, 0x57f
	global_store_dword v[142:143], v144, off
	s_cselect_b32 s98, 1, 0
	s_mov_b64 s[100:101], vcc
	v_cmp_gt_i32_e32 vcc, s7, v44
	v_cmp_gt_u32_e64 s[36:37], s10, v45
	s_and_b64 s[36:37], s[36:37], vcc
	s_waitcnt vmcnt(23)
	v_cndmask_b32_e64 v0, 0, v53, s[36:37]
	v_cmp_gt_u32_e64 s[36:37], s10, v46
	s_and_b64 s[36:37], s[36:37], vcc
	s_waitcnt vmcnt(22)
	v_cndmask_b32_e64 v1, 0, v54, s[36:37]
	v_cmp_gt_u32_e64 s[36:37], s10, v47
	s_and_b64 s[36:37], s[36:37], vcc
	s_waitcnt vmcnt(21)
	v_cndmask_b32_e64 v2, 0, v55, s[36:37]
	v_cmp_gt_u32_e64 s[36:37], s10, v48
	s_and_b64 s[36:37], s[36:37], vcc
	s_waitcnt vmcnt(20)
	v_cndmask_b32_e64 v3, 0, v56, s[36:37]
	v_cmp_gt_u32_e64 s[36:37], s10, v49
	s_and_b64 s[36:37], s[36:37], vcc
	s_waitcnt vmcnt(19)
	v_cndmask_b32_e64 v4, 0, v57, s[36:37]
	v_cmp_gt_u32_e64 s[36:37], s10, v50
	s_and_b64 s[36:37], s[36:37], vcc
	s_waitcnt vmcnt(18)
	v_cndmask_b32_e64 v5, 0, v12, s[36:37]
	v_cmp_gt_u32_e64 s[36:37], s10, v51
	s_and_b64 s[36:37], s[36:37], vcc
	s_waitcnt vmcnt(17)
	v_cndmask_b32_e64 v6, 0, v13, s[36:37]
	v_cmp_gt_u32_e64 s[36:37], s10, v52
	s_and_b64 s[36:37], s[36:37], vcc
	s_waitcnt vmcnt(16)
	v_cndmask_b32_e64 v7, 0, v14, s[36:37]
	v_cmp_gt_u32_e64 s[36:37], s10, v15
	s_and_b64 s[36:37], s[36:37], vcc
	s_waitcnt vmcnt(15)
	v_cndmask_b32_e64 v8, 0, v60, s[36:37]
	v_cmp_gt_u32_e64 s[36:37], s10, v42
	s_and_b64 s[36:37], s[36:37], vcc
	s_waitcnt vmcnt(14)
	v_cndmask_b32_e64 v9, 0, v61, s[36:37]
	v_cmp_gt_u32_e64 s[36:37], s10, v43
	s_and_b64 s[36:37], s[36:37], vcc
	s_waitcnt vmcnt(13)
	v_cndmask_b32_e64 v10, 0, v62, s[36:37]
	v_cmp_gt_u32_e64 s[36:37], s10, v58
	s_and_b64 s[36:37], s[36:37], vcc
	s_waitcnt vmcnt(12)
	v_cndmask_b32_e64 v11, 0, v63, s[36:37]
	v_cmp_gt_u32_e64 s[36:37], s10, v59
	s_and_b64 s[36:37], s[36:37], vcc
	s_waitcnt vmcnt(11)
	v_cndmask_b32_e64 v12, 0, v64, s[36:37]
	v_cmp_gt_u32_e64 s[36:37], s10, v65
	s_and_b64 s[36:37], s[36:37], vcc
	s_waitcnt vmcnt(10)
	v_cndmask_b32_e64 v13, 0, v67, s[36:37]
	v_cmp_gt_u32_e64 s[36:37], s10, v66
	s_and_b64 s[36:37], s[36:37], vcc
	s_waitcnt vmcnt(9)
	v_cndmask_b32_e64 v14, 0, v68, s[36:37]
	v_cmp_gt_u32_e64 s[36:37], s10, v69
	s_and_b64 vcc, s[36:37], vcc
	s_waitcnt vmcnt(8)
	v_cndmask_b32_e32 v15, 0, v70, vcc
	s_mov_b64 vcc, s[100:101]
	s_cmp_lg_u32 s98, 0
	s_barrier
; DEVI void cvt_job(LAS float* tile, const float* src, int srcK, int srcN, bf16_t* dst, int dstLd, int dstRows, int dstCol0, int mode, const float* gk = nullptr) {
;     ...
;     auto gl = [&](int t, float (&regs)[16]) {
;         int rho0, kap0, n0; coords(t, rho0, kap0, n0);
;         const int n = n0 + tx, nc = n < srcN ? n : srcN - 1;
;         const bool nok = n < srcN;
;         float raw[16], gs[16];
; #pragma unroll
;         for (int i = 0; i < 16; ++i) { const int k = kap0 + ty + 8 * i - dstCol0; const int kc = k < 0 ? 0 : (k < srcK ? k : srcK - 1);
;             raw[i] = __builtin_nontemporal_load(src + (size_t)kc * srcN + nc); }
;     ...
;     auto emit = [&](int t, float (&regs)[16]) {
; #pragma unroll
;         for (int i = 0; i < 16; ++i) tile[(ty + 8 * i) * 65 + tx] = regs[i];
;         __syncthreads();
;         int rho0, kap0, n0; coords(t, rho0, kap0, n0);
;         const int tn = t + 2 * gridDim.x;
;         if (tn < ntot) gl(tn, regs);
	s_cbranch_scc1 .LBB0_1412
	s_add_i32 s4, s18, s4
	s_cmpk_gt_i32 s4, 0x57f
	ds_write_b32 v40, v16
	ds_write_b32 v40, v17 offset:2080
	ds_write_b32 v40, v18 offset:4160
	ds_write_b32 v40, v19 offset:6240
	ds_write_b32 v40, v20 offset:8320
	ds_write_b32 v40, v21 offset:10400
	ds_write_b32 v40, v22 offset:12480
	ds_write_b32 v40, v23 offset:14560
	ds_write_b32 v40, v24 offset:16640
	ds_write_b32 v40, v25 offset:18720
	ds_write_b32 v40, v26 offset:20800
	ds_write_b32 v40, v27 offset:22880
	ds_write_b32 v40, v28 offset:24960
	ds_write_b32 v40, v29 offset:27040
	ds_write_b32 v40, v30 offset:29120
	ds_write_b32 v40, v31 offset:31200
	s_waitcnt lgkmcnt(0)
	s_barrier
	s_cbranch_scc1 .LBB0_1411
	s_ashr_i32 s9, s4, 31
	s_lshr_b32 s9, s9, 27
	s_add_i32 s4, s4, s9
	s_ashr_i32 s4, s4, 5
	v_add_u32_e32 v16, s5, v36
	s_lshl_b32 s9, s4, 11
	v_subrev_u32_e32 v44, s9, v16
	v_lshl_add_u32 v45, s4, 7, v34
	v_min_i32_e32 v16, 0x7ff, v44
	v_add_u32_e32 v50, 40, v45
	v_add_u32_e32 v51, 48, v45
	v_ashrrev_i32_e32 v17, 31, v16
	v_med3_i32 v18, v45, 0, v41
	v_add_u32_e32 v46, 8, v45
	v_add_u32_e32 v47, 16, v45
	v_add_u32_e32 v48, 24, v45
	v_add_u32_e32 v49, 32, v45
	v_med3_i32 v28, v50, 0, v41
	v_med3_i32 v30, v51, 0, v41
	v_add_u32_e32 v52, 56, v45
	v_lshl_add_u64 v[16:17], v[16:17], 2, s[0:1]
	v_lshlrev_b32_e32 v18, 13, v18
	v_mov_b32_e32 v19, v33
	v_med3_i32 v20, v46, 0, v41
	v_med3_i32 v22, v47, 0, v41
	v_med3_i32 v24, v48, 0, v41
	v_med3_i32 v26, v49, 0, v41
	v_lshlrev_b32_e32 v28, 13, v28
	v_mov_b32_e32 v29, v33
	v_lshlrev_b32_e32 v30, 13, v30
	v_mov_b32_e32 v31, v33
	v_med3_i32 v42, v52, 0, v41
	v_lshl_add_u64 v[18:19], v[16:17], 0, v[18:19]
	v_lshlrev_b32_e32 v20, 13, v20
	v_mov_b32_e32 v21, v33
	v_lshlrev_b32_e32 v22, 13, v22
	v_mov_b32_e32 v23, v33
	v_lshlrev_b32_e32 v24, 13, v24
	v_mov_b32_e32 v25, v33
	v_lshlrev_b32_e32 v26, 13, v26
	v_mov_b32_e32 v27, v33
	v_lshl_add_u64 v[28:29], v[16:17], 0, v[28:29]
	v_lshl_add_u64 v[30:31], v[16:17], 0, v[30:31]
	v_lshlrev_b32_e32 v42, 13, v42
	v_mov_b32_e32 v43, v33
	v_lshl_add_u64 v[20:21], v[16:17], 0, v[20:21]
	v_lshl_add_u64 v[22:23], v[16:17], 0, v[22:23]
	v_lshl_add_u64 v[24:25], v[16:17], 0, v[24:25]
	v_lshl_add_u64 v[26:27], v[16:17], 0, v[26:27]
	v_lshl_add_u64 v[42:43], v[16:17], 0, v[42:43]
	global_load_dword v53, v[18:19], off nt
	global_load_dword v54, v[20:21], off nt
	global_load_dword v55, v[22:23], off nt
	global_load_dword v56, v[24:25], off nt
	global_load_dword v57, v[26:27], off nt
	s_nop 0
	global_load_dword v28, v[28:29], off nt
	s_nop 0
	global_load_dword v29, v[30:31], off nt
	s_nop 0
	global_load_dword v30, v[42:43], off nt
	v_add_u32_e32 v31, 64, v45
	v_med3_i32 v18, v31, 0, v41
	v_add_u32_e32 v42, 0x48, v45
	v_add_u32_e32 v43, 0x50, v45
	v_add_u32_e32 v58, 0x58, v45
	v_add_u32_e32 v59, 0x60, v45
	v_lshlrev_b32_e32 v18, 13, v18
	v_mov_b32_e32 v19, v33
	v_med3_i32 v20, v42, 0, v41
	v_med3_i32 v22, v43, 0, v41
	v_med3_i32 v24, v58, 0, v41
	v_med3_i32 v26, v59, 0, v41
	v_lshl_add_u64 v[18:19], v[16:17], 0, v[18:19]
	v_lshlrev_b32_e32 v20, 13, v20
	v_mov_b32_e32 v21, v33
	v_lshlrev_b32_e32 v22, 13, v22
	v_mov_b32_e32 v23, v33
	v_lshlrev_b32_e32 v24, 13, v24
	v_mov_b32_e32 v25, v33
	v_lshlrev_b32_e32 v26, 13, v26
	v_mov_b32_e32 v27, v33
	v_lshl_add_u64 v[20:21], v[16:17], 0, v[20:21]
	v_lshl_add_u64 v[22:23], v[16:17], 0, v[22:23]
	v_lshl_add_u64 v[24:25], v[16:17], 0, v[24:25]
	v_lshl_add_u64 v[26:27], v[16:17], 0, v[26:27]
	global_load_dword v60, v[18:19], off nt
	global_load_dword v61, v[20:21], off nt
	global_load_dword v62, v[22:23], off nt
	global_load_dword v63, v[24:25], off nt
	global_load_dword v64, v[26:27], off nt
	v_add_u32_e32 v65, 0x68, v45
	v_med3_i32 v18, v65, 0, v41
	v_add_u32_e32 v66, 0x70, v45
	v_lshlrev_b32_e32 v18, 13, v18
	v_mov_b32_e32 v19, v33
	v_med3_i32 v20, v66, 0, v41
	v_lshl_add_u64 v[18:19], v[16:17], 0, v[18:19]
	v_lshlrev_b32_e32 v20, 13, v20
	v_mov_b32_e32 v21, v33
	v_add_u32_e32 v69, 0x78, v45
	v_lshl_add_u64 v[20:21], v[16:17], 0, v[20:21]
	global_load_dword v67, v[18:19], off nt
	global_load_dword v68, v[20:21], off nt
	v_med3_i32 v18, v69, 0, v41
	v_lshlrev_b32_e32 v18, 13, v18
	v_mov_b32_e32 v19, v33
	v_lshl_add_u64 v[16:17], v[16:17], 0, v[18:19]
	global_load_dword v70, v[16:17], off nt
	s_branch .LBB0_1411

; DEVI unsigned pk_bf16(float lo, float hi) { unsigned r; asm("v_cvt_pk_bf16_f32 %0, %1, %2" : "=v"(r) : "v"(lo), "v"(hi)); return r; }
; DEVI void cvt_job(LAS float* tile, const float* src, int srcK, int srcN, bf16_t* dst, int dstLd, int dstRows, int dstCol0, int mode, const float* gk = nullptr) {
;     ...
;         for (int i = 0; i < 16; ++i) { const int k = kap0 + ty + 8 * i - dstCol0; const int kc = k < 0 ? 0 : (k < srcK ? k : srcK - 1);
;             raw[i] = __builtin_nontemporal_load(src + (size_t)kc * srcN + nc); }
;         if (gk) {
; #pragma unroll
;             for (int i = 0; i < 16; ++i) { const int k = kap0 + ty + 8 * i - dstCol0; const int kc = k < 0 ? 0 : (k < srcK ? k : srcK - 1); gs[i] = gk[kc]; }
;         } else {
; #pragma unroll
;             for (int i = 0; i < 16; ++i) gs[i] = 1.0f;
;         }
; #pragma unroll
;         for (int i = 0; i < 16; ++i) { const int k = kap0 + ty + 8 * i - dstCol0; regs[i] = (nok && k >= 0 && k < srcK) ? raw[i] * gs[i] : 0.f; }
;     ...
;         for (int i = 0; i < 8; ++i) { const int row = ty + 8 * i;
;             const float lo = tile[(2 * tx) * 65 + row], hi = tile[(2 * tx + 1) * 65 + row];
;             *(unsigned*)(dst + (size_t)(rho0 + row) * dstLd + kap0 + 2 * tx) = pk_bf16(lo, hi); }
.LBB0_1522:
.LBB0_1523:
	s_mul_hi_i32 s4, s8, 0x2e8ba2e9
	s_lshr_b32 s8, s4, 31
	s_ashr_i32 s4, s4, 4
	s_add_i32 s8, s4, s8
	s_mul_i32 s4, s8, 0x3ffff50
	s_add_i32 s9, s30, s7
	s_add_i32 s9, s9, s4
	s_and_b32 s4, s9, 0x3fffffc
	s_or_b32 s4, s4, s5
	s_lshl_b32 s4, s4, 6
	ds_read2_b32 v[134:135], v52 offset0:65 offset1:73
	ds_read2_b32 v[136:137], v52 offset1:8
	v_add_u32_e32 v138, s4, v51
	s_lshl_b32 s8, s8, 7
	v_ashrrev_i32_e32 v139, 31, v138
	s_ashr_i32 s9, s8, 31
	v_lshlrev_b64 v[138:139], 12, v[138:139]
	v_lshl_add_u64 v[138:139], s[62:63], 0, v[138:139]
	s_lshl_b64 s[8:9], s[8:9], 1
	v_lshl_add_u64 v[138:139], v[138:139], 0, s[8:9]
	s_waitcnt lgkmcnt(0)
	v_cvt_pk_bf16_f32 v134, v136, v134
	v_lshl_add_u64 v[138:139], v[138:139], 0, v[32:33]
	global_store_dword v[138:139], v134, off
	v_add_u32_e32 v134, s4, v53
	v_cvt_pk_bf16_f32 v136, v137, v135
	v_ashrrev_i32_e32 v135, 31, v134
	v_lshlrev_b64 v[134:135], 12, v[134:135]
	v_lshl_add_u64 v[134:135], s[62:63], 0, v[134:135]
	v_lshl_add_u64 v[134:135], v[134:135], 0, s[8:9]
	v_lshl_add_u64 v[134:135], v[134:135], 0, v[32:33]
	global_store_dword v[134:135], v136, off
	ds_read2_b32 v[134:135], v52 offset0:16 offset1:24
	ds_read2_b32 v[136:137], v52 offset0:81 offset1:89
	v_add_u32_e32 v138, s4, v54
	v_ashrrev_i32_e32 v139, 31, v138
	v_lshlrev_b64 v[138:139], 12, v[138:139]
	v_lshl_add_u64 v[138:139], s[62:63], 0, v[138:139]
	v_lshl_add_u64 v[138:139], v[138:139], 0, s[8:9]
	s_waitcnt lgkmcnt(0)
	v_cvt_pk_bf16_f32 v134, v134, v136
	v_lshl_add_u64 v[138:139], v[138:139], 0, v[32:33]
	global_store_dword v[138:139], v134, off
	v_add_u32_e32 v134, s4, v55
	v_cvt_pk_bf16_f32 v136, v135, v137
	v_ashrrev_i32_e32 v135, 31, v134
	v_lshlrev_b64 v[134:135], 12, v[134:135]
	v_lshl_add_u64 v[134:135], s[62:63], 0, v[134:135]
	v_lshl_add_u64 v[134:135], v[134:135], 0, s[8:9]
	v_lshl_add_u64 v[134:135], v[134:135], 0, v[32:33]
	global_store_dword v[134:135], v136, off
	ds_read2_b32 v[134:135], v52 offset0:32 offset1:40
	ds_read2_b32 v[136:137], v52 offset0:97 offset1:105
	v_add_u32_e32 v138, s4, v56
	v_ashrrev_i32_e32 v139, 31, v138
	v_lshlrev_b64 v[138:139], 12, v[138:139]
	v_lshl_add_u64 v[138:139], s[62:63], 0, v[138:139]
	v_lshl_add_u64 v[138:139], v[138:139], 0, s[8:9]
	s_waitcnt lgkmcnt(0)
	v_cvt_pk_bf16_f32 v134, v134, v136
	v_lshl_add_u64 v[138:139], v[138:139], 0, v[32:33]
	global_store_dword v[138:139], v134, off
	v_add_u32_e32 v134, s4, v57
	v_cvt_pk_bf16_f32 v136, v135, v137
	v_ashrrev_i32_e32 v135, 31, v134
	v_lshlrev_b64 v[134:135], 12, v[134:135]
	v_lshl_add_u64 v[134:135], s[62:63], 0, v[134:135]
	v_lshl_add_u64 v[134:135], v[134:135], 0, s[8:9]
	v_lshl_add_u64 v[134:135], v[134:135], 0, v[32:33]
	global_store_dword v[134:135], v136, off
	ds_read2_b32 v[134:135], v52 offset0:48 offset1:56
	ds_read2_b32 v[136:137], v52 offset0:113 offset1:121
	v_add_u32_e32 v138, s4, v58
	v_ashrrev_i32_e32 v139, 31, v138
	v_lshlrev_b64 v[138:139], 12, v[138:139]
	v_lshl_add_u64 v[138:139], s[62:63], 0, v[138:139]
	v_lshl_add_u64 v[138:139], v[138:139], 0, s[8:9]
	s_waitcnt lgkmcnt(0)
	v_cvt_pk_bf16_f32 v134, v134, v136
	v_lshl_add_u64 v[138:139], v[138:139], 0, v[32:33]
	global_store_dword v[138:139], v134, off
	v_add_u32_e32 v134, s4, v59
	v_cvt_pk_bf16_f32 v136, v135, v137
	v_ashrrev_i32_e32 v135, 31, v134
	v_lshlrev_b64 v[134:135], 12, v[134:135]
	v_lshl_add_u64 v[134:135], s[62:63], 0, v[134:135]
	v_lshl_add_u64 v[134:135], v[134:135], 0, s[8:9]
	v_lshl_add_u64 v[134:135], v[134:135], 0, v[32:33]
	global_store_dword v[134:135], v136, off
	v_cmp_gt_i32_e32 vcc, s11, v63
	v_cmp_gt_u32_e64 s[36:37], s12, v62
	s_waitcnt vmcnt(23)
	v_mul_f32_e32 v16, v65, v16
	s_and_b64 s[36:37], s[36:37], vcc
	v_cndmask_b32_e64 v16, 0, v16, s[36:37]
	v_cmp_gt_u32_e64 s[36:37], s12, v64
	s_waitcnt vmcnt(22)
	v_mul_f32_e32 v17, v67, v17
	s_and_b64 s[36:37], s[36:37], vcc
	v_cndmask_b32_e64 v17, 0, v17, s[36:37]
	v_cmp_gt_u32_e64 s[36:37], s12, v66
	s_waitcnt vmcnt(21)
	v_mul_f32_e32 v18, v69, v18
	s_and_b64 s[36:37], s[36:37], vcc
	v_cndmask_b32_e64 v18, 0, v18, s[36:37]
	v_cmp_gt_u32_e64 s[36:37], s12, v68
	s_waitcnt vmcnt(20)
	v_mul_f32_e32 v19, v71, v19
	s_and_b64 s[36:37], s[36:37], vcc
	v_cndmask_b32_e64 v19, 0, v19, s[36:37]
	v_cmp_gt_u32_e64 s[36:37], s12, v70
	s_waitcnt vmcnt(19)
	v_mul_f32_e32 v20, v73, v20
	s_and_b64 s[36:37], s[36:37], vcc
	v_cndmask_b32_e64 v20, 0, v20, s[36:37]
	v_cmp_gt_u32_e64 s[36:37], s12, v72
	s_waitcnt vmcnt(18)
	v_mul_f32_e32 v21, v75, v21
	s_and_b64 s[36:37], s[36:37], vcc
	v_cndmask_b32_e64 v21, 0, v21, s[36:37]
	v_cmp_gt_u32_e64 s[36:37], s12, v74
	s_waitcnt vmcnt(17)
	v_mul_f32_e32 v22, v77, v22
	s_and_b64 s[36:37], s[36:37], vcc
	v_cndmask_b32_e64 v22, 0, v22, s[36:37]
	v_cmp_gt_u32_e64 s[36:37], s12, v76
	s_waitcnt vmcnt(16)
	v_mul_f32_e32 v23, v80, v23
	s_and_b64 s[36:37], s[36:37], vcc
	v_cndmask_b32_e64 v23, 0, v23, s[36:37]
	v_cmp_gt_u32_e64 s[36:37], s12, v78
	s_waitcnt vmcnt(15)
	v_mul_f32_e32 v24, v81, v24
	s_and_b64 s[36:37], s[36:37], vcc
	v_cndmask_b32_e64 v24, 0, v24, s[36:37]
	v_cmp_gt_u32_e64 s[36:37], s12, v79
	s_waitcnt vmcnt(14)
	v_mul_f32_e32 v25, v83, v25
	s_and_b64 s[36:37], s[36:37], vcc
	v_cndmask_b32_e64 v25, 0, v25, s[36:37]
	v_cmp_gt_u32_e64 s[36:37], s12, v82
	s_waitcnt vmcnt(13)
	v_mul_f32_e32 v26, v85, v26
	s_and_b64 s[36:37], s[36:37], vcc
	v_cndmask_b32_e64 v26, 0, v26, s[36:37]
	v_cmp_gt_u32_e64 s[36:37], s12, v84
	s_waitcnt vmcnt(12)
	v_mul_f32_e32 v27, v87, v27
	s_and_b64 s[36:37], s[36:37], vcc
	v_cndmask_b32_e64 v27, 0, v27, s[36:37]
	v_cmp_gt_u32_e64 s[36:37], s12, v86
	s_waitcnt vmcnt(11)
	v_mul_f32_e32 v28, v89, v28
	s_and_b64 s[36:37], s[36:37], vcc
	v_cndmask_b32_e64 v28, 0, v28, s[36:37]
	v_cmp_gt_u32_e64 s[36:37], s12, v88
	s_waitcnt vmcnt(10)
	v_mul_f32_e32 v29, v91, v29
	s_and_b64 s[36:37], s[36:37], vcc
	v_cndmask_b32_e64 v29, 0, v29, s[36:37]
	v_cmp_gt_u32_e64 s[36:37], s12, v90
	s_waitcnt vmcnt(9)
	v_mul_f32_e32 v30, v93, v30
	s_and_b64 s[36:37], s[36:37], vcc
	v_cndmask_b32_e64 v30, 0, v30, s[36:37]
	v_cmp_gt_u32_e64 s[36:37], s12, v92
	s_waitcnt vmcnt(8)
	v_mul_f32_e32 v31, v94, v31
	s_and_b64 vcc, s[36:37], vcc
	v_cndmask_b32_e32 v31, 0, v31, vcc
	s_barrier

; DEVI int obid() { int b = __builtin_amdgcn_workgroup_id_x(); asm volatile("" : "+s"(b)); return b; }
; DEVI unsigned pk_bf16(float lo, float hi) { unsigned r; asm("v_cvt_pk_bf16_f32 %0, %1, %2" : "=v"(r) : "v"(lo), "v"(hi)); return r; }
; DEVI void cvt_job(LAS float* tile, const float* src, int srcK, int srcN, bf16_t* dst, int dstLd, int dstRows, int dstCol0, int mode, const float* gk = nullptr) {
;     ...
;         for (int i = 0; i < 16; ++i) { const int k = kap0 + ty + 8 * i - dstCol0; const int kc = k < 0 ? 0 : (k < srcK ? k : srcK - 1);
;             raw[i] = __builtin_nontemporal_load(src + (size_t)kc * srcN + nc); }
;         if (gk) {
; #pragma unroll
;             for (int i = 0; i < 16; ++i) { const int k = kap0 + ty + 8 * i - dstCol0; const int kc = k < 0 ? 0 : (k < srcK ? k : srcK - 1); gs[i] = gk[kc]; }
;         } else {
; #pragma unroll
;             for (int i = 0; i < 16; ++i) gs[i] = 1.0f;
;         }
; #pragma unroll
;         for (int i = 0; i < 16; ++i) { const int k = kap0 + ty + 8 * i - dstCol0; regs[i] = (nok && k >= 0 && k < srcK) ? raw[i] * gs[i] : 0.f; }
;     ...
;         for (int i = 0; i < 8; ++i) { const int row = ty + 8 * i;
;             const float lo = tile[(2 * tx) * 65 + row], hi = tile[(2 * tx + 1) * 65 + row];
;             *(unsigned*)(dst + (size_t)(rho0 + row) * dstLd + kap0 + 2 * tx) = pk_bf16(lo, hi); }
;         __syncthreads();
;     };
;     const int G = gridDim.x;
;     int t = obid();
;     if (t < ntot) gl(t, regsA);
;     if (t + G < ntot) gl(t + G, regsB);
;     while (t < ntot) {
;         emit(t, regsA);
;         if (t + G < ntot) emit(t + G, regsB);
;         t += 2 * G;
.LBB0_1529:
.LBB0_1530:
	s_mul_hi_i32 s8, s4, 0x2e8ba2e9
	s_lshr_b32 s9, s8, 31
	s_ashr_i32 s8, s8, 4
	s_add_i32 s8, s8, s9
	s_mul_i32 s9, s8, 0x3ffff50
	s_add_i32 s9, s7, s9
	s_and_b32 s9, s9, 0x3fffffc
	s_or_b32 s9, s9, s6
	s_lshl_b32 s14, s9, 6
	ds_read2_b32 v[134:135], v52 offset0:65 offset1:73
	ds_read2_b32 v[136:137], v52 offset1:8
	v_add_u32_e32 v138, s14, v51
	s_lshl_b32 s8, s8, 7
	v_ashrrev_i32_e32 v139, 31, v138
	s_ashr_i32 s9, s8, 31
	v_lshlrev_b64 v[138:139], 12, v[138:139]
	v_lshl_add_u64 v[138:139], s[62:63], 0, v[138:139]
	s_lshl_b64 s[8:9], s[8:9], 1
	v_lshl_add_u64 v[138:139], v[138:139], 0, s[8:9]
	s_waitcnt lgkmcnt(0)
	v_cvt_pk_bf16_f32 v134, v136, v134
	v_lshl_add_u64 v[138:139], v[138:139], 0, v[32:33]
	global_store_dword v[138:139], v134, off
	v_add_u32_e32 v134, s14, v53
	v_cvt_pk_bf16_f32 v136, v137, v135
	v_ashrrev_i32_e32 v135, 31, v134
	v_lshlrev_b64 v[134:135], 12, v[134:135]
	v_lshl_add_u64 v[134:135], s[62:63], 0, v[134:135]
	v_lshl_add_u64 v[134:135], v[134:135], 0, s[8:9]
	v_lshl_add_u64 v[134:135], v[134:135], 0, v[32:33]
	global_store_dword v[134:135], v136, off
	ds_read2_b32 v[134:135], v52 offset0:16 offset1:24
	ds_read2_b32 v[136:137], v52 offset0:81 offset1:89
	v_add_u32_e32 v138, s14, v54
	v_ashrrev_i32_e32 v139, 31, v138
	v_lshlrev_b64 v[138:139], 12, v[138:139]
	v_lshl_add_u64 v[138:139], s[62:63], 0, v[138:139]
	v_lshl_add_u64 v[138:139], v[138:139], 0, s[8:9]
	s_waitcnt lgkmcnt(0)
	v_cvt_pk_bf16_f32 v134, v134, v136
	v_lshl_add_u64 v[138:139], v[138:139], 0, v[32:33]
	global_store_dword v[138:139], v134, off
	v_add_u32_e32 v134, s14, v55
	v_cvt_pk_bf16_f32 v136, v135, v137
	v_ashrrev_i32_e32 v135, 31, v134
	v_lshlrev_b64 v[134:135], 12, v[134:135]
	v_lshl_add_u64 v[134:135], s[62:63], 0, v[134:135]
	v_lshl_add_u64 v[134:135], v[134:135], 0, s[8:9]
	v_lshl_add_u64 v[134:135], v[134:135], 0, v[32:33]
	global_store_dword v[134:135], v136, off
	ds_read2_b32 v[134:135], v52 offset0:32 offset1:40
	ds_read2_b32 v[136:137], v52 offset0:97 offset1:105
	v_add_u32_e32 v138, s14, v56
	v_ashrrev_i32_e32 v139, 31, v138
	v_lshlrev_b64 v[138:139], 12, v[138:139]
	v_lshl_add_u64 v[138:139], s[62:63], 0, v[138:139]
	v_lshl_add_u64 v[138:139], v[138:139], 0, s[8:9]
	s_waitcnt lgkmcnt(0)
	v_cvt_pk_bf16_f32 v134, v134, v136
	v_lshl_add_u64 v[138:139], v[138:139], 0, v[32:33]
	global_store_dword v[138:139], v134, off
	v_add_u32_e32 v134, s14, v57
	v_cvt_pk_bf16_f32 v136, v135, v137
	v_ashrrev_i32_e32 v135, 31, v134
	v_lshlrev_b64 v[134:135], 12, v[134:135]
	v_lshl_add_u64 v[134:135], s[62:63], 0, v[134:135]
	v_lshl_add_u64 v[134:135], v[134:135], 0, s[8:9]
	v_lshl_add_u64 v[134:135], v[134:135], 0, v[32:33]
	global_store_dword v[134:135], v136, off
	ds_read2_b32 v[134:135], v52 offset0:48 offset1:56
	ds_read2_b32 v[136:137], v52 offset0:113 offset1:121
	v_add_u32_e32 v138, s14, v58
	v_ashrrev_i32_e32 v139, 31, v138
	v_lshlrev_b64 v[138:139], 12, v[138:139]
	v_lshl_add_u64 v[138:139], s[62:63], 0, v[138:139]
	v_lshl_add_u64 v[138:139], v[138:139], 0, s[8:9]
	s_waitcnt lgkmcnt(0)
	v_cvt_pk_bf16_f32 v134, v134, v136
	v_lshl_add_u64 v[138:139], v[138:139], 0, v[32:33]
	global_store_dword v[138:139], v134, off
	v_add_u32_e32 v134, s14, v59
	v_cvt_pk_bf16_f32 v136, v135, v137
	v_ashrrev_i32_e32 v135, 31, v134
	v_lshlrev_b64 v[134:135], 12, v[134:135]
	v_lshl_add_u64 v[134:135], s[62:63], 0, v[134:135]
	v_lshl_add_u64 v[134:135], v[134:135], 0, s[8:9]
	s_add_i32 s8, s33, s4
	v_lshl_add_u64 v[134:135], v[134:135], 0, v[32:33]
	s_cmpk_gt_i32 s8, 0x57f
	global_store_dword v[134:135], v136, off
	s_cselect_b32 s98, 1, 0
	v_cmp_gt_i32_e32 vcc, s11, v63
	v_cmp_gt_u32_e64 s[36:37], s12, v62
	s_waitcnt vmcnt(23)
	v_mul_f32_e32 v0, v65, v0
	s_and_b64 s[36:37], s[36:37], vcc
	v_cndmask_b32_e64 v0, 0, v0, s[36:37]
	v_cmp_gt_u32_e64 s[36:37], s12, v64
	s_waitcnt vmcnt(22)
	v_mul_f32_e32 v1, v67, v1
	s_and_b64 s[36:37], s[36:37], vcc
	v_cndmask_b32_e64 v1, 0, v1, s[36:37]
	v_cmp_gt_u32_e64 s[36:37], s12, v66
	s_waitcnt vmcnt(21)
	v_mul_f32_e32 v2, v69, v2
	s_and_b64 s[36:37], s[36:37], vcc
	v_cndmask_b32_e64 v2, 0, v2, s[36:37]
	v_cmp_gt_u32_e64 s[36:37], s12, v68
	s_waitcnt vmcnt(20)
	v_mul_f32_e32 v3, v71, v3
	s_and_b64 s[36:37], s[36:37], vcc
	v_cndmask_b32_e64 v3, 0, v3, s[36:37]
	v_cmp_gt_u32_e64 s[36:37], s12, v70
	s_waitcnt vmcnt(19)
	v_mul_f32_e32 v4, v73, v4
	s_and_b64 s[36:37], s[36:37], vcc
	v_cndmask_b32_e64 v4, 0, v4, s[36:37]
	v_cmp_gt_u32_e64 s[36:37], s12, v72
	s_waitcnt vmcnt(18)
	v_mul_f32_e32 v5, v75, v5
	s_and_b64 s[36:37], s[36:37], vcc
	v_cndmask_b32_e64 v5, 0, v5, s[36:37]
	v_cmp_gt_u32_e64 s[36:37], s12, v74
	s_waitcnt vmcnt(17)
	v_mul_f32_e32 v6, v77, v6
	s_and_b64 s[36:37], s[36:37], vcc
	v_cndmask_b32_e64 v6, 0, v6, s[36:37]
	v_cmp_gt_u32_e64 s[36:37], s12, v76
	s_waitcnt vmcnt(16)
	v_mul_f32_e32 v7, v80, v7
	s_and_b64 s[36:37], s[36:37], vcc
	v_cndmask_b32_e64 v7, 0, v7, s[36:37]
	v_cmp_gt_u32_e64 s[36:37], s12, v78
	s_waitcnt vmcnt(15)
	v_mul_f32_e32 v8, v81, v8
	s_and_b64 s[36:37], s[36:37], vcc
	v_cndmask_b32_e64 v8, 0, v8, s[36:37]
	v_cmp_gt_u32_e64 s[36:37], s12, v79
	s_waitcnt vmcnt(14)
	v_mul_f32_e32 v9, v83, v9
	s_and_b64 s[36:37], s[36:37], vcc
	v_cndmask_b32_e64 v9, 0, v9, s[36:37]
	v_cmp_gt_u32_e64 s[36:37], s12, v82
	s_waitcnt vmcnt(13)
	v_mul_f32_e32 v10, v85, v10
	s_and_b64 s[36:37], s[36:37], vcc
	v_cndmask_b32_e64 v10, 0, v10, s[36:37]
	v_cmp_gt_u32_e64 s[36:37], s12, v84
	s_waitcnt vmcnt(12)
	v_mul_f32_e32 v11, v87, v11
	s_and_b64 s[36:37], s[36:37], vcc
	v_cndmask_b32_e64 v11, 0, v11, s[36:37]
	v_cmp_gt_u32_e64 s[36:37], s12, v86
	s_waitcnt vmcnt(11)
	v_mul_f32_e32 v12, v89, v12
	s_and_b64 s[36:37], s[36:37], vcc
	v_cndmask_b32_e64 v12, 0, v12, s[36:37]
	v_cmp_gt_u32_e64 s[36:37], s12, v88
	s_waitcnt vmcnt(10)
	v_mul_f32_e32 v13, v91, v13
	s_and_b64 s[36:37], s[36:37], vcc
	v_cndmask_b32_e64 v13, 0, v13, s[36:37]
	v_cmp_gt_u32_e64 s[36:37], s12, v90
	s_waitcnt vmcnt(9)
	v_mul_f32_e32 v14, v93, v14
	s_and_b64 s[36:37], s[36:37], vcc
	v_cndmask_b32_e64 v14, 0, v14, s[36:37]
	v_cmp_gt_u32_e64 s[36:37], s12, v92
	s_waitcnt vmcnt(8)
	v_mul_f32_e32 v15, v94, v15
	s_and_b64 vcc, s[36:37], vcc
	v_cndmask_b32_e32 v15, 0, v15, vcc
	s_cmp_lg_u32 s98, 0
	s_barrier
; DEVI void cvt_job(LAS float* tile, const float* src, int srcK, int srcN, bf16_t* dst, int dstLd, int dstRows, int dstCol0, int mode, const float* gk = nullptr) {
;     ...
;     auto gl = [&](int t, float (&regs)[16]) {
;         int rho0, kap0, n0; coords(t, rho0, kap0, n0);
;         const int n = n0 + tx, nc = n < srcN ? n : srcN - 1;
;         const bool nok = n < srcN;
;         float raw[16], gs[16];
; #pragma unroll
;         for (int i = 0; i < 16; ++i) { const int k = kap0 + ty + 8 * i - dstCol0; const int kc = k < 0 ? 0 : (k < srcK ? k : srcK - 1);
;             raw[i] = __builtin_nontemporal_load(src + (size_t)kc * srcN + nc); }
;         if (gk) {
; #pragma unroll
;             for (int i = 0; i < 16; ++i) { const int k = kap0 + ty + 8 * i - dstCol0; const int kc = k < 0 ? 0 : (k < srcK ? k : srcK - 1); gs[i] = gk[kc]; }
;         } else {
; #pragma unroll
;             for (int i = 0; i < 16; ++i) gs[i] = 1.0f;
;         }
;     ...
;     auto emit = [&](int t, float (&regs)[16]) {
; #pragma unroll
;         for (int i = 0; i < 16; ++i) tile[(ty + 8 * i) * 65 + tx] = regs[i];
;         __syncthreads();
;         int rho0, kap0, n0; coords(t, rho0, kap0, n0);
;         const int tn = t + 2 * gridDim.x;
;         if (tn < ntot) gl(tn, regs);
	s_cbranch_scc1 .LBB0_1524
	s_add_i32 s4, s18, s4
	s_cmpk_gt_i32 s4, 0x57f
	ds_write_b32 v60, v16
	ds_write_b32 v60, v17 offset:2080
	ds_write_b32 v60, v18 offset:4160
	ds_write_b32 v60, v19 offset:6240
	ds_write_b32 v60, v20 offset:8320
	ds_write_b32 v60, v21 offset:10400
	ds_write_b32 v60, v22 offset:12480
	ds_write_b32 v60, v23 offset:14560
	ds_write_b32 v60, v24 offset:16640
	ds_write_b32 v60, v25 offset:18720
	ds_write_b32 v60, v26 offset:20800
	ds_write_b32 v60, v27 offset:22880
	ds_write_b32 v60, v28 offset:24960
	ds_write_b32 v60, v29 offset:27040
	ds_write_b32 v60, v30 offset:29120
	ds_write_b32 v60, v31 offset:31200
	s_waitcnt lgkmcnt(0)
	s_barrier
	s_cbranch_scc1 .LBB0_1523
	s_mul_hi_i32 s4, s4, 0x2e8ba2e9
	s_lshr_b32 s9, s4, 31
	s_ashr_i32 s4, s4, 4
	s_add_i32 s4, s4, s9
	s_mul_i32 s9, s4, 0x3ffff50
	s_add_i32 s14, s96, s7
	s_add_i32 s14, s14, s9
	s_and_b32 s9, s14, 0x3fffffc
	s_or_b32 s9, s9, s5
	s_lshl_b32 s9, s9, 6
	s_ashr_i32 s14, s9, 1
	s_and_b32 s14, s14, 0xffffff80
	s_and_b32 s9, s9, 64
	s_or_b32 s9, s9, s14
	v_or_b32_e32 v63, s9, v50
	v_min_i32_e32 v16, 0x15ff, v63
	v_lshl_add_u32 v62, s4, 7, v51
	v_ashrrev_i32_e32 v17, 31, v16
	v_lshl_add_u64 v[94:95], v[16:17], 2, s[0:1]
	v_med3_i32 v16, v62, 0, v61
	v_mad_u64_u32 v[18:19], s[14:15], v16, s10, v[94:95]
	v_add_u32_e32 v64, 8, v62
	global_load_dword v65, v[18:19], off nt
	v_med3_i32 v18, v64, 0, v61
	v_mad_u64_u32 v[20:21], s[14:15], v18, s10, v[94:95]
	v_add_u32_e32 v66, 16, v62
	global_load_dword v67, v[20:21], off nt
	v_med3_i32 v20, v66, 0, v61
	v_mad_u64_u32 v[22:23], s[14:15], v20, s10, v[94:95]
	v_add_u32_e32 v68, 24, v62
	global_load_dword v69, v[22:23], off nt
	v_med3_i32 v22, v68, 0, v61
	v_mad_u64_u32 v[24:25], s[14:15], v22, s10, v[94:95]
	v_add_u32_e32 v70, 32, v62
	global_load_dword v71, v[24:25], off nt
	v_med3_i32 v24, v70, 0, v61
	v_mad_u64_u32 v[26:27], s[14:15], v24, s10, v[94:95]
	v_add_u32_e32 v72, 40, v62
	global_load_dword v73, v[26:27], off nt
	v_med3_i32 v26, v72, 0, v61
	v_mad_u64_u32 v[28:29], s[14:15], v26, s10, v[94:95]
	v_add_u32_e32 v74, 48, v62
	global_load_dword v75, v[28:29], off nt
	v_med3_i32 v28, v74, 0, v61
	v_mad_u64_u32 v[30:31], s[14:15], v28, s10, v[94:95]
	v_add_u32_e32 v76, 56, v62
	global_load_dword v77, v[30:31], off nt
	v_med3_i32 v30, v76, 0, v61
	v_mad_u64_u32 v[34:35], s[14:15], v30, s10, v[94:95]
	v_add_u32_e32 v78, 64, v62
	global_load_dword v80, v[34:35], off nt
	v_med3_i32 v34, v78, 0, v61
	v_mad_u64_u32 v[36:37], s[14:15], v34, s10, v[94:95]
	v_add_u32_e32 v79, 0x48, v62
	global_load_dword v81, v[36:37], off nt
	v_med3_i32 v36, v79, 0, v61
	v_mad_u64_u32 v[38:39], s[14:15], v36, s10, v[94:95]
	v_add_u32_e32 v82, 0x50, v62
	global_load_dword v83, v[38:39], off nt
	v_med3_i32 v38, v82, 0, v61
	v_mad_u64_u32 v[40:41], s[14:15], v38, s10, v[94:95]
	v_add_u32_e32 v84, 0x58, v62
	global_load_dword v85, v[40:41], off nt
	v_med3_i32 v40, v84, 0, v61
	v_mad_u64_u32 v[42:43], s[14:15], v40, s10, v[94:95]
	v_add_u32_e32 v86, 0x60, v62
	global_load_dword v87, v[42:43], off nt
	v_med3_i32 v42, v86, 0, v61
	v_mad_u64_u32 v[44:45], s[14:15], v42, s10, v[94:95]
	v_add_u32_e32 v88, 0x68, v62
	global_load_dword v89, v[44:45], off nt
	v_med3_i32 v44, v88, 0, v61
	v_mad_u64_u32 v[46:47], s[14:15], v44, s10, v[94:95]
	v_add_u32_e32 v90, 0x70, v62
	global_load_dword v91, v[46:47], off nt
	v_med3_i32 v46, v90, 0, v61
	v_mad_u64_u32 v[48:49], s[14:15], v46, s10, v[94:95]
	v_add_u32_e32 v92, 0x78, v62
	global_load_dword v93, v[48:49], off nt
	v_med3_i32 v48, v92, 0, v61
	v_mad_u64_u32 v[94:95], s[14:15], v48, s10, v[94:95]
	global_load_dword v94, v[94:95], off nt
	v_readlane_b32 s14, v240, 48
	v_readlane_b32 s15, v240, 49
	s_and_b64 vcc, exec, s[14:15]
	s_cbranch_vccz .LBB0_1521
	v_mov_b32_e32 v31, 1.0
	v_mov_b32_e32 v30, 1.0
	v_mov_b32_e32 v29, 1.0
	v_mov_b32_e32 v28, 1.0
	v_mov_b32_e32 v27, 1.0
	v_mov_b32_e32 v26, 1.0
	v_mov_b32_e32 v25, 1.0
	v_mov_b32_e32 v24, 1.0
	v_mov_b32_e32 v23, 1.0
	v_mov_b32_e32 v22, 1.0
	v_mov_b32_e32 v21, 1.0
	v_mov_b32_e32 v20, 1.0
	v_mov_b32_e32 v19, 1.0
	v_mov_b32_e32 v18, 1.0
	v_mov_b32_e32 v17, 1.0
	v_mov_b32_e32 v16, 1.0
	s_branch .LBB0_1522

; DEVI unsigned pk_bf16(float lo, float hi) { unsigned r; asm("v_cvt_pk_bf16_f32 %0, %1, %2" : "=v"(r) : "v"(lo), "v"(hi)); return r; }
; DEVI void cvt_job(LAS float* tile, const float* src, int srcK, int srcN, bf16_t* dst, int dstLd, int dstRows, int dstCol0, int mode, const float* gk = nullptr) {
;     ...
;         for (int i = 0; i < 16; ++i) { const int k = kap0 + ty + 8 * i - dstCol0; const int kc = k < 0 ? 0 : (k < srcK ? k : srcK - 1);
;             raw[i] = __builtin_nontemporal_load(src + (size_t)kc * srcN + nc); }
;         if (gk) {
; #pragma unroll
;             for (int i = 0; i < 16; ++i) { const int k = kap0 + ty + 8 * i - dstCol0; const int kc = k < 0 ? 0 : (k < srcK ? k : srcK - 1); gs[i] = gk[kc]; }
;         } else {
; #pragma unroll
;             for (int i = 0; i < 16; ++i) gs[i] = 1.0f;
;         }
; #pragma unroll
;         for (int i = 0; i < 16; ++i) { const int k = kap0 + ty + 8 * i - dstCol0; regs[i] = (nok && k >= 0 && k < srcK) ? raw[i] * gs[i] : 0.f; }
;     ...
;         for (int i = 0; i < 8; ++i) { const int row = ty + 8 * i;
;             const float lo = tile[(2 * tx) * 65 + row], hi = tile[(2 * tx + 1) * 65 + row];
;             *(unsigned*)(dst + (size_t)(rho0 + row) * dstLd + kap0 + 2 * tx) = pk_bf16(lo, hi); }
.LBB0_1547:
.LBB0_1548:
	s_mul_hi_i32 s4, s8, 0x2e8ba2e9
	s_lshr_b32 s8, s4, 31
	s_ashr_i32 s4, s4, 4
	s_add_i32 s8, s4, s8
	s_mul_i32 s4, s8, 0x3ffff50
	s_add_i32 s9, s30, s7
	s_add_i32 s9, s9, s4
	s_and_b32 s4, s9, 0x3fffffc
	s_or_b32 s4, s4, s5
	s_lshl_b32 s4, s4, 6
	s_bitset1_b32 s4, 7
	ds_read2_b32 v[134:135], v52 offset0:65 offset1:73
	ds_read2_b32 v[136:137], v52 offset1:8
	v_add_u32_e32 v138, s4, v51
	s_lshl_b32 s8, s8, 7
	v_ashrrev_i32_e32 v139, 31, v138
	s_ashr_i32 s9, s8, 31
	v_lshlrev_b64 v[138:139], 12, v[138:139]
	v_lshl_add_u64 v[138:139], s[62:63], 0, v[138:139]
	s_lshl_b64 s[8:9], s[8:9], 1
	v_lshl_add_u64 v[138:139], v[138:139], 0, s[8:9]
	s_waitcnt lgkmcnt(0)
	v_cvt_pk_bf16_f32 v134, v136, v134
	v_lshl_add_u64 v[138:139], v[138:139], 0, v[32:33]
	global_store_dword v[138:139], v134, off
	v_add_u32_e32 v134, s4, v53
	v_cvt_pk_bf16_f32 v136, v137, v135
	v_ashrrev_i32_e32 v135, 31, v134
	v_lshlrev_b64 v[134:135], 12, v[134:135]
	v_lshl_add_u64 v[134:135], s[62:63], 0, v[134:135]
	v_lshl_add_u64 v[134:135], v[134:135], 0, s[8:9]
	v_lshl_add_u64 v[134:135], v[134:135], 0, v[32:33]
	global_store_dword v[134:135], v136, off
	ds_read2_b32 v[134:135], v52 offset0:16 offset1:24
	ds_read2_b32 v[136:137], v52 offset0:81 offset1:89
	v_add_u32_e32 v138, s4, v54
	v_ashrrev_i32_e32 v139, 31, v138
	v_lshlrev_b64 v[138:139], 12, v[138:139]
	v_lshl_add_u64 v[138:139], s[62:63], 0, v[138:139]
	v_lshl_add_u64 v[138:139], v[138:139], 0, s[8:9]
	s_waitcnt lgkmcnt(0)
	v_cvt_pk_bf16_f32 v134, v134, v136
	v_lshl_add_u64 v[138:139], v[138:139], 0, v[32:33]
	global_store_dword v[138:139], v134, off
	v_add_u32_e32 v134, s4, v55
	v_cvt_pk_bf16_f32 v136, v135, v137
	v_ashrrev_i32_e32 v135, 31, v134
	v_lshlrev_b64 v[134:135], 12, v[134:135]
	v_lshl_add_u64 v[134:135], s[62:63], 0, v[134:135]
	v_lshl_add_u64 v[134:135], v[134:135], 0, s[8:9]
	v_lshl_add_u64 v[134:135], v[134:135], 0, v[32:33]
	global_store_dword v[134:135], v136, off
	ds_read2_b32 v[134:135], v52 offset0:32 offset1:40
	ds_read2_b32 v[136:137], v52 offset0:97 offset1:105
	v_add_u32_e32 v138, s4, v56
	v_ashrrev_i32_e32 v139, 31, v138
	v_lshlrev_b64 v[138:139], 12, v[138:139]
	v_lshl_add_u64 v[138:139], s[62:63], 0, v[138:139]
	v_lshl_add_u64 v[138:139], v[138:139], 0, s[8:9]
	s_waitcnt lgkmcnt(0)
	v_cvt_pk_bf16_f32 v134, v134, v136
	v_lshl_add_u64 v[138:139], v[138:139], 0, v[32:33]
	global_store_dword v[138:139], v134, off
	v_add_u32_e32 v134, s4, v57
	v_cvt_pk_bf16_f32 v136, v135, v137
	v_ashrrev_i32_e32 v135, 31, v134
	v_lshlrev_b64 v[134:135], 12, v[134:135]
	v_lshl_add_u64 v[134:135], s[62:63], 0, v[134:135]
	v_lshl_add_u64 v[134:135], v[134:135], 0, s[8:9]
	v_lshl_add_u64 v[134:135], v[134:135], 0, v[32:33]
	global_store_dword v[134:135], v136, off
	ds_read2_b32 v[134:135], v52 offset0:48 offset1:56
	ds_read2_b32 v[136:137], v52 offset0:113 offset1:121
	v_add_u32_e32 v138, s4, v58
	v_ashrrev_i32_e32 v139, 31, v138
	v_lshlrev_b64 v[138:139], 12, v[138:139]
	v_lshl_add_u64 v[138:139], s[62:63], 0, v[138:139]
	v_lshl_add_u64 v[138:139], v[138:139], 0, s[8:9]
	s_waitcnt lgkmcnt(0)
	v_cvt_pk_bf16_f32 v134, v134, v136
	v_lshl_add_u64 v[138:139], v[138:139], 0, v[32:33]
	global_store_dword v[138:139], v134, off
	v_add_u32_e32 v134, s4, v59
	v_cvt_pk_bf16_f32 v136, v135, v137
	v_ashrrev_i32_e32 v135, 31, v134
	v_lshlrev_b64 v[134:135], 12, v[134:135]
	v_lshl_add_u64 v[134:135], s[62:63], 0, v[134:135]
	v_lshl_add_u64 v[134:135], v[134:135], 0, s[8:9]
	v_lshl_add_u64 v[134:135], v[134:135], 0, v[32:33]
	global_store_dword v[134:135], v136, off
	v_cmp_gt_i32_e32 vcc, s11, v63
	v_cmp_gt_u32_e64 s[36:37], s12, v62
	s_waitcnt vmcnt(23)
	v_mul_f32_e32 v16, v65, v16
	s_and_b64 s[36:37], s[36:37], vcc
	v_cndmask_b32_e64 v16, 0, v16, s[36:37]
	v_cmp_gt_u32_e64 s[36:37], s12, v64
	s_waitcnt vmcnt(22)
	v_mul_f32_e32 v17, v67, v17
	s_and_b64 s[36:37], s[36:37], vcc
	v_cndmask_b32_e64 v17, 0, v17, s[36:37]
	v_cmp_gt_u32_e64 s[36:37], s12, v66
	s_waitcnt vmcnt(21)
	v_mul_f32_e32 v18, v69, v18
	s_and_b64 s[36:37], s[36:37], vcc
	v_cndmask_b32_e64 v18, 0, v18, s[36:37]
	v_cmp_gt_u32_e64 s[36:37], s12, v68
	s_waitcnt vmcnt(20)
	v_mul_f32_e32 v19, v71, v19
	s_and_b64 s[36:37], s[36:37], vcc
	v_cndmask_b32_e64 v19, 0, v19, s[36:37]
	v_cmp_gt_u32_e64 s[36:37], s12, v70
	s_waitcnt vmcnt(19)
	v_mul_f32_e32 v20, v73, v20
	s_and_b64 s[36:37], s[36:37], vcc
	v_cndmask_b32_e64 v20, 0, v20, s[36:37]
	v_cmp_gt_u32_e64 s[36:37], s12, v72
	s_waitcnt vmcnt(18)
	v_mul_f32_e32 v21, v75, v21
	s_and_b64 s[36:37], s[36:37], vcc
	v_cndmask_b32_e64 v21, 0, v21, s[36:37]
	v_cmp_gt_u32_e64 s[36:37], s12, v74
	s_waitcnt vmcnt(17)
	v_mul_f32_e32 v22, v77, v22
	s_and_b64 s[36:37], s[36:37], vcc
	v_cndmask_b32_e64 v22, 0, v22, s[36:37]
	v_cmp_gt_u32_e64 s[36:37], s12, v76
	s_waitcnt vmcnt(16)
	v_mul_f32_e32 v23, v80, v23
	s_and_b64 s[36:37], s[36:37], vcc
	v_cndmask_b32_e64 v23, 0, v23, s[36:37]
	v_cmp_gt_u32_e64 s[36:37], s12, v78
	s_waitcnt vmcnt(15)
	v_mul_f32_e32 v24, v81, v24
	s_and_b64 s[36:37], s[36:37], vcc
	v_cndmask_b32_e64 v24, 0, v24, s[36:37]
	v_cmp_gt_u32_e64 s[36:37], s12, v79
	s_waitcnt vmcnt(14)
	v_mul_f32_e32 v25, v83, v25
	s_and_b64 s[36:37], s[36:37], vcc
	v_cndmask_b32_e64 v25, 0, v25, s[36:37]
	v_cmp_gt_u32_e64 s[36:37], s12, v82
	s_waitcnt vmcnt(13)
	v_mul_f32_e32 v26, v85, v26
	s_and_b64 s[36:37], s[36:37], vcc
	v_cndmask_b32_e64 v26, 0, v26, s[36:37]
	v_cmp_gt_u32_e64 s[36:37], s12, v84
	s_waitcnt vmcnt(12)
	v_mul_f32_e32 v27, v87, v27
	s_and_b64 s[36:37], s[36:37], vcc
	v_cndmask_b32_e64 v27, 0, v27, s[36:37]
	v_cmp_gt_u32_e64 s[36:37], s12, v86
	s_waitcnt vmcnt(11)
	v_mul_f32_e32 v28, v89, v28
	s_and_b64 s[36:37], s[36:37], vcc
	v_cndmask_b32_e64 v28, 0, v28, s[36:37]
	v_cmp_gt_u32_e64 s[36:37], s12, v88
	s_waitcnt vmcnt(10)
	v_mul_f32_e32 v29, v91, v29
	s_and_b64 s[36:37], s[36:37], vcc
	v_cndmask_b32_e64 v29, 0, v29, s[36:37]
	v_cmp_gt_u32_e64 s[36:37], s12, v90
	s_waitcnt vmcnt(9)
	v_mul_f32_e32 v30, v93, v30
	s_and_b64 s[36:37], s[36:37], vcc
	v_cndmask_b32_e64 v30, 0, v30, s[36:37]
	v_cmp_gt_u32_e64 s[36:37], s12, v92
	s_waitcnt vmcnt(8)
	v_mul_f32_e32 v31, v94, v31
	s_and_b64 vcc, s[36:37], vcc
	v_cndmask_b32_e32 v31, 0, v31, vcc
	s_barrier

; DEVI int obid() { int b = __builtin_amdgcn_workgroup_id_x(); asm volatile("" : "+s"(b)); return b; }
; DEVI unsigned pk_bf16(float lo, float hi) { unsigned r; asm("v_cvt_pk_bf16_f32 %0, %1, %2" : "=v"(r) : "v"(lo), "v"(hi)); return r; }
; DEVI void cvt_job(LAS float* tile, const float* src, int srcK, int srcN, bf16_t* dst, int dstLd, int dstRows, int dstCol0, int mode, const float* gk = nullptr) {
;     ...
;         for (int i = 0; i < 16; ++i) { const int k = kap0 + ty + 8 * i - dstCol0; const int kc = k < 0 ? 0 : (k < srcK ? k : srcK - 1);
;             raw[i] = __builtin_nontemporal_load(src + (size_t)kc * srcN + nc); }
;         if (gk) {
; #pragma unroll
;             for (int i = 0; i < 16; ++i) { const int k = kap0 + ty + 8 * i - dstCol0; const int kc = k < 0 ? 0 : (k < srcK ? k : srcK - 1); gs[i] = gk[kc]; }
;         } else {
; #pragma unroll
;             for (int i = 0; i < 16; ++i) gs[i] = 1.0f;
;         }
; #pragma unroll
;         for (int i = 0; i < 16; ++i) { const int k = kap0 + ty + 8 * i - dstCol0; regs[i] = (nok && k >= 0 && k < srcK) ? raw[i] * gs[i] : 0.f; }
;     ...
;         for (int i = 0; i < 8; ++i) { const int row = ty + 8 * i;
;             const float lo = tile[(2 * tx) * 65 + row], hi = tile[(2 * tx + 1) * 65 + row];
;             *(unsigned*)(dst + (size_t)(rho0 + row) * dstLd + kap0 + 2 * tx) = pk_bf16(lo, hi); }
;         __syncthreads();
;     };
;     const int G = gridDim.x;
;     int t = obid();
;     if (t < ntot) gl(t, regsA);
;     if (t + G < ntot) gl(t + G, regsB);
;     while (t < ntot) {
;         emit(t, regsA);
;         if (t + G < ntot) emit(t + G, regsB);
;         t += 2 * G;
.LBB0_1554:
.LBB0_1555:
	s_mul_hi_i32 s8, s4, 0x2e8ba2e9
	s_lshr_b32 s9, s8, 31
	s_ashr_i32 s8, s8, 4
	s_add_i32 s8, s8, s9
	s_mul_i32 s9, s8, 0x3ffff50
	s_add_i32 s9, s7, s9
	s_and_b32 s9, s9, 0x3fffffc
	s_or_b32 s9, s9, s6
	s_lshl_b32 s14, s9, 6
	s_bitset1_b32 s14, 7
	ds_read2_b32 v[134:135], v52 offset0:65 offset1:73
	ds_read2_b32 v[136:137], v52 offset1:8
	v_add_u32_e32 v138, s14, v51
	s_lshl_b32 s8, s8, 7
	v_ashrrev_i32_e32 v139, 31, v138
	s_ashr_i32 s9, s8, 31
	v_lshlrev_b64 v[138:139], 12, v[138:139]
	v_lshl_add_u64 v[138:139], s[62:63], 0, v[138:139]
	s_lshl_b64 s[8:9], s[8:9], 1
	v_lshl_add_u64 v[138:139], v[138:139], 0, s[8:9]
	s_waitcnt lgkmcnt(0)
	v_cvt_pk_bf16_f32 v134, v136, v134
	v_lshl_add_u64 v[138:139], v[138:139], 0, v[32:33]
	global_store_dword v[138:139], v134, off
	v_add_u32_e32 v134, s14, v53
	v_cvt_pk_bf16_f32 v136, v137, v135
	v_ashrrev_i32_e32 v135, 31, v134
	v_lshlrev_b64 v[134:135], 12, v[134:135]
	v_lshl_add_u64 v[134:135], s[62:63], 0, v[134:135]
	v_lshl_add_u64 v[134:135], v[134:135], 0, s[8:9]
	v_lshl_add_u64 v[134:135], v[134:135], 0, v[32:33]
	global_store_dword v[134:135], v136, off
	ds_read2_b32 v[134:135], v52 offset0:16 offset1:24
	ds_read2_b32 v[136:137], v52 offset0:81 offset1:89
	v_add_u32_e32 v138, s14, v54
	v_ashrrev_i32_e32 v139, 31, v138
	v_lshlrev_b64 v[138:139], 12, v[138:139]
	v_lshl_add_u64 v[138:139], s[62:63], 0, v[138:139]
	v_lshl_add_u64 v[138:139], v[138:139], 0, s[8:9]
	s_waitcnt lgkmcnt(0)
	v_cvt_pk_bf16_f32 v134, v134, v136
	v_lshl_add_u64 v[138:139], v[138:139], 0, v[32:33]
	global_store_dword v[138:139], v134, off
	v_add_u32_e32 v134, s14, v55
	v_cvt_pk_bf16_f32 v136, v135, v137
	v_ashrrev_i32_e32 v135, 31, v134
	v_lshlrev_b64 v[134:135], 12, v[134:135]
	v_lshl_add_u64 v[134:135], s[62:63], 0, v[134:135]
	v_lshl_add_u64 v[134:135], v[134:135], 0, s[8:9]
	v_lshl_add_u64 v[134:135], v[134:135], 0, v[32:33]
	global_store_dword v[134:135], v136, off
	ds_read2_b32 v[134:135], v52 offset0:32 offset1:40
	ds_read2_b32 v[136:137], v52 offset0:97 offset1:105
	v_add_u32_e32 v138, s14, v56
	v_ashrrev_i32_e32 v139, 31, v138
	v_lshlrev_b64 v[138:139], 12, v[138:139]
	v_lshl_add_u64 v[138:139], s[62:63], 0, v[138:139]
	v_lshl_add_u64 v[138:139], v[138:139], 0, s[8:9]
	s_waitcnt lgkmcnt(0)
	v_cvt_pk_bf16_f32 v134, v134, v136
	v_lshl_add_u64 v[138:139], v[138:139], 0, v[32:33]
	global_store_dword v[138:139], v134, off
	v_add_u32_e32 v134, s14, v57
	v_cvt_pk_bf16_f32 v136, v135, v137
	v_ashrrev_i32_e32 v135, 31, v134
	v_lshlrev_b64 v[134:135], 12, v[134:135]
	v_lshl_add_u64 v[134:135], s[62:63], 0, v[134:135]
	v_lshl_add_u64 v[134:135], v[134:135], 0, s[8:9]
	v_lshl_add_u64 v[134:135], v[134:135], 0, v[32:33]
	global_store_dword v[134:135], v136, off
	ds_read2_b32 v[134:135], v52 offset0:48 offset1:56
	ds_read2_b32 v[136:137], v52 offset0:113 offset1:121
	v_add_u32_e32 v138, s14, v58
	v_ashrrev_i32_e32 v139, 31, v138
	v_lshlrev_b64 v[138:139], 12, v[138:139]
	v_lshl_add_u64 v[138:139], s[62:63], 0, v[138:139]
	v_lshl_add_u64 v[138:139], v[138:139], 0, s[8:9]
	s_waitcnt lgkmcnt(0)
	v_cvt_pk_bf16_f32 v134, v134, v136
	v_lshl_add_u64 v[138:139], v[138:139], 0, v[32:33]
	global_store_dword v[138:139], v134, off
	v_add_u32_e32 v134, s14, v59
	v_cvt_pk_bf16_f32 v136, v135, v137
	v_ashrrev_i32_e32 v135, 31, v134
	v_lshlrev_b64 v[134:135], 12, v[134:135]
	v_lshl_add_u64 v[134:135], s[62:63], 0, v[134:135]
	v_lshl_add_u64 v[134:135], v[134:135], 0, s[8:9]
	s_add_i32 s8, s33, s4
	v_lshl_add_u64 v[134:135], v[134:135], 0, v[32:33]
	s_cmpk_gt_i32 s8, 0x57f
	global_store_dword v[134:135], v136, off
	s_cselect_b32 s98, 1, 0
	v_cmp_gt_i32_e32 vcc, s11, v63
	v_cmp_gt_u32_e64 s[36:37], s12, v62
	s_waitcnt vmcnt(23)
	v_mul_f32_e32 v0, v65, v0
	s_and_b64 s[36:37], s[36:37], vcc
	v_cndmask_b32_e64 v0, 0, v0, s[36:37]
	v_cmp_gt_u32_e64 s[36:37], s12, v64
	s_waitcnt vmcnt(22)
	v_mul_f32_e32 v1, v67, v1
	s_and_b64 s[36:37], s[36:37], vcc
	v_cndmask_b32_e64 v1, 0, v1, s[36:37]
	v_cmp_gt_u32_e64 s[36:37], s12, v66
	s_waitcnt vmcnt(21)
	v_mul_f32_e32 v2, v69, v2
	s_and_b64 s[36:37], s[36:37], vcc
	v_cndmask_b32_e64 v2, 0, v2, s[36:37]
	v_cmp_gt_u32_e64 s[36:37], s12, v68
	s_waitcnt vmcnt(20)
	v_mul_f32_e32 v3, v71, v3
	s_and_b64 s[36:37], s[36:37], vcc
	v_cndmask_b32_e64 v3, 0, v3, s[36:37]
	v_cmp_gt_u32_e64 s[36:37], s12, v70
	s_waitcnt vmcnt(19)
	v_mul_f32_e32 v4, v73, v4
	s_and_b64 s[36:37], s[36:37], vcc
	v_cndmask_b32_e64 v4, 0, v4, s[36:37]
	v_cmp_gt_u32_e64 s[36:37], s12, v72
	s_waitcnt vmcnt(18)
	v_mul_f32_e32 v5, v75, v5
	s_and_b64 s[36:37], s[36:37], vcc
	v_cndmask_b32_e64 v5, 0, v5, s[36:37]
	v_cmp_gt_u32_e64 s[36:37], s12, v74
	s_waitcnt vmcnt(17)
	v_mul_f32_e32 v6, v77, v6
	s_and_b64 s[36:37], s[36:37], vcc
	v_cndmask_b32_e64 v6, 0, v6, s[36:37]
	v_cmp_gt_u32_e64 s[36:37], s12, v76
	s_waitcnt vmcnt(16)
	v_mul_f32_e32 v7, v80, v7
	s_and_b64 s[36:37], s[36:37], vcc
	v_cndmask_b32_e64 v7, 0, v7, s[36:37]
	v_cmp_gt_u32_e64 s[36:37], s12, v78
	s_waitcnt vmcnt(15)
	v_mul_f32_e32 v8, v81, v8
	s_and_b64 s[36:37], s[36:37], vcc
	v_cndmask_b32_e64 v8, 0, v8, s[36:37]
	v_cmp_gt_u32_e64 s[36:37], s12, v79
	s_waitcnt vmcnt(14)
	v_mul_f32_e32 v9, v83, v9
	s_and_b64 s[36:37], s[36:37], vcc
	v_cndmask_b32_e64 v9, 0, v9, s[36:37]
	v_cmp_gt_u32_e64 s[36:37], s12, v82
	s_waitcnt vmcnt(13)
	v_mul_f32_e32 v10, v85, v10
	s_and_b64 s[36:37], s[36:37], vcc
	v_cndmask_b32_e64 v10, 0, v10, s[36:37]
	v_cmp_gt_u32_e64 s[36:37], s12, v84
	s_waitcnt vmcnt(12)
	v_mul_f32_e32 v11, v87, v11
	s_and_b64 s[36:37], s[36:37], vcc
	v_cndmask_b32_e64 v11, 0, v11, s[36:37]
	v_cmp_gt_u32_e64 s[36:37], s12, v86
	s_waitcnt vmcnt(11)
	v_mul_f32_e32 v12, v89, v12
	s_and_b64 s[36:37], s[36:37], vcc
	v_cndmask_b32_e64 v12, 0, v12, s[36:37]
	v_cmp_gt_u32_e64 s[36:37], s12, v88
	s_waitcnt vmcnt(10)
	v_mul_f32_e32 v13, v91, v13
	s_and_b64 s[36:37], s[36:37], vcc
	v_cndmask_b32_e64 v13, 0, v13, s[36:37]
	v_cmp_gt_u32_e64 s[36:37], s12, v90
	s_waitcnt vmcnt(9)
	v_mul_f32_e32 v14, v93, v14
	s_and_b64 s[36:37], s[36:37], vcc
	v_cndmask_b32_e64 v14, 0, v14, s[36:37]
	v_cmp_gt_u32_e64 s[36:37], s12, v92
	s_waitcnt vmcnt(8)
	v_mul_f32_e32 v15, v94, v15
	s_and_b64 vcc, s[36:37], vcc
	v_cndmask_b32_e32 v15, 0, v15, vcc
	s_cmp_lg_u32 s98, 0
	s_barrier
; DEVI void cvt_job(LAS float* tile, const float* src, int srcK, int srcN, bf16_t* dst, int dstLd, int dstRows, int dstCol0, int mode, const float* gk = nullptr) {
;     ...
;     auto gl = [&](int t, float (&regs)[16]) {
;         int rho0, kap0, n0; coords(t, rho0, kap0, n0);
;         const int n = n0 + tx, nc = n < srcN ? n : srcN - 1;
;         const bool nok = n < srcN;
;         float raw[16], gs[16];
; #pragma unroll
;         for (int i = 0; i < 16; ++i) { const int k = kap0 + ty + 8 * i - dstCol0; const int kc = k < 0 ? 0 : (k < srcK ? k : srcK - 1);
;             raw[i] = __builtin_nontemporal_load(src + (size_t)kc * srcN + nc); }
;         if (gk) {
; #pragma unroll
;             for (int i = 0; i < 16; ++i) { const int k = kap0 + ty + 8 * i - dstCol0; const int kc = k < 0 ? 0 : (k < srcK ? k : srcK - 1); gs[i] = gk[kc]; }
;         } else {
; #pragma unroll
;             for (int i = 0; i < 16; ++i) gs[i] = 1.0f;
;         }
;     ...
;     auto emit = [&](int t, float (&regs)[16]) {
; #pragma unroll
;         for (int i = 0; i < 16; ++i) tile[(ty + 8 * i) * 65 + tx] = regs[i];
;         __syncthreads();
;         int rho0, kap0, n0; coords(t, rho0, kap0, n0);
;         const int tn = t + 2 * gridDim.x;
;         if (tn < ntot) gl(tn, regs);
	s_cbranch_scc1 .LBB0_1549
	s_add_i32 s4, s18, s4
	s_cmpk_gt_i32 s4, 0x57f
	ds_write_b32 v60, v16
	ds_write_b32 v60, v17 offset:2080
	ds_write_b32 v60, v18 offset:4160
	ds_write_b32 v60, v19 offset:6240
	ds_write_b32 v60, v20 offset:8320
	ds_write_b32 v60, v21 offset:10400
	ds_write_b32 v60, v22 offset:12480
	ds_write_b32 v60, v23 offset:14560
	ds_write_b32 v60, v24 offset:16640
	ds_write_b32 v60, v25 offset:18720
	ds_write_b32 v60, v26 offset:20800
	ds_write_b32 v60, v27 offset:22880
	ds_write_b32 v60, v28 offset:24960
	ds_write_b32 v60, v29 offset:27040
	ds_write_b32 v60, v30 offset:29120
	ds_write_b32 v60, v31 offset:31200
	s_waitcnt lgkmcnt(0)
	s_barrier
	s_cbranch_scc1 .LBB0_1548
	s_mul_hi_i32 s4, s4, 0x2e8ba2e9
	s_lshr_b32 s9, s4, 31
	s_ashr_i32 s4, s4, 4
	s_add_i32 s4, s4, s9
	s_mul_i32 s9, s4, 0x3ffff50
	s_add_i32 s14, s96, s7
	s_add_i32 s14, s14, s9
	s_and_b32 s9, s14, 0x3fffffc
	s_or_b32 s9, s9, s5
	s_lshl_b32 s9, s9, 6
	s_ashr_i32 s14, s9, 1
	s_and_b32 s14, s14, 0xffffff80
	s_and_b32 s9, s9, 64
	s_or_b32 s9, s9, s14
	v_or_b32_e32 v63, s9, v50
	v_min_i32_e32 v16, 0x15ff, v63
	v_lshl_add_u32 v62, s4, 7, v51
	v_ashrrev_i32_e32 v17, 31, v16
	v_lshl_add_u64 v[94:95], v[16:17], 2, s[0:1]
	v_med3_i32 v16, v62, 0, v61
	v_mad_u64_u32 v[18:19], s[14:15], v16, s10, v[94:95]
	v_add_u32_e32 v64, 8, v62
	global_load_dword v65, v[18:19], off nt
	v_med3_i32 v18, v64, 0, v61
	v_mad_u64_u32 v[20:21], s[14:15], v18, s10, v[94:95]
	v_add_u32_e32 v66, 16, v62
	global_load_dword v67, v[20:21], off nt
	v_med3_i32 v20, v66, 0, v61
	v_mad_u64_u32 v[22:23], s[14:15], v20, s10, v[94:95]
	v_add_u32_e32 v68, 24, v62
	global_load_dword v69, v[22:23], off nt
	v_med3_i32 v22, v68, 0, v61
	v_mad_u64_u32 v[24:25], s[14:15], v22, s10, v[94:95]
	v_add_u32_e32 v70, 32, v62
	global_load_dword v71, v[24:25], off nt
	v_med3_i32 v24, v70, 0, v61
	v_mad_u64_u32 v[26:27], s[14:15], v24, s10, v[94:95]
	v_add_u32_e32 v72, 40, v62
	global_load_dword v73, v[26:27], off nt
	v_med3_i32 v26, v72, 0, v61
	v_mad_u64_u32 v[28:29], s[14:15], v26, s10, v[94:95]
	v_add_u32_e32 v74, 48, v62
	global_load_dword v75, v[28:29], off nt
	v_med3_i32 v28, v74, 0, v61
	v_mad_u64_u32 v[30:31], s[14:15], v28, s10, v[94:95]
	v_add_u32_e32 v76, 56, v62
	global_load_dword v77, v[30:31], off nt
	v_med3_i32 v30, v76, 0, v61
	v_mad_u64_u32 v[34:35], s[14:15], v30, s10, v[94:95]
	v_add_u32_e32 v78, 64, v62
	global_load_dword v80, v[34:35], off nt
	v_med3_i32 v34, v78, 0, v61
	v_mad_u64_u32 v[36:37], s[14:15], v34, s10, v[94:95]
	v_add_u32_e32 v79, 0x48, v62
	global_load_dword v81, v[36:37], off nt
	v_med3_i32 v36, v79, 0, v61
	v_mad_u64_u32 v[38:39], s[14:15], v36, s10, v[94:95]
	v_add_u32_e32 v82, 0x50, v62
	global_load_dword v83, v[38:39], off nt
	v_med3_i32 v38, v82, 0, v61
	v_mad_u64_u32 v[40:41], s[14:15], v38, s10, v[94:95]
	v_add_u32_e32 v84, 0x58, v62
	global_load_dword v85, v[40:41], off nt
	v_med3_i32 v40, v84, 0, v61
	v_mad_u64_u32 v[42:43], s[14:15], v40, s10, v[94:95]
	v_add_u32_e32 v86, 0x60, v62
	global_load_dword v87, v[42:43], off nt
	v_med3_i32 v42, v86, 0, v61
	v_mad_u64_u32 v[44:45], s[14:15], v42, s10, v[94:95]
	v_add_u32_e32 v88, 0x68, v62
	global_load_dword v89, v[44:45], off nt
	v_med3_i32 v44, v88, 0, v61
	v_mad_u64_u32 v[46:47], s[14:15], v44, s10, v[94:95]
	v_add_u32_e32 v90, 0x70, v62
	global_load_dword v91, v[46:47], off nt
	v_med3_i32 v46, v90, 0, v61
	v_mad_u64_u32 v[48:49], s[14:15], v46, s10, v[94:95]
	v_add_u32_e32 v92, 0x78, v62
	global_load_dword v93, v[48:49], off nt
	v_med3_i32 v48, v92, 0, v61
	v_mad_u64_u32 v[94:95], s[14:15], v48, s10, v[94:95]
	global_load_dword v94, v[94:95], off nt
	v_readlane_b32 s14, v240, 48
	v_readlane_b32 s15, v240, 49
	s_and_b64 vcc, exec, s[14:15]
	s_cbranch_vccz .LBB0_1546
	v_mov_b32_e32 v31, 1.0
	v_mov_b32_e32 v30, 1.0
	v_mov_b32_e32 v29, 1.0
	v_mov_b32_e32 v28, 1.0
	v_mov_b32_e32 v27, 1.0
	v_mov_b32_e32 v26, 1.0
	v_mov_b32_e32 v25, 1.0
	v_mov_b32_e32 v24, 1.0
	v_mov_b32_e32 v23, 1.0
	v_mov_b32_e32 v22, 1.0
	v_mov_b32_e32 v21, 1.0
	v_mov_b32_e32 v20, 1.0
	v_mov_b32_e32 v19, 1.0
	v_mov_b32_e32 v18, 1.0
	v_mov_b32_e32 v17, 1.0
	v_mov_b32_e32 v16, 1.0
	s_branch .LBB0_1547

; DEVI int obid() { int b = __builtin_amdgcn_workgroup_id_x(); asm volatile("" : "+s"(b)); return b; }
; DEVI unsigned pk_bf16(float lo, float hi) { unsigned r; asm("v_cvt_pk_bf16_f32 %0, %1, %2" : "=v"(r) : "v"(lo), "v"(hi)); return r; }
; DEVI void cvt_job(LAS float* tile, const float* src, int srcK, int srcN, bf16_t* dst, int dstLd, int dstRows, int dstCol0, int mode, const float* gk = nullptr) {
;     ...
;         for (int i = 0; i < 16; ++i) { const int k = kap0 + ty + 8 * i - dstCol0; const int kc = k < 0 ? 0 : (k < srcK ? k : srcK - 1);
;             raw[i] = __builtin_nontemporal_load(src + (size_t)kc * srcN + nc); }
;         if (gk) {
; #pragma unroll
;             for (int i = 0; i < 16; ++i) { const int k = kap0 + ty + 8 * i - dstCol0; const int kc = k < 0 ? 0 : (k < srcK ? k : srcK - 1); gs[i] = gk[kc]; }
;         } else {
; #pragma unroll
;             for (int i = 0; i < 16; ++i) gs[i] = 1.0f;
;         }
; #pragma unroll
;         for (int i = 0; i < 16; ++i) { const int k = kap0 + ty + 8 * i - dstCol0; regs[i] = (nok && k >= 0 && k < srcK) ? raw[i] * gs[i] : 0.f; }
;     ...
;         for (int i = 0; i < 8; ++i) { const int row = ty + 8 * i;
;             const float lo = tile[(2 * tx) * 65 + row], hi = tile[(2 * tx + 1) * 65 + row];
;             *(unsigned*)(dst + (size_t)(rho0 + row) * dstLd + kap0 + 2 * tx) = pk_bf16(lo, hi); }
;         __syncthreads();
;     };
;     const int G = gridDim.x;
;     int t = obid();
;     if (t < ntot) gl(t, regsA);
;     if (t + G < ntot) gl(t + G, regsB);
;     while (t < ntot) {
;         emit(t, regsA);
;         if (t + G < ntot) emit(t + G, regsB);
;         t += 2 * G;
.LBB0_1803:
.LBB0_1804:
	s_mul_hi_i32 s8, s4, 0x2e8ba2e9
	s_lshr_b32 s9, s8, 31
	s_ashr_i32 s8, s8, 4
	s_add_i32 s8, s8, s9
	s_mul_i32 s9, s8, 0x3ffff50
	s_add_i32 s9, s7, s9
	s_and_b32 s9, s9, 0x3fffffc
	s_or_b32 s9, s9, s6
	s_lshl_b32 s14, s9, 6
	ds_read2_b32 v[134:135], v52 offset0:65 offset1:73
	ds_read2_b32 v[136:137], v52 offset1:8
	v_add_u32_e32 v138, s14, v51
	s_lshl_b32 s8, s8, 7
	v_ashrrev_i32_e32 v139, 31, v138
	s_ashr_i32 s9, s8, 31
	v_lshlrev_b64 v[138:139], 12, v[138:139]
	v_lshl_add_u64 v[138:139], s[62:63], 0, v[138:139]
	s_lshl_b64 s[8:9], s[8:9], 1
	v_lshl_add_u64 v[138:139], v[138:139], 0, s[8:9]
	s_waitcnt lgkmcnt(0)
	v_cvt_pk_bf16_f32 v134, v136, v134
	v_lshl_add_u64 v[138:139], v[138:139], 0, v[32:33]
	global_store_dword v[138:139], v134, off
	v_add_u32_e32 v134, s14, v53
	v_cvt_pk_bf16_f32 v136, v137, v135
	v_ashrrev_i32_e32 v135, 31, v134
	v_lshlrev_b64 v[134:135], 12, v[134:135]
	v_lshl_add_u64 v[134:135], s[62:63], 0, v[134:135]
	v_lshl_add_u64 v[134:135], v[134:135], 0, s[8:9]
	v_lshl_add_u64 v[134:135], v[134:135], 0, v[32:33]
	global_store_dword v[134:135], v136, off
	ds_read2_b32 v[134:135], v52 offset0:16 offset1:24
	ds_read2_b32 v[136:137], v52 offset0:81 offset1:89
	v_add_u32_e32 v138, s14, v54
	v_ashrrev_i32_e32 v139, 31, v138
	v_lshlrev_b64 v[138:139], 12, v[138:139]
	v_lshl_add_u64 v[138:139], s[62:63], 0, v[138:139]
	v_lshl_add_u64 v[138:139], v[138:139], 0, s[8:9]
	s_waitcnt lgkmcnt(0)
	v_cvt_pk_bf16_f32 v134, v134, v136
	v_lshl_add_u64 v[138:139], v[138:139], 0, v[32:33]
	global_store_dword v[138:139], v134, off
	v_add_u32_e32 v134, s14, v55
	v_cvt_pk_bf16_f32 v136, v135, v137
	v_ashrrev_i32_e32 v135, 31, v134
	v_lshlrev_b64 v[134:135], 12, v[134:135]
	v_lshl_add_u64 v[134:135], s[62:63], 0, v[134:135]
	v_lshl_add_u64 v[134:135], v[134:135], 0, s[8:9]
	v_lshl_add_u64 v[134:135], v[134:135], 0, v[32:33]
	global_store_dword v[134:135], v136, off
	ds_read2_b32 v[134:135], v52 offset0:32 offset1:40
	ds_read2_b32 v[136:137], v52 offset0:97 offset1:105
	v_add_u32_e32 v138, s14, v56
	v_ashrrev_i32_e32 v139, 31, v138
	v_lshlrev_b64 v[138:139], 12, v[138:139]
	v_lshl_add_u64 v[138:139], s[62:63], 0, v[138:139]
	v_lshl_add_u64 v[138:139], v[138:139], 0, s[8:9]
	s_waitcnt lgkmcnt(0)
	v_cvt_pk_bf16_f32 v134, v134, v136
	v_lshl_add_u64 v[138:139], v[138:139], 0, v[32:33]
	global_store_dword v[138:139], v134, off
	v_add_u32_e32 v134, s14, v57
	v_cvt_pk_bf16_f32 v136, v135, v137
	v_ashrrev_i32_e32 v135, 31, v134
	v_lshlrev_b64 v[134:135], 12, v[134:135]
	v_lshl_add_u64 v[134:135], s[62:63], 0, v[134:135]
	v_lshl_add_u64 v[134:135], v[134:135], 0, s[8:9]
	v_lshl_add_u64 v[134:135], v[134:135], 0, v[32:33]
	global_store_dword v[134:135], v136, off
	ds_read2_b32 v[134:135], v52 offset0:48 offset1:56
	ds_read2_b32 v[136:137], v52 offset0:113 offset1:121
	v_add_u32_e32 v138, s14, v58
	v_ashrrev_i32_e32 v139, 31, v138
	v_lshlrev_b64 v[138:139], 12, v[138:139]
	v_lshl_add_u64 v[138:139], s[62:63], 0, v[138:139]
	v_lshl_add_u64 v[138:139], v[138:139], 0, s[8:9]
	s_waitcnt lgkmcnt(0)
	v_cvt_pk_bf16_f32 v134, v134, v136
	v_lshl_add_u64 v[138:139], v[138:139], 0, v[32:33]
	global_store_dword v[138:139], v134, off
	v_add_u32_e32 v134, s14, v59
	v_cvt_pk_bf16_f32 v136, v135, v137
	v_ashrrev_i32_e32 v135, 31, v134
	v_lshlrev_b64 v[134:135], 12, v[134:135]
	v_lshl_add_u64 v[134:135], s[62:63], 0, v[134:135]
	v_lshl_add_u64 v[134:135], v[134:135], 0, s[8:9]
	s_add_i32 s8, s33, s4
	v_lshl_add_u64 v[134:135], v[134:135], 0, v[32:33]
	s_cmpk_gt_i32 s8, 0x57f
	global_store_dword v[134:135], v136, off
	s_cselect_b32 s98, 1, 0
	v_cmp_gt_i32_e32 vcc, s11, v63
	v_cmp_gt_u32_e64 s[36:37], s12, v62
	s_waitcnt vmcnt(23)
	v_mul_f32_e32 v0, v65, v0
	s_and_b64 s[36:37], s[36:37], vcc
	v_cndmask_b32_e64 v0, 0, v0, s[36:37]
	v_cmp_gt_u32_e64 s[36:37], s12, v64
	s_waitcnt vmcnt(22)
	v_mul_f32_e32 v1, v67, v1
	s_and_b64 s[36:37], s[36:37], vcc
	v_cndmask_b32_e64 v1, 0, v1, s[36:37]
	v_cmp_gt_u32_e64 s[36:37], s12, v66
	s_waitcnt vmcnt(21)
	v_mul_f32_e32 v2, v69, v2
	s_and_b64 s[36:37], s[36:37], vcc
	v_cndmask_b32_e64 v2, 0, v2, s[36:37]
	v_cmp_gt_u32_e64 s[36:37], s12, v68
	s_waitcnt vmcnt(20)
	v_mul_f32_e32 v3, v71, v3
	s_and_b64 s[36:37], s[36:37], vcc
	v_cndmask_b32_e64 v3, 0, v3, s[36:37]
	v_cmp_gt_u32_e64 s[36:37], s12, v70
	s_waitcnt vmcnt(19)
	v_mul_f32_e32 v4, v73, v4
	s_and_b64 s[36:37], s[36:37], vcc
	v_cndmask_b32_e64 v4, 0, v4, s[36:37]
	v_cmp_gt_u32_e64 s[36:37], s12, v72
	s_waitcnt vmcnt(18)
	v_mul_f32_e32 v5, v75, v5
	s_and_b64 s[36:37], s[36:37], vcc
	v_cndmask_b32_e64 v5, 0, v5, s[36:37]
	v_cmp_gt_u32_e64 s[36:37], s12, v74
	s_waitcnt vmcnt(17)
	v_mul_f32_e32 v6, v77, v6
	s_and_b64 s[36:37], s[36:37], vcc
	v_cndmask_b32_e64 v6, 0, v6, s[36:37]
	v_cmp_gt_u32_e64 s[36:37], s12, v76
	s_waitcnt vmcnt(16)
	v_mul_f32_e32 v7, v80, v7
	s_and_b64 s[36:37], s[36:37], vcc
	v_cndmask_b32_e64 v7, 0, v7, s[36:37]
	v_cmp_gt_u32_e64 s[36:37], s12, v78
	s_waitcnt vmcnt(15)
	v_mul_f32_e32 v8, v81, v8
	s_and_b64 s[36:37], s[36:37], vcc
	v_cndmask_b32_e64 v8, 0, v8, s[36:37]
	v_cmp_gt_u32_e64 s[36:37], s12, v79
	s_waitcnt vmcnt(14)
	v_mul_f32_e32 v9, v83, v9
	s_and_b64 s[36:37], s[36:37], vcc
	v_cndmask_b32_e64 v9, 0, v9, s[36:37]
	v_cmp_gt_u32_e64 s[36:37], s12, v82
	s_waitcnt vmcnt(13)
	v_mul_f32_e32 v10, v85, v10
	s_and_b64 s[36:37], s[36:37], vcc
	v_cndmask_b32_e64 v10, 0, v10, s[36:37]
	v_cmp_gt_u32_e64 s[36:37], s12, v84
	s_waitcnt vmcnt(12)
	v_mul_f32_e32 v11, v87, v11
	s_and_b64 s[36:37], s[36:37], vcc
	v_cndmask_b32_e64 v11, 0, v11, s[36:37]
	v_cmp_gt_u32_e64 s[36:37], s12, v86
	s_waitcnt vmcnt(11)
	v_mul_f32_e32 v12, v89, v12
	s_and_b64 s[36:37], s[36:37], vcc
	v_cndmask_b32_e64 v12, 0, v12, s[36:37]
	v_cmp_gt_u32_e64 s[36:37], s12, v88
	s_waitcnt vmcnt(10)
	v_mul_f32_e32 v13, v91, v13
	s_and_b64 s[36:37], s[36:37], vcc
	v_cndmask_b32_e64 v13, 0, v13, s[36:37]
	v_cmp_gt_u32_e64 s[36:37], s12, v90
	s_waitcnt vmcnt(9)
	v_mul_f32_e32 v14, v93, v14
	s_and_b64 s[36:37], s[36:37], vcc
	v_cndmask_b32_e64 v14, 0, v14, s[36:37]
	v_cmp_gt_u32_e64 s[36:37], s12, v92
	s_waitcnt vmcnt(8)
	v_mul_f32_e32 v15, v94, v15
	s_and_b64 vcc, s[36:37], vcc
	v_cndmask_b32_e32 v15, 0, v15, vcc
	s_cmp_lg_u32 s98, 0
	s_barrier
; DEVI void cvt_job(LAS float* tile, const float* src, int srcK, int srcN, bf16_t* dst, int dstLd, int dstRows, int dstCol0, int mode, const float* gk = nullptr) {
;     ...
;     auto gl = [&](int t, float (&regs)[16]) {
;         int rho0, kap0, n0; coords(t, rho0, kap0, n0);
;         const int n = n0 + tx, nc = n < srcN ? n : srcN - 1;
;         const bool nok = n < srcN;
;         float raw[16], gs[16];
; #pragma unroll
;         for (int i = 0; i < 16; ++i) { const int k = kap0 + ty + 8 * i - dstCol0; const int kc = k < 0 ? 0 : (k < srcK ? k : srcK - 1);
;             raw[i] = __builtin_nontemporal_load(src + (size_t)kc * srcN + nc); }
;         if (gk) {
; #pragma unroll
;             for (int i = 0; i < 16; ++i) { const int k = kap0 + ty + 8 * i - dstCol0; const int kc = k < 0 ? 0 : (k < srcK ? k : srcK - 1); gs[i] = gk[kc]; }
;         } else {
; #pragma unroll
;             for (int i = 0; i < 16; ++i) gs[i] = 1.0f;
;         }
;     ...
;     auto emit = [&](int t, float (&regs)[16]) {
; #pragma unroll
;         for (int i = 0; i < 16; ++i) tile[(ty + 8 * i) * 65 + tx] = regs[i];
;         __syncthreads();
;         int rho0, kap0, n0; coords(t, rho0, kap0, n0);
;         const int tn = t + 2 * gridDim.x;
;         if (tn < ntot) gl(tn, regs);
	s_cbranch_scc1 .LBB0_1798
	s_add_i32 s4, s18, s4
	s_cmpk_gt_i32 s4, 0x57f
	ds_write_b32 v60, v16
	ds_write_b32 v60, v17 offset:2080
	ds_write_b32 v60, v18 offset:4160
	ds_write_b32 v60, v19 offset:6240
	ds_write_b32 v60, v20 offset:8320
	ds_write_b32 v60, v21 offset:10400
	ds_write_b32 v60, v22 offset:12480
	ds_write_b32 v60, v23 offset:14560
	ds_write_b32 v60, v24 offset:16640
	ds_write_b32 v60, v25 offset:18720
	ds_write_b32 v60, v26 offset:20800
	ds_write_b32 v60, v27 offset:22880
	ds_write_b32 v60, v28 offset:24960
	ds_write_b32 v60, v29 offset:27040
	ds_write_b32 v60, v30 offset:29120
	ds_write_b32 v60, v31 offset:31200
	s_waitcnt lgkmcnt(0)
	s_barrier
	s_cbranch_scc1 .LBB0_1797
	s_mul_hi_i32 s4, s4, 0x2e8ba2e9
	s_lshr_b32 s9, s4, 31
	s_ashr_i32 s4, s4, 4
	s_add_i32 s4, s4, s9
	s_mul_i32 s9, s4, 0x3ffff50
	s_add_i32 s14, s96, s7
	s_add_i32 s14, s14, s9
	s_and_b32 s9, s14, 0x3fffffc
	s_or_b32 s9, s9, s5
	s_lshl_b32 s9, s9, 6
	s_ashr_i32 s14, s9, 1
	s_and_b32 s14, s14, 0xffffff80
	s_and_b32 s9, s9, 64
	s_or_b32 s9, s9, s14
	v_or_b32_e32 v63, s9, v50
	v_min_i32_e32 v16, 0x15ff, v63
	v_lshl_add_u32 v62, s4, 7, v51
	v_ashrrev_i32_e32 v17, 31, v16
	v_lshl_add_u64 v[94:95], v[16:17], 2, s[0:1]
	v_med3_i32 v16, v62, 0, v61
	v_mad_u64_u32 v[18:19], s[14:15], v16, s10, v[94:95]
	v_add_u32_e32 v64, 8, v62
	global_load_dword v65, v[18:19], off nt
	v_med3_i32 v18, v64, 0, v61
	v_mad_u64_u32 v[20:21], s[14:15], v18, s10, v[94:95]
	v_add_u32_e32 v66, 16, v62
	global_load_dword v67, v[20:21], off nt
	v_med3_i32 v20, v66, 0, v61
	v_mad_u64_u32 v[22:23], s[14:15], v20, s10, v[94:95]
	v_add_u32_e32 v68, 24, v62
	global_load_dword v69, v[22:23], off nt
	v_med3_i32 v22, v68, 0, v61
	v_mad_u64_u32 v[24:25], s[14:15], v22, s10, v[94:95]
	v_add_u32_e32 v70, 32, v62
	global_load_dword v71, v[24:25], off nt
	v_med3_i32 v24, v70, 0, v61
	v_mad_u64_u32 v[26:27], s[14:15], v24, s10, v[94:95]
	v_add_u32_e32 v72, 40, v62
	global_load_dword v73, v[26:27], off nt
	v_med3_i32 v26, v72, 0, v61
	v_mad_u64_u32 v[28:29], s[14:15], v26, s10, v[94:95]
	v_add_u32_e32 v74, 48, v62
	global_load_dword v75, v[28:29], off nt
	v_med3_i32 v28, v74, 0, v61
	v_mad_u64_u32 v[30:31], s[14:15], v28, s10, v[94:95]
	v_add_u32_e32 v76, 56, v62
	global_load_dword v77, v[30:31], off nt
	v_med3_i32 v30, v76, 0, v61
	v_mad_u64_u32 v[34:35], s[14:15], v30, s10, v[94:95]
	v_add_u32_e32 v78, 64, v62
	global_load_dword v80, v[34:35], off nt
	v_med3_i32 v34, v78, 0, v61
	v_mad_u64_u32 v[36:37], s[14:15], v34, s10, v[94:95]
	v_add_u32_e32 v79, 0x48, v62
	global_load_dword v81, v[36:37], off nt
	v_med3_i32 v36, v79, 0, v61
	v_mad_u64_u32 v[38:39], s[14:15], v36, s10, v[94:95]
	v_add_u32_e32 v82, 0x50, v62
	global_load_dword v83, v[38:39], off nt
	v_med3_i32 v38, v82, 0, v61
	v_mad_u64_u32 v[40:41], s[14:15], v38, s10, v[94:95]
	v_add_u32_e32 v84, 0x58, v62
	global_load_dword v85, v[40:41], off nt
	v_med3_i32 v40, v84, 0, v61
	v_mad_u64_u32 v[42:43], s[14:15], v40, s10, v[94:95]
	v_add_u32_e32 v86, 0x60, v62
	global_load_dword v87, v[42:43], off nt
	v_med3_i32 v42, v86, 0, v61
	v_mad_u64_u32 v[44:45], s[14:15], v42, s10, v[94:95]
	v_add_u32_e32 v88, 0x68, v62
	global_load_dword v89, v[44:45], off nt
	v_med3_i32 v44, v88, 0, v61
	v_mad_u64_u32 v[46:47], s[14:15], v44, s10, v[94:95]
	v_add_u32_e32 v90, 0x70, v62
	global_load_dword v91, v[46:47], off nt
	v_med3_i32 v46, v90, 0, v61
	v_mad_u64_u32 v[48:49], s[14:15], v46, s10, v[94:95]
	v_add_u32_e32 v92, 0x78, v62
	global_load_dword v93, v[48:49], off nt
	v_med3_i32 v48, v92, 0, v61
	v_mad_u64_u32 v[94:95], s[14:15], v48, s10, v[94:95]
	global_load_dword v94, v[94:95], off nt
	s_and_b64 vcc, exec, s[16:17]
	s_cbranch_vccz .LBB0_1795
	v_mov_b32_e32 v31, 1.0
	v_mov_b32_e32 v30, 1.0
	v_mov_b32_e32 v29, 1.0
	v_mov_b32_e32 v28, 1.0
	v_mov_b32_e32 v27, 1.0
	v_mov_b32_e32 v26, 1.0
	v_mov_b32_e32 v25, 1.0
	v_mov_b32_e32 v24, 1.0
	v_mov_b32_e32 v23, 1.0
	v_mov_b32_e32 v22, 1.0
	v_mov_b32_e32 v21, 1.0
	v_mov_b32_e32 v20, 1.0
	v_mov_b32_e32 v19, 1.0
	v_mov_b32_e32 v18, 1.0
	v_mov_b32_e32 v17, 1.0
	v_mov_b32_e32 v16, 1.0
	s_branch .LBB0_1796

; DEVI int obid() { int b = __builtin_amdgcn_workgroup_id_x(); asm volatile("" : "+s"(b)); return b; }
; DEVI unsigned pk_bf16(float lo, float hi) { unsigned r; asm("v_cvt_pk_bf16_f32 %0, %1, %2" : "=v"(r) : "v"(lo), "v"(hi)); return r; }
; DEVI void cvt_job(LAS float* tile, const float* src, int srcK, int srcN, bf16_t* dst, int dstLd, int dstRows, int dstCol0, int mode, const float* gk = nullptr) {
;     ...
;         for (int i = 0; i < 16; ++i) { const int k = kap0 + ty + 8 * i - dstCol0; const int kc = k < 0 ? 0 : (k < srcK ? k : srcK - 1);
;             raw[i] = __builtin_nontemporal_load(src + (size_t)kc * srcN + nc); }
;         if (gk) {
; #pragma unroll
;             for (int i = 0; i < 16; ++i) { const int k = kap0 + ty + 8 * i - dstCol0; const int kc = k < 0 ? 0 : (k < srcK ? k : srcK - 1); gs[i] = gk[kc]; }
;         } else {
; #pragma unroll
;             for (int i = 0; i < 16; ++i) gs[i] = 1.0f;
;         }
; #pragma unroll
;         for (int i = 0; i < 16; ++i) { const int k = kap0 + ty + 8 * i - dstCol0; regs[i] = (nok && k >= 0 && k < srcK) ? raw[i] * gs[i] : 0.f; }
;     ...
;         for (int i = 0; i < 8; ++i) { const int row = ty + 8 * i;
;             const float lo = tile[(2 * tx) * 65 + row], hi = tile[(2 * tx + 1) * 65 + row];
;             *(unsigned*)(dst + (size_t)(rho0 + row) * dstLd + kap0 + 2 * tx) = pk_bf16(lo, hi); }
;         __syncthreads();
;     };
;     const int G = gridDim.x;
;     int t = obid();
;     if (t < ntot) gl(t, regsA);
;     if (t + G < ntot) gl(t + G, regsB);
;     while (t < ntot) {
;         emit(t, regsA);
;         if (t + G < ntot) emit(t + G, regsB);
;         t += 2 * G;
.LBB0_1828:
.LBB0_1829:
	s_mul_hi_i32 s8, s4, 0x2e8ba2e9
	s_lshr_b32 s9, s8, 31
	s_ashr_i32 s8, s8, 4
	s_add_i32 s8, s8, s9
	s_mul_i32 s9, s8, 0x3ffff50
	s_add_i32 s9, s7, s9
	s_and_b32 s9, s9, 0x3fffffc
	s_or_b32 s9, s9, s6
	s_lshl_b32 s14, s9, 6
	s_bitset1_b32 s14, 7
	ds_read2_b32 v[134:135], v52 offset0:65 offset1:73
	ds_read2_b32 v[136:137], v52 offset1:8
	v_add_u32_e32 v138, s14, v51
	s_lshl_b32 s8, s8, 7
	v_ashrrev_i32_e32 v139, 31, v138
	s_ashr_i32 s9, s8, 31
	v_lshlrev_b64 v[138:139], 12, v[138:139]
	v_lshl_add_u64 v[138:139], s[62:63], 0, v[138:139]
	s_lshl_b64 s[8:9], s[8:9], 1
	v_lshl_add_u64 v[138:139], v[138:139], 0, s[8:9]
	s_waitcnt lgkmcnt(0)
	v_cvt_pk_bf16_f32 v134, v136, v134
	v_lshl_add_u64 v[138:139], v[138:139], 0, v[32:33]
	global_store_dword v[138:139], v134, off
	v_add_u32_e32 v134, s14, v53
	v_cvt_pk_bf16_f32 v136, v137, v135
	v_ashrrev_i32_e32 v135, 31, v134
	v_lshlrev_b64 v[134:135], 12, v[134:135]
	v_lshl_add_u64 v[134:135], s[62:63], 0, v[134:135]
	v_lshl_add_u64 v[134:135], v[134:135], 0, s[8:9]
	v_lshl_add_u64 v[134:135], v[134:135], 0, v[32:33]
	global_store_dword v[134:135], v136, off
	ds_read2_b32 v[134:135], v52 offset0:16 offset1:24
	ds_read2_b32 v[136:137], v52 offset0:81 offset1:89
	v_add_u32_e32 v138, s14, v54
	v_ashrrev_i32_e32 v139, 31, v138
	v_lshlrev_b64 v[138:139], 12, v[138:139]
	v_lshl_add_u64 v[138:139], s[62:63], 0, v[138:139]
	v_lshl_add_u64 v[138:139], v[138:139], 0, s[8:9]
	s_waitcnt lgkmcnt(0)
	v_cvt_pk_bf16_f32 v134, v134, v136
	v_lshl_add_u64 v[138:139], v[138:139], 0, v[32:33]
	global_store_dword v[138:139], v134, off
	v_add_u32_e32 v134, s14, v55
	v_cvt_pk_bf16_f32 v136, v135, v137
	v_ashrrev_i32_e32 v135, 31, v134
	v_lshlrev_b64 v[134:135], 12, v[134:135]
	v_lshl_add_u64 v[134:135], s[62:63], 0, v[134:135]
	v_lshl_add_u64 v[134:135], v[134:135], 0, s[8:9]
	v_lshl_add_u64 v[134:135], v[134:135], 0, v[32:33]
	global_store_dword v[134:135], v136, off
	ds_read2_b32 v[134:135], v52 offset0:32 offset1:40
	ds_read2_b32 v[136:137], v52 offset0:97 offset1:105
	v_add_u32_e32 v138, s14, v56
	v_ashrrev_i32_e32 v139, 31, v138
	v_lshlrev_b64 v[138:139], 12, v[138:139]
	v_lshl_add_u64 v[138:139], s[62:63], 0, v[138:139]
	v_lshl_add_u64 v[138:139], v[138:139], 0, s[8:9]
	s_waitcnt lgkmcnt(0)
	v_cvt_pk_bf16_f32 v134, v134, v136
	v_lshl_add_u64 v[138:139], v[138:139], 0, v[32:33]
	global_store_dword v[138:139], v134, off
	v_add_u32_e32 v134, s14, v57
	v_cvt_pk_bf16_f32 v136, v135, v137
	v_ashrrev_i32_e32 v135, 31, v134
	v_lshlrev_b64 v[134:135], 12, v[134:135]
	v_lshl_add_u64 v[134:135], s[62:63], 0, v[134:135]
	v_lshl_add_u64 v[134:135], v[134:135], 0, s[8:9]
	v_lshl_add_u64 v[134:135], v[134:135], 0, v[32:33]
	global_store_dword v[134:135], v136, off
	ds_read2_b32 v[134:135], v52 offset0:48 offset1:56
	ds_read2_b32 v[136:137], v52 offset0:113 offset1:121
	v_add_u32_e32 v138, s14, v58
	v_ashrrev_i32_e32 v139, 31, v138
	v_lshlrev_b64 v[138:139], 12, v[138:139]
	v_lshl_add_u64 v[138:139], s[62:63], 0, v[138:139]
	v_lshl_add_u64 v[138:139], v[138:139], 0, s[8:9]
	s_waitcnt lgkmcnt(0)
	v_cvt_pk_bf16_f32 v134, v134, v136
	v_lshl_add_u64 v[138:139], v[138:139], 0, v[32:33]
	global_store_dword v[138:139], v134, off
	v_add_u32_e32 v134, s14, v59
	v_cvt_pk_bf16_f32 v136, v135, v137
	v_ashrrev_i32_e32 v135, 31, v134
	v_lshlrev_b64 v[134:135], 12, v[134:135]
	v_lshl_add_u64 v[134:135], s[62:63], 0, v[134:135]
	v_lshl_add_u64 v[134:135], v[134:135], 0, s[8:9]
	s_add_i32 s8, s33, s4
	v_lshl_add_u64 v[134:135], v[134:135], 0, v[32:33]
	s_cmpk_gt_i32 s8, 0x57f
	global_store_dword v[134:135], v136, off
	s_cselect_b32 s98, 1, 0
	v_cmp_gt_i32_e32 vcc, s11, v63
	v_cmp_gt_u32_e64 s[36:37], s12, v62
	s_waitcnt vmcnt(23)
	v_mul_f32_e32 v0, v65, v0
	s_and_b64 s[36:37], s[36:37], vcc
	v_cndmask_b32_e64 v0, 0, v0, s[36:37]
	v_cmp_gt_u32_e64 s[36:37], s12, v64
	s_waitcnt vmcnt(22)
	v_mul_f32_e32 v1, v67, v1
	s_and_b64 s[36:37], s[36:37], vcc
	v_cndmask_b32_e64 v1, 0, v1, s[36:37]
	v_cmp_gt_u32_e64 s[36:37], s12, v66
	s_waitcnt vmcnt(21)
	v_mul_f32_e32 v2, v69, v2
	s_and_b64 s[36:37], s[36:37], vcc
	v_cndmask_b32_e64 v2, 0, v2, s[36:37]
	v_cmp_gt_u32_e64 s[36:37], s12, v68
	s_waitcnt vmcnt(20)
	v_mul_f32_e32 v3, v71, v3
	s_and_b64 s[36:37], s[36:37], vcc
	v_cndmask_b32_e64 v3, 0, v3, s[36:37]
	v_cmp_gt_u32_e64 s[36:37], s12, v70
	s_waitcnt vmcnt(19)
	v_mul_f32_e32 v4, v73, v4
	s_and_b64 s[36:37], s[36:37], vcc
	v_cndmask_b32_e64 v4, 0, v4, s[36:37]
	v_cmp_gt_u32_e64 s[36:37], s12, v72
	s_waitcnt vmcnt(18)
	v_mul_f32_e32 v5, v75, v5
	s_and_b64 s[36:37], s[36:37], vcc
	v_cndmask_b32_e64 v5, 0, v5, s[36:37]
	v_cmp_gt_u32_e64 s[36:37], s12, v74
	s_waitcnt vmcnt(17)
	v_mul_f32_e32 v6, v77, v6
	s_and_b64 s[36:37], s[36:37], vcc
	v_cndmask_b32_e64 v6, 0, v6, s[36:37]
	v_cmp_gt_u32_e64 s[36:37], s12, v76
	s_waitcnt vmcnt(16)
	v_mul_f32_e32 v7, v80, v7
	s_and_b64 s[36:37], s[36:37], vcc
	v_cndmask_b32_e64 v7, 0, v7, s[36:37]
	v_cmp_gt_u32_e64 s[36:37], s12, v78
	s_waitcnt vmcnt(15)
	v_mul_f32_e32 v8, v81, v8
	s_and_b64 s[36:37], s[36:37], vcc
	v_cndmask_b32_e64 v8, 0, v8, s[36:37]
	v_cmp_gt_u32_e64 s[36:37], s12, v79
	s_waitcnt vmcnt(14)
	v_mul_f32_e32 v9, v83, v9
	s_and_b64 s[36:37], s[36:37], vcc
	v_cndmask_b32_e64 v9, 0, v9, s[36:37]
	v_cmp_gt_u32_e64 s[36:37], s12, v82
	s_waitcnt vmcnt(13)
	v_mul_f32_e32 v10, v85, v10
	s_and_b64 s[36:37], s[36:37], vcc
	v_cndmask_b32_e64 v10, 0, v10, s[36:37]
	v_cmp_gt_u32_e64 s[36:37], s12, v84
	s_waitcnt vmcnt(12)
	v_mul_f32_e32 v11, v87, v11
	s_and_b64 s[36:37], s[36:37], vcc
	v_cndmask_b32_e64 v11, 0, v11, s[36:37]
	v_cmp_gt_u32_e64 s[36:37], s12, v86
	s_waitcnt vmcnt(11)
	v_mul_f32_e32 v12, v89, v12
	s_and_b64 s[36:37], s[36:37], vcc
	v_cndmask_b32_e64 v12, 0, v12, s[36:37]
	v_cmp_gt_u32_e64 s[36:37], s12, v88
	s_waitcnt vmcnt(10)
	v_mul_f32_e32 v13, v91, v13
	s_and_b64 s[36:37], s[36:37], vcc
	v_cndmask_b32_e64 v13, 0, v13, s[36:37]
	v_cmp_gt_u32_e64 s[36:37], s12, v90
	s_waitcnt vmcnt(9)
	v_mul_f32_e32 v14, v93, v14
	s_and_b64 s[36:37], s[36:37], vcc
	v_cndmask_b32_e64 v14, 0, v14, s[36:37]
	v_cmp_gt_u32_e64 s[36:37], s12, v92
	s_waitcnt vmcnt(8)
	v_mul_f32_e32 v15, v94, v15
	s_and_b64 vcc, s[36:37], vcc
	v_cndmask_b32_e32 v15, 0, v15, vcc
	s_cmp_lg_u32 s98, 0
	s_barrier
; DEVI void cvt_job(LAS float* tile, const float* src, int srcK, int srcN, bf16_t* dst, int dstLd, int dstRows, int dstCol0, int mode, const float* gk = nullptr) {
;     ...
;     auto gl = [&](int t, float (&regs)[16]) {
;         int rho0, kap0, n0; coords(t, rho0, kap0, n0);
;         const int n = n0 + tx, nc = n < srcN ? n : srcN - 1;
;         const bool nok = n < srcN;
;         float raw[16], gs[16];
; #pragma unroll
;         for (int i = 0; i < 16; ++i) { const int k = kap0 + ty + 8 * i - dstCol0; const int kc = k < 0 ? 0 : (k < srcK ? k : srcK - 1);
;             raw[i] = __builtin_nontemporal_load(src + (size_t)kc * srcN + nc); }
;         if (gk) {
; #pragma unroll
;             for (int i = 0; i < 16; ++i) { const int k = kap0 + ty + 8 * i - dstCol0; const int kc = k < 0 ? 0 : (k < srcK ? k : srcK - 1); gs[i] = gk[kc]; }
;         } else {
; #pragma unroll
;             for (int i = 0; i < 16; ++i) gs[i] = 1.0f;
;         }
;     ...
;     auto emit = [&](int t, float (&regs)[16]) {
; #pragma unroll
;         for (int i = 0; i < 16; ++i) tile[(ty + 8 * i) * 65 + tx] = regs[i];
;         __syncthreads();
;         int rho0, kap0, n0; coords(t, rho0, kap0, n0);
;         const int tn = t + 2 * gridDim.x;
;         if (tn < ntot) gl(tn, regs);
	s_cbranch_scc1 .LBB0_1823
	s_add_i32 s4, s18, s4
	s_cmpk_gt_i32 s4, 0x57f
	ds_write_b32 v60, v16
	ds_write_b32 v60, v17 offset:2080
	ds_write_b32 v60, v18 offset:4160
	ds_write_b32 v60, v19 offset:6240
	ds_write_b32 v60, v20 offset:8320
	ds_write_b32 v60, v21 offset:10400
	ds_write_b32 v60, v22 offset:12480
	ds_write_b32 v60, v23 offset:14560
	ds_write_b32 v60, v24 offset:16640
	ds_write_b32 v60, v25 offset:18720
	ds_write_b32 v60, v26 offset:20800
	ds_write_b32 v60, v27 offset:22880
	ds_write_b32 v60, v28 offset:24960
	ds_write_b32 v60, v29 offset:27040
	ds_write_b32 v60, v30 offset:29120
	ds_write_b32 v60, v31 offset:31200
	s_waitcnt lgkmcnt(0)
	s_barrier
	s_cbranch_scc1 .LBB0_1822
	s_mul_hi_i32 s4, s4, 0x2e8ba2e9
	s_lshr_b32 s9, s4, 31
	s_ashr_i32 s4, s4, 4
	s_add_i32 s4, s4, s9
	s_mul_i32 s9, s4, 0x3ffff50
	s_add_i32 s14, s96, s7
	s_add_i32 s14, s14, s9
	s_and_b32 s9, s14, 0x3fffffc
	s_or_b32 s9, s9, s5
	s_lshl_b32 s9, s9, 6
	s_ashr_i32 s14, s9, 1
	s_and_b32 s14, s14, 0xffffff80
	s_and_b32 s9, s9, 64
	s_or_b32 s9, s9, s14
	v_or_b32_e32 v63, s9, v50
	v_min_i32_e32 v16, 0x15ff, v63
	v_lshl_add_u32 v62, s4, 7, v51
	v_ashrrev_i32_e32 v17, 31, v16
	v_lshl_add_u64 v[94:95], v[16:17], 2, s[0:1]
	v_med3_i32 v16, v62, 0, v61
	v_mad_u64_u32 v[18:19], s[14:15], v16, s10, v[94:95]
	v_add_u32_e32 v64, 8, v62
	global_load_dword v65, v[18:19], off nt
	v_med3_i32 v18, v64, 0, v61
	v_mad_u64_u32 v[20:21], s[14:15], v18, s10, v[94:95]
	v_add_u32_e32 v66, 16, v62
	global_load_dword v67, v[20:21], off nt
	v_med3_i32 v20, v66, 0, v61
	v_mad_u64_u32 v[22:23], s[14:15], v20, s10, v[94:95]
	v_add_u32_e32 v68, 24, v62
	global_load_dword v69, v[22:23], off nt
	v_med3_i32 v22, v68, 0, v61
	v_mad_u64_u32 v[24:25], s[14:15], v22, s10, v[94:95]
	v_add_u32_e32 v70, 32, v62
	global_load_dword v71, v[24:25], off nt
	v_med3_i32 v24, v70, 0, v61
	v_mad_u64_u32 v[26:27], s[14:15], v24, s10, v[94:95]
	v_add_u32_e32 v72, 40, v62
	global_load_dword v73, v[26:27], off nt
	v_med3_i32 v26, v72, 0, v61
	v_mad_u64_u32 v[28:29], s[14:15], v26, s10, v[94:95]
	v_add_u32_e32 v74, 48, v62
	global_load_dword v75, v[28:29], off nt
	v_med3_i32 v28, v74, 0, v61
	v_mad_u64_u32 v[30:31], s[14:15], v28, s10, v[94:95]
	v_add_u32_e32 v76, 56, v62
	global_load_dword v77, v[30:31], off nt
	v_med3_i32 v30, v76, 0, v61
	v_mad_u64_u32 v[34:35], s[14:15], v30, s10, v[94:95]
	v_add_u32_e32 v78, 64, v62
	global_load_dword v80, v[34:35], off nt
	v_med3_i32 v34, v78, 0, v61
	v_mad_u64_u32 v[36:37], s[14:15], v34, s10, v[94:95]
	v_add_u32_e32 v79, 0x48, v62
	global_load_dword v81, v[36:37], off nt
	v_med3_i32 v36, v79, 0, v61
	v_mad_u64_u32 v[38:39], s[14:15], v36, s10, v[94:95]
	v_add_u32_e32 v82, 0x50, v62
	global_load_dword v83, v[38:39], off nt
	v_med3_i32 v38, v82, 0, v61
	v_mad_u64_u32 v[40:41], s[14:15], v38, s10, v[94:95]
	v_add_u32_e32 v84, 0x58, v62
	global_load_dword v85, v[40:41], off nt
	v_med3_i32 v40, v84, 0, v61
	v_mad_u64_u32 v[42:43], s[14:15], v40, s10, v[94:95]
	v_add_u32_e32 v86, 0x60, v62
	global_load_dword v87, v[42:43], off nt
	v_med3_i32 v42, v86, 0, v61
	v_mad_u64_u32 v[44:45], s[14:15], v42, s10, v[94:95]
	v_add_u32_e32 v88, 0x68, v62
	global_load_dword v89, v[44:45], off nt
	v_med3_i32 v44, v88, 0, v61
	v_mad_u64_u32 v[46:47], s[14:15], v44, s10, v[94:95]
	v_add_u32_e32 v90, 0x70, v62
	global_load_dword v91, v[46:47], off nt
	v_med3_i32 v46, v90, 0, v61
	v_mad_u64_u32 v[48:49], s[14:15], v46, s10, v[94:95]
	v_add_u32_e32 v92, 0x78, v62
	global_load_dword v93, v[48:49], off nt
	v_med3_i32 v48, v92, 0, v61
	v_mad_u64_u32 v[94:95], s[14:15], v48, s10, v[94:95]
	global_load_dword v94, v[94:95], off nt
	s_and_b64 vcc, exec, s[16:17]
	s_cbranch_vccz .LBB0_1820
	v_mov_b32_e32 v31, 1.0
	v_mov_b32_e32 v30, 1.0
	v_mov_b32_e32 v29, 1.0
	v_mov_b32_e32 v28, 1.0
	v_mov_b32_e32 v27, 1.0
	v_mov_b32_e32 v26, 1.0
	v_mov_b32_e32 v25, 1.0
	v_mov_b32_e32 v24, 1.0
	v_mov_b32_e32 v23, 1.0
	v_mov_b32_e32 v22, 1.0
	v_mov_b32_e32 v21, 1.0
	v_mov_b32_e32 v20, 1.0
	v_mov_b32_e32 v19, 1.0
	v_mov_b32_e32 v18, 1.0
	v_mov_b32_e32 v17, 1.0
	v_mov_b32_e32 v16, 1.0
	s_branch .LBB0_1821

; DEVI unsigned pk_bf16(float lo, float hi) { unsigned r; asm("v_cvt_pk_bf16_f32 %0, %1, %2" : "=v"(r) : "v"(lo), "v"(hi)); return r; }
; DEVI void cvt_job(LAS float* tile, const float* src, int srcK, int srcN, bf16_t* dst, int dstLd, int dstRows, int dstCol0, int mode, const float* gk = nullptr) {
;     ...
;         for (int i = 0; i < 16; ++i) { const int k = kap0 + ty + 8 * i - dstCol0; const int kc = k < 0 ? 0 : (k < srcK ? k : srcK - 1);
;             raw[i] = __builtin_nontemporal_load(src + (size_t)kc * srcN + nc); }
;         if (gk) {
; #pragma unroll
;             for (int i = 0; i < 16; ++i) { const int k = kap0 + ty + 8 * i - dstCol0; const int kc = k < 0 ? 0 : (k < srcK ? k : srcK - 1); gs[i] = gk[kc]; }
;         } else {
; #pragma unroll
;             for (int i = 0; i < 16; ++i) gs[i] = 1.0f;
;         }
; #pragma unroll
;         for (int i = 0; i < 16; ++i) { const int k = kap0 + ty + 8 * i - dstCol0; regs[i] = (nok && k >= 0 && k < srcK) ? raw[i] * gs[i] : 0.f; }
;     ...
;         for (int i = 0; i < 8; ++i) { const int row = ty + 8 * i;
;             const float lo = tile[(2 * tx) * 65 + row], hi = tile[(2 * tx + 1) * 65 + row];
;             *(unsigned*)(dst + (size_t)(rho0 + row) * dstLd + kap0 + 2 * tx) = pk_bf16(lo, hi); }
.LBB0_2476:
	ds_read2_b32 v[142:143], v35 offset0:65 offset1:73
	ds_read2_b32 v[144:145], v35 offset1:8
	s_ashr_i32 s4, s8, 31
	s_lshr_b32 s4, s4, 27
	s_add_i32 s8, s8, s4
	s_ashr_i32 s4, s8, 5
	v_readlane_b32 s14, v238, 59
	s_lshl_b32 s8, s4, 7
	s_waitcnt lgkmcnt(0)
	v_cvt_pk_bf16_f32 v142, v144, v142
	v_add_u32_e32 v144, s5, v37
	s_lshl_b32 s4, s4, 11
	v_readlane_b32 s15, v238, 60
	s_ashr_i32 s9, s8, 31
	v_subrev_u32_e32 v150, s4, v144
	v_mov_b64_e32 v[146:147], s[14:15]
	v_mad_i64_i32 v[148:149], s[14:15], v150, s11, v[146:147]
	s_lshl_b64 s[8:9], s[8:9], 1
	v_lshl_add_u64 v[148:149], v[148:149], 0, s[8:9]
	v_lshl_add_u64 v[148:149], v[148:149], 0, v[32:33]
	global_store_dword v[148:149], v142, off
	v_add_u32_e32 v142, 8, v150
	v_cvt_pk_bf16_f32 v144, v145, v143
	v_mad_i64_i32 v[142:143], s[14:15], v142, s11, v[146:147]
	v_lshl_add_u64 v[142:143], v[142:143], 0, s[8:9]
	v_lshl_add_u64 v[142:143], v[142:143], 0, v[32:33]
	global_store_dword v[142:143], v144, off
	ds_read2_b32 v[142:143], v35 offset0:16 offset1:24
	ds_read2_b32 v[144:145], v35 offset0:81 offset1:89
	s_waitcnt lgkmcnt(0)
	v_cvt_pk_bf16_f32 v142, v142, v144
	v_add_u32_e32 v144, 16, v150
	v_mad_i64_i32 v[148:149], s[14:15], v144, s11, v[146:147]
	v_lshl_add_u64 v[148:149], v[148:149], 0, s[8:9]
	v_lshl_add_u64 v[148:149], v[148:149], 0, v[32:33]
	global_store_dword v[148:149], v142, off
	v_add_u32_e32 v142, 24, v150
	v_cvt_pk_bf16_f32 v144, v143, v145
	v_mad_i64_i32 v[142:143], s[14:15], v142, s11, v[146:147]
	v_lshl_add_u64 v[142:143], v[142:143], 0, s[8:9]
	v_lshl_add_u64 v[142:143], v[142:143], 0, v[32:33]
	global_store_dword v[142:143], v144, off
	ds_read2_b32 v[142:143], v35 offset0:32 offset1:40
	ds_read2_b32 v[144:145], v35 offset0:97 offset1:105
	s_waitcnt lgkmcnt(0)
	v_cvt_pk_bf16_f32 v142, v142, v144
	v_add_u32_e32 v144, 32, v150
	v_mad_i64_i32 v[148:149], s[14:15], v144, s11, v[146:147]
	v_lshl_add_u64 v[148:149], v[148:149], 0, s[8:9]
	v_lshl_add_u64 v[148:149], v[148:149], 0, v[32:33]
	global_store_dword v[148:149], v142, off
	v_add_u32_e32 v142, 40, v150
	v_cvt_pk_bf16_f32 v144, v143, v145
	v_mad_i64_i32 v[142:143], s[14:15], v142, s11, v[146:147]
	v_lshl_add_u64 v[142:143], v[142:143], 0, s[8:9]
	v_lshl_add_u64 v[142:143], v[142:143], 0, v[32:33]
	global_store_dword v[142:143], v144, off
	ds_read2_b32 v[142:143], v35 offset0:48 offset1:56
	ds_read2_b32 v[144:145], v35 offset0:113 offset1:121
	s_waitcnt lgkmcnt(0)
	v_cvt_pk_bf16_f32 v142, v142, v144
	v_add_u32_e32 v144, 48, v150
	v_mad_i64_i32 v[148:149], s[14:15], v144, s11, v[146:147]
	v_lshl_add_u64 v[148:149], v[148:149], 0, s[8:9]
	v_lshl_add_u64 v[148:149], v[148:149], 0, v[32:33]
	global_store_dword v[148:149], v142, off
	v_add_u32_e32 v142, 56, v150
	v_cvt_pk_bf16_f32 v144, v143, v145
	v_mad_i64_i32 v[142:143], s[14:15], v142, s11, v[146:147]
	v_lshl_add_u64 v[142:143], v[142:143], 0, s[8:9]
	v_lshl_add_u64 v[142:143], v[142:143], 0, v[32:33]
	global_store_dword v[142:143], v144, off
	v_cmp_gt_i32_e32 vcc, s7, v44
	v_cmp_gt_u32_e64 s[34:35], s10, v45
	s_and_b64 s[34:35], s[34:35], vcc
	s_waitcnt vmcnt(23)
	v_cndmask_b32_e64 v16, 0, v53, s[34:35]
	v_cmp_gt_u32_e64 s[34:35], s10, v46
	s_and_b64 s[34:35], s[34:35], vcc
	s_waitcnt vmcnt(22)
	v_cndmask_b32_e64 v17, 0, v54, s[34:35]
	v_cmp_gt_u32_e64 s[34:35], s10, v47
	s_and_b64 s[34:35], s[34:35], vcc
	s_waitcnt vmcnt(21)
	v_cndmask_b32_e64 v18, 0, v55, s[34:35]
	v_cmp_gt_u32_e64 s[34:35], s10, v48
	s_and_b64 s[34:35], s[34:35], vcc
	s_waitcnt vmcnt(20)
	v_cndmask_b32_e64 v19, 0, v56, s[34:35]
	v_cmp_gt_u32_e64 s[34:35], s10, v49
	s_and_b64 s[34:35], s[34:35], vcc
	s_waitcnt vmcnt(19)
	v_cndmask_b32_e64 v20, 0, v57, s[34:35]
	v_cmp_gt_u32_e64 s[34:35], s10, v50
	s_and_b64 s[34:35], s[34:35], vcc
	s_waitcnt vmcnt(18)
	v_cndmask_b32_e64 v21, 0, v28, s[34:35]
	v_cmp_gt_u32_e64 s[34:35], s10, v51
	s_and_b64 s[34:35], s[34:35], vcc
	s_waitcnt vmcnt(17)
	v_cndmask_b32_e64 v22, 0, v29, s[34:35]
	v_cmp_gt_u32_e64 s[34:35], s10, v52
	s_and_b64 s[34:35], s[34:35], vcc
	s_waitcnt vmcnt(16)
	v_cndmask_b32_e64 v23, 0, v30, s[34:35]
	v_cmp_gt_u32_e64 s[34:35], s10, v31
	s_and_b64 s[34:35], s[34:35], vcc
	s_waitcnt vmcnt(15)
	v_cndmask_b32_e64 v24, 0, v60, s[34:35]
	v_cmp_gt_u32_e64 s[34:35], s10, v42
	s_and_b64 s[34:35], s[34:35], vcc
	s_waitcnt vmcnt(14)
	v_cndmask_b32_e64 v25, 0, v61, s[34:35]
	v_cmp_gt_u32_e64 s[34:35], s10, v43
	s_and_b64 s[34:35], s[34:35], vcc
	s_waitcnt vmcnt(13)
	v_cndmask_b32_e64 v26, 0, v62, s[34:35]
	v_cmp_gt_u32_e64 s[34:35], s10, v58
	s_and_b64 s[34:35], s[34:35], vcc
	s_waitcnt vmcnt(12)
	v_cndmask_b32_e64 v27, 0, v63, s[34:35]
	v_cmp_gt_u32_e64 s[34:35], s10, v59
	s_and_b64 s[34:35], s[34:35], vcc
	s_waitcnt vmcnt(11)
	v_cndmask_b32_e64 v28, 0, v64, s[34:35]
	v_cmp_gt_u32_e64 s[34:35], s10, v65
	s_and_b64 s[34:35], s[34:35], vcc
	s_waitcnt vmcnt(10)
	v_cndmask_b32_e64 v29, 0, v67, s[34:35]
	v_cmp_gt_u32_e64 s[34:35], s10, v66
	s_and_b64 s[34:35], s[34:35], vcc
	s_waitcnt vmcnt(9)
	v_cndmask_b32_e64 v30, 0, v68, s[34:35]
	v_cmp_gt_u32_e64 s[34:35], s10, v69
	s_and_b64 vcc, s[34:35], vcc
	s_waitcnt vmcnt(8)
	v_cndmask_b32_e32 v31, 0, v70, vcc
	s_waitcnt vmcnt(63) expcnt(7) lgkmcnt(15)
	s_barrier

; DEVI int obid() { int b = __builtin_amdgcn_workgroup_id_x(); asm volatile("" : "+s"(b)); return b; }
; DEVI unsigned pk_bf16(float lo, float hi) { unsigned r; asm("v_cvt_pk_bf16_f32 %0, %1, %2" : "=v"(r) : "v"(lo), "v"(hi)); return r; }
; DEVI void cvt_job(LAS float* tile, const float* src, int srcK, int srcN, bf16_t* dst, int dstLd, int dstRows, int dstCol0, int mode, const float* gk = nullptr) {
;     ...
;         for (int i = 0; i < 16; ++i) { const int k = kap0 + ty + 8 * i - dstCol0; const int kc = k < 0 ? 0 : (k < srcK ? k : srcK - 1);
;             raw[i] = __builtin_nontemporal_load(src + (size_t)kc * srcN + nc); }
;         if (gk) {
; #pragma unroll
;             for (int i = 0; i < 16; ++i) { const int k = kap0 + ty + 8 * i - dstCol0; const int kc = k < 0 ? 0 : (k < srcK ? k : srcK - 1); gs[i] = gk[kc]; }
;         } else {
; #pragma unroll
;             for (int i = 0; i < 16; ++i) gs[i] = 1.0f;
;         }
; #pragma unroll
;         for (int i = 0; i < 16; ++i) { const int k = kap0 + ty + 8 * i - dstCol0; regs[i] = (nok && k >= 0 && k < srcK) ? raw[i] * gs[i] : 0.f; }
;     ...
;         for (int i = 0; i < 8; ++i) { const int row = ty + 8 * i;
;             const float lo = tile[(2 * tx) * 65 + row], hi = tile[(2 * tx + 1) * 65 + row];
;             *(unsigned*)(dst + (size_t)(rho0 + row) * dstLd + kap0 + 2 * tx) = pk_bf16(lo, hi); }
;         __syncthreads();
;     };
;     const int G = gridDim.x;
;     int t = obid();
;     if (t < ntot) gl(t, regsA);
;     if (t + G < ntot) gl(t + G, regsB);
;     while (t < ntot) {
;         emit(t, regsA);
;         if (t + G < ntot) emit(t + G, regsB);
;         t += 2 * G;
.LBB0_2480:
	ds_read2_b32 v[142:143], v35 offset0:65 offset1:73
	ds_read2_b32 v[144:145], v35 offset1:8
	s_ashr_i32 s8, s4, 31
	s_lshr_b32 s8, s8, 27
	s_add_i32 s8, s4, s8
	s_ashr_i32 s13, s8, 5
	v_readlane_b32 s14, v238, 59
	s_lshl_b32 s8, s13, 7
	s_waitcnt lgkmcnt(0)
	v_cvt_pk_bf16_f32 v142, v144, v142
	v_add_u32_e32 v144, s5, v38
	s_lshl_b32 s13, s13, 11
	v_readlane_b32 s15, v238, 60
	s_ashr_i32 s9, s8, 31
	v_subrev_u32_e32 v150, s13, v144
	v_mov_b64_e32 v[146:147], s[14:15]
	v_mad_i64_i32 v[148:149], s[14:15], v150, s11, v[146:147]
	s_lshl_b64 s[8:9], s[8:9], 1
	v_lshl_add_u64 v[148:149], v[148:149], 0, s[8:9]
	v_lshl_add_u64 v[148:149], v[148:149], 0, v[32:33]
	global_store_dword v[148:149], v142, off
	v_add_u32_e32 v142, 8, v150
	v_cvt_pk_bf16_f32 v144, v145, v143
	v_mad_i64_i32 v[142:143], s[14:15], v142, s11, v[146:147]
	v_lshl_add_u64 v[142:143], v[142:143], 0, s[8:9]
	v_lshl_add_u64 v[142:143], v[142:143], 0, v[32:33]
	global_store_dword v[142:143], v144, off
	ds_read2_b32 v[142:143], v35 offset0:16 offset1:24
	ds_read2_b32 v[144:145], v35 offset0:81 offset1:89
	s_waitcnt lgkmcnt(0)
	v_cvt_pk_bf16_f32 v142, v142, v144
	v_add_u32_e32 v144, 16, v150
	v_mad_i64_i32 v[148:149], s[14:15], v144, s11, v[146:147]
	v_lshl_add_u64 v[148:149], v[148:149], 0, s[8:9]
	v_lshl_add_u64 v[148:149], v[148:149], 0, v[32:33]
	global_store_dword v[148:149], v142, off
	v_add_u32_e32 v142, 24, v150
	v_cvt_pk_bf16_f32 v144, v143, v145
	v_mad_i64_i32 v[142:143], s[14:15], v142, s11, v[146:147]
	v_lshl_add_u64 v[142:143], v[142:143], 0, s[8:9]
	v_lshl_add_u64 v[142:143], v[142:143], 0, v[32:33]
	global_store_dword v[142:143], v144, off
	ds_read2_b32 v[142:143], v35 offset0:32 offset1:40
	ds_read2_b32 v[144:145], v35 offset0:97 offset1:105
	s_waitcnt lgkmcnt(0)
	v_cvt_pk_bf16_f32 v142, v142, v144
	v_add_u32_e32 v144, 32, v150
	v_mad_i64_i32 v[148:149], s[14:15], v144, s11, v[146:147]
	v_lshl_add_u64 v[148:149], v[148:149], 0, s[8:9]
	v_lshl_add_u64 v[148:149], v[148:149], 0, v[32:33]
	global_store_dword v[148:149], v142, off
	v_add_u32_e32 v142, 40, v150
	v_cvt_pk_bf16_f32 v144, v143, v145
	v_mad_i64_i32 v[142:143], s[14:15], v142, s11, v[146:147]
	v_lshl_add_u64 v[142:143], v[142:143], 0, s[8:9]
	v_lshl_add_u64 v[142:143], v[142:143], 0, v[32:33]
	global_store_dword v[142:143], v144, off
	ds_read2_b32 v[142:143], v35 offset0:48 offset1:56
	ds_read2_b32 v[144:145], v35 offset0:113 offset1:121
	s_waitcnt lgkmcnt(0)
	v_cvt_pk_bf16_f32 v142, v142, v144
	v_add_u32_e32 v144, 48, v150
	v_mad_i64_i32 v[148:149], s[14:15], v144, s11, v[146:147]
	v_lshl_add_u64 v[148:149], v[148:149], 0, s[8:9]
	v_lshl_add_u64 v[148:149], v[148:149], 0, v[32:33]
	global_store_dword v[148:149], v142, off
	v_add_u32_e32 v142, 56, v150
	v_cvt_pk_bf16_f32 v144, v143, v145
	v_mad_i64_i32 v[142:143], s[14:15], v142, s11, v[146:147]
	v_lshl_add_u64 v[142:143], v[142:143], 0, s[8:9]
	s_add_i32 s8, s33, s4
	v_lshl_add_u64 v[142:143], v[142:143], 0, v[32:33]
	s_cmpk_gt_i32 s8, 0x57f
	global_store_dword v[142:143], v144, off
	s_cselect_b32 s98, 1, 0
	s_mov_b64 s[100:101], vcc
	v_cmp_gt_i32_e32 vcc, s7, v44
	v_cmp_gt_u32_e64 s[34:35], s10, v45
	s_and_b64 s[34:35], s[34:35], vcc
	s_waitcnt vmcnt(23)
	v_cndmask_b32_e64 v0, 0, v53, s[34:35]
	v_cmp_gt_u32_e64 s[34:35], s10, v46
	s_and_b64 s[34:35], s[34:35], vcc
	s_waitcnt vmcnt(22)
	v_cndmask_b32_e64 v1, 0, v54, s[34:35]
	v_cmp_gt_u32_e64 s[34:35], s10, v47
	s_and_b64 s[34:35], s[34:35], vcc
	s_waitcnt vmcnt(21)
	v_cndmask_b32_e64 v2, 0, v55, s[34:35]
	v_cmp_gt_u32_e64 s[34:35], s10, v48
	s_and_b64 s[34:35], s[34:35], vcc
	s_waitcnt vmcnt(20)
	v_cndmask_b32_e64 v3, 0, v56, s[34:35]
	v_cmp_gt_u32_e64 s[34:35], s10, v49
	s_and_b64 s[34:35], s[34:35], vcc
	s_waitcnt vmcnt(19)
	v_cndmask_b32_e64 v4, 0, v57, s[34:35]
	v_cmp_gt_u32_e64 s[34:35], s10, v50
	s_and_b64 s[34:35], s[34:35], vcc
	s_waitcnt vmcnt(18)
	v_cndmask_b32_e64 v5, 0, v12, s[34:35]
	v_cmp_gt_u32_e64 s[34:35], s10, v51
	s_and_b64 s[34:35], s[34:35], vcc
	s_waitcnt vmcnt(17)
	v_cndmask_b32_e64 v6, 0, v13, s[34:35]
	v_cmp_gt_u32_e64 s[34:35], s10, v52
	s_and_b64 s[34:35], s[34:35], vcc
	s_waitcnt vmcnt(16)
	v_cndmask_b32_e64 v7, 0, v14, s[34:35]
	v_cmp_gt_u32_e64 s[34:35], s10, v15
	s_and_b64 s[34:35], s[34:35], vcc
	s_waitcnt vmcnt(15)
	v_cndmask_b32_e64 v8, 0, v60, s[34:35]
	v_cmp_gt_u32_e64 s[34:35], s10, v42
	s_and_b64 s[34:35], s[34:35], vcc
	s_waitcnt vmcnt(14)
	v_cndmask_b32_e64 v9, 0, v61, s[34:35]
	v_cmp_gt_u32_e64 s[34:35], s10, v43
	s_and_b64 s[34:35], s[34:35], vcc
	s_waitcnt vmcnt(13)
	v_cndmask_b32_e64 v10, 0, v62, s[34:35]
	v_cmp_gt_u32_e64 s[34:35], s10, v58
	s_and_b64 s[34:35], s[34:35], vcc
	s_waitcnt vmcnt(12)
	v_cndmask_b32_e64 v11, 0, v63, s[34:35]
	v_cmp_gt_u32_e64 s[34:35], s10, v59
	s_and_b64 s[34:35], s[34:35], vcc
	s_waitcnt vmcnt(11)
	v_cndmask_b32_e64 v12, 0, v64, s[34:35]
	v_cmp_gt_u32_e64 s[34:35], s10, v65
	s_and_b64 s[34:35], s[34:35], vcc
	s_waitcnt vmcnt(10)
	v_cndmask_b32_e64 v13, 0, v67, s[34:35]
	v_cmp_gt_u32_e64 s[34:35], s10, v66
	s_and_b64 s[34:35], s[34:35], vcc
	s_waitcnt vmcnt(9)
	v_cndmask_b32_e64 v14, 0, v68, s[34:35]
	v_cmp_gt_u32_e64 s[34:35], s10, v69
	s_and_b64 vcc, s[34:35], vcc
	s_waitcnt vmcnt(8)
	v_cndmask_b32_e32 v15, 0, v70, vcc
	s_mov_b64 vcc, s[100:101]
	s_cmp_lg_u32 s98, 0
	s_waitcnt vmcnt(63) expcnt(7) lgkmcnt(15)
	s_barrier
; DEVI void cvt_job(LAS float* tile, const float* src, int srcK, int srcN, bf16_t* dst, int dstLd, int dstRows, int dstCol0, int mode, const float* gk = nullptr) {
;     ...
;     auto gl = [&](int t, float (&regs)[16]) {
;         int rho0, kap0, n0; coords(t, rho0, kap0, n0);
;         const int n = n0 + tx, nc = n < srcN ? n : srcN - 1;
;         const bool nok = n < srcN;
;         float raw[16], gs[16];
; #pragma unroll
;         for (int i = 0; i < 16; ++i) { const int k = kap0 + ty + 8 * i - dstCol0; const int kc = k < 0 ? 0 : (k < srcK ? k : srcK - 1);
;             raw[i] = __builtin_nontemporal_load(src + (size_t)kc * srcN + nc); }
;     ...
;     auto emit = [&](int t, float (&regs)[16]) {
; #pragma unroll
;         for (int i = 0; i < 16; ++i) tile[(ty + 8 * i) * 65 + tx] = regs[i];
;         __syncthreads();
;         int rho0, kap0, n0; coords(t, rho0, kap0, n0);
;         const int tn = t + 2 * gridDim.x;
;         if (tn < ntot) gl(tn, regs);
	s_cbranch_scc1 .LBB0_2477
	s_add_i32 s4, s18, s4
	s_cmpk_gt_i32 s4, 0x57f
	ds_write_b32 v40, v16
	ds_write_b32 v40, v17 offset:2080
	ds_write_b32 v40, v18 offset:4160
	ds_write_b32 v40, v19 offset:6240
	ds_write_b32 v40, v20 offset:8320
	ds_write_b32 v40, v21 offset:10400
	ds_write_b32 v40, v22 offset:12480
	ds_write_b32 v40, v23 offset:14560
	ds_write_b32 v40, v24 offset:16640
	ds_write_b32 v40, v25 offset:18720
	ds_write_b32 v40, v26 offset:20800
	ds_write_b32 v40, v27 offset:22880
	ds_write_b32 v40, v28 offset:24960
	ds_write_b32 v40, v29 offset:27040
	ds_write_b32 v40, v30 offset:29120
	ds_write_b32 v40, v31 offset:31200
	s_waitcnt lgkmcnt(0)
	s_barrier
	s_cbranch_scc1 .LBB0_2476
	s_ashr_i32 s9, s4, 31
	s_lshr_b32 s9, s9, 27
	s_add_i32 s4, s4, s9
	s_ashr_i32 s4, s4, 5
	v_add_u32_e32 v16, s5, v36
	s_lshl_b32 s9, s4, 11
	v_subrev_u32_e32 v44, s9, v16
	v_lshl_add_u32 v45, s4, 7, v34
	v_min_i32_e32 v16, 0x7ff, v44
	v_add_u32_e32 v50, 40, v45
	v_add_u32_e32 v51, 48, v45
	v_ashrrev_i32_e32 v17, 31, v16
	v_med3_i32 v18, v45, 0, v41
	v_add_u32_e32 v46, 8, v45
	v_add_u32_e32 v47, 16, v45
	v_add_u32_e32 v48, 24, v45
	v_add_u32_e32 v49, 32, v45
	v_med3_i32 v28, v50, 0, v41
	v_med3_i32 v30, v51, 0, v41
	v_add_u32_e32 v52, 56, v45
	v_lshl_add_u64 v[16:17], v[16:17], 2, s[0:1]
	v_lshlrev_b32_e32 v18, 13, v18
	v_mov_b32_e32 v19, v33
	v_med3_i32 v20, v46, 0, v41
	v_med3_i32 v22, v47, 0, v41
	v_med3_i32 v24, v48, 0, v41
	v_med3_i32 v26, v49, 0, v41
	v_lshlrev_b32_e32 v28, 13, v28
	v_mov_b32_e32 v29, v33
	v_lshlrev_b32_e32 v30, 13, v30
	v_mov_b32_e32 v31, v33
	v_med3_i32 v42, v52, 0, v41
	v_lshl_add_u64 v[18:19], v[16:17], 0, v[18:19]
	v_lshlrev_b32_e32 v20, 13, v20
	v_mov_b32_e32 v21, v33
	v_lshlrev_b32_e32 v22, 13, v22
	v_mov_b32_e32 v23, v33
	v_lshlrev_b32_e32 v24, 13, v24
	v_mov_b32_e32 v25, v33
	v_lshlrev_b32_e32 v26, 13, v26
	v_mov_b32_e32 v27, v33
	v_lshl_add_u64 v[28:29], v[16:17], 0, v[28:29]
	v_lshl_add_u64 v[30:31], v[16:17], 0, v[30:31]
	v_lshlrev_b32_e32 v42, 13, v42
	v_mov_b32_e32 v43, v33
	v_lshl_add_u64 v[20:21], v[16:17], 0, v[20:21]
	v_lshl_add_u64 v[22:23], v[16:17], 0, v[22:23]
	v_lshl_add_u64 v[24:25], v[16:17], 0, v[24:25]
	v_lshl_add_u64 v[26:27], v[16:17], 0, v[26:27]
	v_lshl_add_u64 v[42:43], v[16:17], 0, v[42:43]
	global_load_dword v53, v[18:19], off nt
	global_load_dword v54, v[20:21], off nt
	global_load_dword v55, v[22:23], off nt
	global_load_dword v56, v[24:25], off nt
	global_load_dword v57, v[26:27], off nt
	s_nop 0
	global_load_dword v28, v[28:29], off nt
	s_nop 0
	global_load_dword v29, v[30:31], off nt
	s_nop 0
	global_load_dword v30, v[42:43], off nt
	v_add_u32_e32 v31, 64, v45
	v_med3_i32 v18, v31, 0, v41
	v_add_u32_e32 v42, 0x48, v45
	v_add_u32_e32 v43, 0x50, v45
	v_add_u32_e32 v58, 0x58, v45
	v_add_u32_e32 v59, 0x60, v45
	v_lshlrev_b32_e32 v18, 13, v18
	v_mov_b32_e32 v19, v33
	v_med3_i32 v20, v42, 0, v41
	v_med3_i32 v22, v43, 0, v41
	v_med3_i32 v24, v58, 0, v41
	v_med3_i32 v26, v59, 0, v41
	v_lshl_add_u64 v[18:19], v[16:17], 0, v[18:19]
	v_lshlrev_b32_e32 v20, 13, v20
	v_mov_b32_e32 v21, v33
	v_lshlrev_b32_e32 v22, 13, v22
	v_mov_b32_e32 v23, v33
	v_lshlrev_b32_e32 v24, 13, v24
	v_mov_b32_e32 v25, v33
	v_lshlrev_b32_e32 v26, 13, v26
	v_mov_b32_e32 v27, v33
	v_lshl_add_u64 v[20:21], v[16:17], 0, v[20:21]
	v_lshl_add_u64 v[22:23], v[16:17], 0, v[22:23]
	v_lshl_add_u64 v[24:25], v[16:17], 0, v[24:25]
	v_lshl_add_u64 v[26:27], v[16:17], 0, v[26:27]
	global_load_dword v60, v[18:19], off nt
	global_load_dword v61, v[20:21], off nt
	global_load_dword v62, v[22:23], off nt
	global_load_dword v63, v[24:25], off nt
	global_load_dword v64, v[26:27], off nt
	v_add_u32_e32 v65, 0x68, v45
	v_med3_i32 v18, v65, 0, v41
	v_add_u32_e32 v66, 0x70, v45
	v_lshlrev_b32_e32 v18, 13, v18
	v_mov_b32_e32 v19, v33
	v_med3_i32 v20, v66, 0, v41
	v_lshl_add_u64 v[18:19], v[16:17], 0, v[18:19]
	v_lshlrev_b32_e32 v20, 13, v20
	v_mov_b32_e32 v21, v33
	v_add_u32_e32 v69, 0x78, v45
	v_lshl_add_u64 v[20:21], v[16:17], 0, v[20:21]
	global_load_dword v67, v[18:19], off nt
	global_load_dword v68, v[20:21], off nt
	v_med3_i32 v18, v69, 0, v41
	v_lshlrev_b32_e32 v18, 13, v18
	v_mov_b32_e32 v19, v33
	v_lshl_add_u64 v[16:17], v[16:17], 0, v[18:19]
	global_load_dword v70, v[16:17], off nt
	s_branch .LBB0_2476

; __global__ void __launch_bounds__(512, 2) hybrid_fwd(const Params P) {
;     extern __shared__ __attribute__((aligned(16))) unsigned char smem[];
	.amdhsa_kernel _Z10hybrid_fwd6Params
		.amdhsa_group_segment_fixed_size 0
		.amdhsa_private_segment_fixed_size 0
		.amdhsa_kernarg_size 2976
		.amdhsa_user_sgpr_count 2
		.amdhsa_user_sgpr_dispatch_ptr 0
		.amdhsa_user_sgpr_queue_ptr 0
		.amdhsa_user_sgpr_kernarg_segment_ptr 1
		.amdhsa_user_sgpr_dispatch_id 0
		.amdhsa_user_sgpr_kernarg_preload_length 0
		.amdhsa_user_sgpr_kernarg_preload_offset 0
		.amdhsa_user_sgpr_private_segment_size 0
		.amdhsa_uses_dynamic_stack 0
		.amdhsa_enable_private_segment 0
		.amdhsa_system_sgpr_workgroup_id_x 1
		.amdhsa_system_sgpr_workgroup_id_y 0
		.amdhsa_system_sgpr_workgroup_id_z 0
		.amdhsa_system_sgpr_workgroup_info 0
		.amdhsa_system_vgpr_workitem_id 2
		.amdhsa_next_free_vgpr 242
		.amdhsa_next_free_sgpr 102
		.amdhsa_accum_offset 244
		.amdhsa_reserve_vcc 1
		.amdhsa_float_round_mode_32 0
		.amdhsa_float_round_mode_16_64 0
		.amdhsa_float_denorm_mode_32 3
		.amdhsa_float_denorm_mode_16_64 3
		.amdhsa_dx10_clamp 1
		.amdhsa_ieee_mode 1
		.amdhsa_fp16_overflow 0
		.amdhsa_tg_split 0
		.amdhsa_exception_fp_ieee_invalid_op 0
		.amdhsa_exception_fp_denorm_src 0
		.amdhsa_exception_fp_ieee_div_zero 0
		.amdhsa_exception_fp_ieee_overflow 0
		.amdhsa_exception_fp_ieee_underflow 0
		.amdhsa_exception_fp_ieee_inexact 0
		.amdhsa_exception_int_div_zero 0
	.end_amdhsa_kernel

; __global__ void __launch_bounds__(512, 2) hybrid_fwd(const Params P) {
amdhsa.kernels:
  - .agpr_count:     0
    .args:
      - .offset:         0
        .size:           2720
        .value_kind:     by_value
      - .offset:         2720
        .size:           4
        .value_kind:     hidden_block_count_x
      - .offset:         2724
        .size:           4
        .value_kind:     hidden_block_count_y
      - .offset:         2728
        .size:           4
        .value_kind:     hidden_block_count_z
      - .offset:         2732
        .size:           2
        .value_kind:     hidden_group_size_x
      - .offset:         2734
        .size:           2
        .value_kind:     hidden_group_size_y
      - .offset:         2736
        .size:           2
        .value_kind:     hidden_group_size_z
      - .offset:         2738
        .size:           2
        .value_kind:     hidden_remainder_x
      - .offset:         2740
        .size:           2
        .value_kind:     hidden_remainder_y
      - .offset:         2742
        .size:           2
        .value_kind:     hidden_remainder_z
      - .offset:         2760
        .size:           8
        .value_kind:     hidden_global_offset_x
      - .offset:         2768
        .size:           8
        .value_kind:     hidden_global_offset_y
      - .offset:         2776
        .size:           8
        .value_kind:     hidden_global_offset_z
      - .offset:         2784
        .size:           2
        .value_kind:     hidden_grid_dims
      - .offset:         2808
        .size:           8
        .value_kind:     hidden_multigrid_sync_arg
      - .offset:         2840
        .size:           4
        .value_kind:     hidden_dynamic_lds_size
    .group_segment_fixed_size: 0
    .kernarg_segment_align: 8
    .kernarg_segment_size: 2976
    .language:       OpenCL C
    .language_version:
      - 2
      - 0
    .max_flat_workgroup_size: 512
    .name:           _Z10hybrid_fwd6Params
    .private_segment_fixed_size: 0
    .sgpr_count:     108
    .sgpr_spill_count: 350
    .symbol:         _Z10hybrid_fwd6Params.kd
    .uniform_work_group_size: 1
    .uses_dynamic_stack: false
    .vgpr_count:     242
    .vgpr_spill_count: 0
    .wavefront_size: 64
